# lever 7: cross-lane butterfly reductions via DPP and v_permlane16/32_swap instead of ds_bpermute (LN pass, sample/prompt softmax, EpiRes and tail row statistics)
# baseline (speedup 1.0000x reference)
; __device__ __forceinline__ int crow(int reg, int h) { return (reg & 3) + 8 * (reg >> 2) + 4 * h; }
; __device__ __forceinline__ void attn_prompt_wave(const Params& P, int l, int qt, int tid_in) {
;     ...
; #pragma unroll
;     for (int kb = 0; kb < 5; ++kb) {
;         if (kb >= 1 && kb <= 3 && interior) {
; #pragma unroll
;             for (int i = 0; i < 16; ++i) mx = fmaxf(mx, st[kb][i]);
;         } else {
; #pragma unroll
;             for (int i = 0; i < 16; ++i) { const int ki = key0 + kb * 32 + crow(i, h); const bool ok = ki <= qi && ki > qi - 128 && ki >= bstart;
;                 st[kb][i] = ok ? st[kb][i] : -1e30f; mx = fmaxf(mx, st[kb][i]); }
;         }
;     }
;     mx = fmaxf(mx, __shfl_xor(mx, 32));
;     float sum = 0.f;
; #pragma unroll
;     for (int kb = 0; kb < 5; ++kb)
; #pragma unroll
;         for (int i = 0; i < 16; ++i) { const float p = st[kb][i] > -1e29f ? __expf(st[kb][i] - mx) : 0.f; st[kb][i] = p; sum += p; }
.LBB0_952:
	v_add_u32_e32 v56, 0x80, v183
	v_cmp_le_i32_e32 vcc, v56, v182
	v_cmp_gt_i32_e64 s[36:37], v56, v190
	s_and_b64 s[0:1], vcc, s[36:37]
	v_cmp_ge_i32_e32 vcc, v56, v185
	s_and_b64 vcc, s[0:1], vcc
	v_cmp_ge_i32_e64 s[36:37], v56, v190
	v_cndmask_b32_e32 v55, v233, v32, vcc
	v_or_b32_e32 v32, 1, v56
	v_cmp_ge_i32_e64 s[38:39], v32, v185
	v_cmp_lt_i32_e32 vcc, v56, v182
	s_and_b64 s[0:1], s[36:37], s[38:39]
	s_and_b64 vcc, s[0:1], vcc
	v_cndmask_b32_e32 v53, v233, v33, vcc
	v_or_b32_e32 v33, 2, v56
	v_cmp_le_i32_e32 vcc, v33, v182
	v_cmp_gt_i32_e64 s[36:37], v33, v190
	s_and_b64 s[0:1], vcc, s[36:37]
	v_cmp_ge_i32_e32 vcc, v33, v185
	s_and_b64 vcc, s[0:1], vcc
	v_or_b32_e32 v33, 3, v56
	v_cndmask_b32_e32 v54, v233, v34, vcc
	v_cmp_le_i32_e32 vcc, v33, v182
	v_cmp_gt_i32_e64 s[36:37], v33, v190
	s_and_b64 s[0:1], vcc, s[36:37]
	v_cmp_ge_i32_e32 vcc, v33, v185
	s_and_b64 vcc, s[0:1], vcc
	v_or_b32_e32 v33, 8, v56
	v_cndmask_b32_e32 v52, v233, v35, vcc
	v_cmp_le_i32_e32 vcc, v33, v182
	v_cmp_gt_i32_e64 s[36:37], v33, v190
	s_and_b64 s[0:1], vcc, s[36:37]
	v_cmp_ge_i32_e32 vcc, v33, v185
	s_and_b64 vcc, s[0:1], vcc
	v_or_b32_e32 v33, 9, v56
	v_cndmask_b32_e32 v50, v233, v36, vcc
	v_cmp_le_i32_e32 vcc, v33, v182
	v_cmp_gt_i32_e64 s[36:37], v33, v190
	s_and_b64 s[0:1], vcc, s[36:37]
	v_cmp_ge_i32_e32 vcc, v33, v185
	s_and_b64 vcc, s[0:1], vcc
	v_or_b32_e32 v33, 10, v56
	v_cndmask_b32_e32 v51, v233, v37, vcc
	v_cmp_le_i32_e32 vcc, v33, v182
	v_cmp_gt_i32_e64 s[36:37], v33, v190
	s_and_b64 s[0:1], vcc, s[36:37]
	v_cmp_ge_i32_e32 vcc, v33, v185
	s_and_b64 vcc, s[0:1], vcc
	v_or_b32_e32 v33, 11, v56
	v_cndmask_b32_e32 v48, v233, v38, vcc
	v_cmp_le_i32_e32 vcc, v33, v182
	v_cmp_gt_i32_e64 s[36:37], v33, v190
	s_and_b64 s[0:1], vcc, s[36:37]
	v_cmp_ge_i32_e32 vcc, v33, v185
	s_and_b64 vcc, s[0:1], vcc
	v_or_b32_e32 v33, 16, v56
	v_cndmask_b32_e32 v49, v233, v39, vcc
	v_cmp_le_i32_e32 vcc, v33, v182
	v_cmp_gt_i32_e64 s[36:37], v33, v190
	s_and_b64 s[0:1], vcc, s[36:37]
	v_cmp_ge_i32_e32 vcc, v33, v185
	s_and_b64 vcc, s[0:1], vcc
	v_or_b32_e32 v33, 17, v56
	v_cndmask_b32_e32 v40, v233, v40, vcc
	v_cmp_le_i32_e32 vcc, v33, v182
	v_cmp_gt_i32_e64 s[36:37], v33, v190
	s_and_b64 s[0:1], vcc, s[36:37]
	v_cmp_ge_i32_e32 vcc, v33, v185
	s_and_b64 vcc, s[0:1], vcc
	v_or_b32_e32 v33, 18, v56
	v_cndmask_b32_e32 v38, v233, v41, vcc
	v_cmp_le_i32_e32 vcc, v33, v182
	v_cmp_gt_i32_e64 s[36:37], v33, v190
	s_and_b64 s[0:1], vcc, s[36:37]
	v_cmp_ge_i32_e32 vcc, v33, v185
	s_and_b64 vcc, s[0:1], vcc
	v_or_b32_e32 v33, 19, v56
	v_cndmask_b32_e32 v39, v233, v42, vcc
	v_cmp_le_i32_e32 vcc, v33, v182
	v_cmp_gt_i32_e64 s[36:37], v33, v190
	s_and_b64 s[0:1], vcc, s[36:37]
	v_cmp_ge_i32_e32 vcc, v33, v185
	s_and_b64 vcc, s[0:1], vcc
	v_or_b32_e32 v33, 24, v56
	v_cndmask_b32_e32 v36, v233, v43, vcc
	v_cmp_le_i32_e32 vcc, v33, v182
	v_cmp_gt_i32_e64 s[36:37], v33, v190
	s_and_b64 s[0:1], vcc, s[36:37]
	v_cmp_ge_i32_e32 vcc, v33, v185
	s_and_b64 vcc, s[0:1], vcc
	v_or_b32_e32 v33, 25, v56
	v_cndmask_b32_e32 v37, v233, v44, vcc
	v_cmp_le_i32_e32 vcc, v33, v182
	v_cmp_gt_i32_e64 s[36:37], v33, v190
	s_and_b64 s[0:1], vcc, s[36:37]
	v_cmp_ge_i32_e32 vcc, v33, v185
	s_and_b64 vcc, s[0:1], vcc
	v_or_b32_e32 v33, 26, v56
	v_max3_f32 v32, v192, v55, v53
	v_cndmask_b32_e32 v35, v233, v45, vcc
	v_cmp_le_i32_e32 vcc, v33, v182
	v_cmp_gt_i32_e64 s[36:37], v33, v190
	v_max3_f32 v32, v32, v54, v52
	s_and_b64 s[0:1], vcc, s[36:37]
	v_cmp_ge_i32_e32 vcc, v33, v185
	v_max3_f32 v32, v32, v50, v51
	s_and_b64 vcc, s[0:1], vcc
	v_or_b32_e32 v34, 27, v56
	v_max3_f32 v32, v32, v48, v49
	v_cndmask_b32_e32 v33, v233, v46, vcc
	v_cmp_le_i32_e32 vcc, v34, v182
	v_cmp_gt_i32_e64 s[36:37], v34, v190
	v_max3_f32 v32, v32, v40, v38
	s_and_b64 s[0:1], vcc, s[36:37]
	v_cmp_ge_i32_e32 vcc, v34, v185
	v_max3_f32 v32, v32, v39, v36
	s_and_b64 vcc, s[0:1], vcc
	v_max3_f32 v32, v32, v37, v35
	v_cndmask_b32_e32 v34, v233, v47, vcc
	v_max3_f32 v32, v32, v33, v34
	v_mov_b32_e32 v41, v32
	s_nop 1
	v_permlane32_swap_b32 v32, v41
	v_cmp_lt_f32_e32 vcc, s35, v184
	v_lshlrev_b32_e32 v80, 1, v80
	s_waitcnt lgkmcnt(0)
	v_max_f32_e32 v41, v41, v41
	v_max_f32_e32 v32, v32, v41
	v_sub_f32_e32 v41, v184, v32
	v_mul_f32_e32 v41, 0x3fb8aa3b, v41
	v_sub_f32_e32 v42, v171, v32
	v_exp_f32_e32 v41, v41
	v_mul_f32_e32 v42, 0x3fb8aa3b, v42
	v_sub_f32_e32 v44, v177, v32
	v_exp_f32_e32 v42, v42
	v_mul_f32_e32 v44, 0x3fb8aa3b, v44
	v_exp_f32_e32 v44, v44
	v_cndmask_b32_e32 v41, 0, v41, vcc
	v_cmp_lt_f32_e32 vcc, s35, v171
	v_add_f32_e32 v43, 0, v41
	v_sub_f32_e32 v46, v176, v32
	v_cndmask_b32_e32 v42, 0, v42, vcc
	v_cmp_lt_f32_e32 vcc, s35, v177
	v_add_f32_e32 v45, v42, v43
	v_mul_f32_e32 v46, 0x3fb8aa3b, v46
	v_cndmask_b32_e32 v43, 0, v44, vcc
	v_sub_f32_e32 v44, v169, v32
	v_mul_f32_e32 v44, 0x3fb8aa3b, v44
	v_exp_f32_e32 v44, v44
	v_exp_f32_e32 v46, v46
	v_cmp_lt_f32_e32 vcc, s35, v169
	v_add_f32_e32 v45, v43, v45
	v_sub_f32_e32 v56, v175, v32
	v_cndmask_b32_e32 v44, 0, v44, vcc
	v_cmp_lt_f32_e32 vcc, s35, v176
	v_add_f32_e32 v47, v44, v45
	v_mul_f32_e32 v56, 0x3fb8aa3b, v56
	v_cndmask_b32_e32 v45, 0, v46, vcc
	v_add_f32_e32 v46, v45, v47
	v_sub_f32_e32 v47, v168, v32
	v_mul_f32_e32 v47, 0x3fb8aa3b, v47
	v_exp_f32_e32 v47, v47
	v_sub_f32_e32 v57, v167, v32
	v_exp_f32_e32 v56, v56
	v_mul_f32_e32 v57, 0x3fb8aa3b, v57
	v_sub_f32_e32 v58, v174, v32
	v_exp_f32_e32 v57, v57
	v_mul_f32_e32 v58, 0x3fb8aa3b, v58
	v_cmp_lt_f32_e32 vcc, s35, v168
	v_exp_f32_e32 v58, v58
	v_sub_f32_e32 v60, v173, v32
	v_cndmask_b32_e32 v47, 0, v47, vcc
	v_cmp_lt_f32_e32 vcc, s35, v175
	v_add_f32_e32 v46, v47, v46
	v_mul_f32_e32 v60, 0x3fb8aa3b, v60
; __device__ __forceinline__ void attn_prompt_wave(const Params& P, int l, int qt, int tid_in) {
;     ...
;     for (int kb = 0; kb < 5; ++kb)
; #pragma unroll
;         for (int i = 0; i < 16; ++i) { const float p = st[kb][i] > -1e29f ? __expf(st[kb][i] - mx) : 0.f; st[kb][i] = p; sum += p; }
	v_cndmask_b32_e32 v56, 0, v56, vcc
	v_cmp_lt_f32_e32 vcc, s35, v167
	v_add_f32_e32 v46, v56, v46
	v_exp_f32_e32 v60, v60
	v_cndmask_b32_e32 v59, 0, v57, vcc
	v_cmp_lt_f32_e32 vcc, s35, v174
	v_add_f32_e32 v57, v59, v46
	v_sub_f32_e32 v62, v172, v32
	v_cndmask_b32_e32 v46, 0, v58, vcc
	v_add_f32_e32 v58, v46, v57
	v_sub_f32_e32 v57, v165, v32
	v_mul_f32_e32 v57, 0x3fb8aa3b, v57
	v_exp_f32_e32 v57, v57
	v_cmp_lt_f32_e32 vcc, s35, v165
	v_mul_f32_e32 v62, 0x3fb8aa3b, v62
	v_exp_f32_e32 v62, v62
	v_cndmask_b32_e32 v57, 0, v57, vcc
	v_cmp_lt_f32_e32 vcc, s35, v173
	v_add_f32_e32 v61, v57, v58
	v_sub_f32_e32 v165, v0, v32
	v_cndmask_b32_e32 v58, 0, v60, vcc
	v_sub_f32_e32 v60, v164, v32
	v_mul_f32_e32 v60, 0x3fb8aa3b, v60
	v_exp_f32_e32 v60, v60
	v_cmp_lt_f32_e32 vcc, s35, v164
	v_add_f32_e32 v61, v58, v61
	v_sub_f32_e32 v164, v170, v32
	v_cndmask_b32_e32 v60, 0, v60, vcc
	v_cmp_lt_f32_e32 vcc, s35, v172
	v_add_f32_e32 v63, v60, v61
	v_mul_f32_e32 v164, 0x3fb8aa3b, v164
	v_cndmask_b32_e32 v61, 0, v62, vcc
	v_add_f32_e32 v62, v61, v63
	v_sub_f32_e32 v63, v163, v32
	v_mul_f32_e32 v63, 0x3fb8aa3b, v63
	v_exp_f32_e32 v63, v63
	v_exp_f32_e32 v164, v164
	v_cmp_lt_f32_e32 vcc, s35, v163
	v_mul_f32_e32 v165, 0x3fb8aa3b, v165
	v_exp_f32_e32 v167, v165
	v_cndmask_b32_e32 v63, 0, v63, vcc
	v_cmp_lt_f32_e32 vcc, s35, v170
	v_add_f32_e32 v62, v63, v62
	s_nop 0
	v_cndmask_b32_e32 v163, 0, v164, vcc
	v_sub_f32_e32 v164, v162, v32
	v_mul_f32_e32 v164, 0x3fb8aa3b, v164
	v_exp_f32_e32 v164, v164
	v_cmp_lt_f32_e32 vcc, s35, v162
	v_add_f32_e32 v62, v163, v62
	s_nop 0
	v_cndmask_b32_e32 v165, 0, v164, vcc
	v_cmp_lt_f32_e32 vcc, s35, v0
	v_add_f32_e32 v162, v165, v62
	v_sub_f32_e32 v164, v2, v32
	v_cndmask_b32_e32 v62, 0, v167, vcc
	v_add_f32_e32 v0, v62, v162
	v_sub_f32_e32 v162, v1, v32
	v_mul_f32_e32 v162, 0x3fb8aa3b, v162
	v_exp_f32_e32 v162, v162
	v_mul_f32_e32 v164, 0x3fb8aa3b, v164
	v_cmp_lt_f32_e32 vcc, s35, v1
	v_sub_f32_e32 v1, v3, v32
	v_exp_f32_e32 v164, v164
	v_cndmask_b32_e32 v162, 0, v162, vcc
	v_cmp_lt_f32_e32 vcc, s35, v2
	v_mul_f32_e32 v1, 0x3fb8aa3b, v1
	v_sub_f32_e32 v2, v4, v32
	v_exp_f32_e32 v1, v1
	v_mul_f32_e32 v2, 0x3fb8aa3b, v2
	v_exp_f32_e32 v2, v2
	v_cndmask_b32_e32 v164, 0, v164, vcc
	v_cmp_lt_f32_e32 vcc, s35, v3
	v_add_f32_e32 v0, v162, v0
	v_add_f32_e32 v0, v164, v0
	v_cndmask_b32_e32 v167, 0, v1, vcc
	v_cmp_lt_f32_e32 vcc, s35, v4
	v_sub_f32_e32 v1, v5, v32
	v_mul_f32_e32 v1, 0x3fb8aa3b, v1
	v_cndmask_b32_e32 v168, 0, v2, vcc
	v_sub_f32_e32 v2, v6, v32
	v_exp_f32_e32 v1, v1
	v_mul_f32_e32 v2, 0x3fb8aa3b, v2
	v_exp_f32_e32 v2, v2
	v_cmp_lt_f32_e32 vcc, s35, v5
	v_add_f32_e32 v0, v167, v0
	v_add_f32_e32 v0, v168, v0
	v_cndmask_b32_e32 v169, 0, v1, vcc
	v_cmp_lt_f32_e32 vcc, s35, v6
	v_sub_f32_e32 v1, v7, v32
	v_mul_f32_e32 v1, 0x3fb8aa3b, v1
	v_cndmask_b32_e32 v170, 0, v2, vcc
	v_sub_f32_e32 v2, v8, v32
	v_exp_f32_e32 v1, v1
	v_mul_f32_e32 v2, 0x3fb8aa3b, v2
	v_exp_f32_e32 v2, v2
	v_cmp_lt_f32_e32 vcc, s35, v7
	v_add_f32_e32 v0, v169, v0
	v_add_f32_e32 v0, v170, v0
	v_cndmask_b32_e32 v171, 0, v1, vcc
	v_cmp_lt_f32_e32 vcc, s35, v8
	v_sub_f32_e32 v1, v9, v32
	v_mul_f32_e32 v1, 0x3fb8aa3b, v1
	v_cndmask_b32_e32 v172, 0, v2, vcc
	v_sub_f32_e32 v2, v10, v32
	v_exp_f32_e32 v1, v1
	v_mul_f32_e32 v2, 0x3fb8aa3b, v2
	v_exp_f32_e32 v2, v2
	v_cmp_lt_f32_e32 vcc, s35, v9
	v_add_f32_e32 v0, v171, v0
	v_add_f32_e32 v0, v172, v0
	v_cndmask_b32_e32 v173, 0, v1, vcc
	v_cmp_lt_f32_e32 vcc, s35, v10
	v_sub_f32_e32 v1, v11, v32
	v_mul_f32_e32 v1, 0x3fb8aa3b, v1
	v_cndmask_b32_e32 v174, 0, v2, vcc
	v_sub_f32_e32 v2, v12, v32
	v_exp_f32_e32 v1, v1
	v_mul_f32_e32 v2, 0x3fb8aa3b, v2
	v_exp_f32_e32 v2, v2
	v_cmp_lt_f32_e32 vcc, s35, v11
	v_add_f32_e32 v0, v173, v0
	v_add_f32_e32 v0, v174, v0
	v_cndmask_b32_e32 v175, 0, v1, vcc
	v_cmp_lt_f32_e32 vcc, s35, v12
	v_sub_f32_e32 v1, v13, v32
	v_mul_f32_e32 v1, 0x3fb8aa3b, v1
	v_cndmask_b32_e32 v176, 0, v2, vcc
	v_sub_f32_e32 v2, v14, v32
	v_exp_f32_e32 v1, v1
	v_mul_f32_e32 v2, 0x3fb8aa3b, v2
	v_exp_f32_e32 v2, v2
	v_cmp_lt_f32_e32 vcc, s35, v13
	v_add_f32_e32 v0, v175, v0
	v_add_f32_e32 v0, v176, v0
	v_cndmask_b32_e32 v177, 0, v1, vcc
	v_cmp_lt_f32_e32 vcc, s35, v14
	v_sub_f32_e32 v1, v15, v32
	v_mul_f32_e32 v1, 0x3fb8aa3b, v1
	v_cndmask_b32_e32 v182, 0, v2, vcc
	v_sub_f32_e32 v2, v16, v32
	v_exp_f32_e32 v1, v1
	v_mul_f32_e32 v2, 0x3fb8aa3b, v2
	v_exp_f32_e32 v2, v2
	v_cmp_lt_f32_e32 vcc, s35, v15
	v_add_f32_e32 v0, v177, v0
	v_add_f32_e32 v0, v182, v0
	v_cndmask_b32_e32 v183, 0, v1, vcc
	v_cmp_lt_f32_e32 vcc, s35, v16
	v_sub_f32_e32 v1, v17, v32
	v_mul_f32_e32 v1, 0x3fb8aa3b, v1
	v_cndmask_b32_e32 v184, 0, v2, vcc
	v_sub_f32_e32 v2, v18, v32
	v_exp_f32_e32 v1, v1
	v_mul_f32_e32 v2, 0x3fb8aa3b, v2
	v_exp_f32_e32 v2, v2
	v_cmp_lt_f32_e32 vcc, s35, v17
	v_add_f32_e32 v0, v183, v0
	v_add_f32_e32 v0, v184, v0
	v_cndmask_b32_e32 v185, 0, v1, vcc
	v_cmp_lt_f32_e32 vcc, s35, v18
	v_sub_f32_e32 v1, v19, v32
	v_mul_f32_e32 v1, 0x3fb8aa3b, v1
	v_cndmask_b32_e32 v186, 0, v2, vcc
	v_sub_f32_e32 v2, v20, v32
	v_exp_f32_e32 v1, v1
	v_mul_f32_e32 v2, 0x3fb8aa3b, v2
	v_exp_f32_e32 v2, v2
	v_cmp_lt_f32_e32 vcc, s35, v19
	v_add_f32_e32 v0, v185, v0
	v_add_f32_e32 v0, v186, v0
	v_cndmask_b32_e32 v187, 0, v1, vcc
	v_cmp_lt_f32_e32 vcc, s35, v20
	v_sub_f32_e32 v1, v21, v32
	v_mul_f32_e32 v1, 0x3fb8aa3b, v1
	v_cndmask_b32_e32 v188, 0, v2, vcc
	v_sub_f32_e32 v2, v22, v32
	v_exp_f32_e32 v1, v1
	v_mul_f32_e32 v2, 0x3fb8aa3b, v2
	v_exp_f32_e32 v2, v2
	v_cmp_lt_f32_e32 vcc, s35, v21
	v_add_f32_e32 v0, v187, v0
	v_add_f32_e32 v0, v188, v0
	v_cndmask_b32_e32 v189, 0, v1, vcc
	v_cmp_lt_f32_e32 vcc, s35, v22
	v_sub_f32_e32 v1, v23, v32
; __device__ __forceinline__ unsigned cvtpk(float lo, float hi) { f32x2_t v = {lo, hi}; bf16x2_t b = __builtin_convertvector(v, bf16x2_t); return __builtin_bit_cast(unsigned, b); }
; #define MFMA32(a, b, c) __builtin_amdgcn_mfma_f32_32x32x16_bf16((a), (b), (c), 0, 0, 0)
; __device__ __forceinline__ void attn_prompt_wave(const Params& P, int l, int qt, int tid_in) {
;     ...
;     for (int kb = 0; kb < 5; ++kb)
; #pragma unroll
;         for (int i = 0; i < 16; ++i) { const float p = st[kb][i] > -1e29f ? __expf(st[kb][i] - mx) : 0.f; st[kb][i] = p; sum += p; }
;     sum += __shfl_xor(sum, 32);
;     const float inv = 1.f / (sum + __expf(sink - mx));
;     f32x16 o0, o1;
; #pragma unroll
;     for (int i = 0; i < 16; ++i) { o0[i] = 0.f; o1[i] = 0.f; }
; #pragma unroll
;     for (int kb = 0; kb < 5; ++kb)
; #pragma unroll
;         for (int s = 0; s < 2; ++s) {
;             u32x4 pw; pw.x = cvtpk(st[kb][8 * s], st[kb][8 * s + 1]); pw.y = cvtpk(st[kb][8 * s + 2], st[kb][8 * s + 3]); pw.z = cvtpk(st[kb][8 * s + 4], st[kb][8 * s + 5]); pw.w = cvtpk(st[kb][8 * s + 6], st[kb][8 * s + 7]);
;             const bf16x8 pf = __builtin_bit_cast(bf16x8, pw);
; #pragma unroll
;             for (int db = 0; db < 2; ++db) {
;                 const u32x2 va = vfa[kb][s][db], vb = vfb[kb][s][db];
;                 u32x4 vw; vw.x = va.x; vw.y = va.y; vw.z = vb.x; vw.w = vb.y;
;                 const bf16x8 vf = __builtin_bit_cast(bf16x8, vw);
;                 if (db == 0) o0 = MFMA32(vf, pf, o0); else o1 = MFMA32(vf, pf, o1);
;             }
;         }
	v_mul_f32_e32 v1, 0x3fb8aa3b, v1
	v_cndmask_b32_e32 v190, 0, v2, vcc
	v_sub_f32_e32 v2, v24, v32
	v_exp_f32_e32 v1, v1
	v_mul_f32_e32 v2, 0x3fb8aa3b, v2
	v_exp_f32_e32 v2, v2
	v_cmp_lt_f32_e32 vcc, s35, v23
	v_add_f32_e32 v0, v189, v0
	v_add_f32_e32 v0, v190, v0
	v_cndmask_b32_e32 v191, 0, v1, vcc
	v_cmp_lt_f32_e32 vcc, s35, v24
	v_sub_f32_e32 v1, v25, v32
	v_mul_f32_e32 v1, 0x3fb8aa3b, v1
	v_cndmask_b32_e32 v192, 0, v2, vcc
	v_sub_f32_e32 v2, v26, v32
	v_exp_f32_e32 v1, v1
	v_mul_f32_e32 v2, 0x3fb8aa3b, v2
	v_exp_f32_e32 v2, v2
	v_cmp_lt_f32_e32 vcc, s35, v25
	v_add_f32_e32 v0, v191, v0
	v_add_f32_e32 v0, v192, v0
	v_cndmask_b32_e32 v193, 0, v1, vcc
	v_cmp_lt_f32_e32 vcc, s35, v26
	v_sub_f32_e32 v1, v27, v32
	v_mul_f32_e32 v1, 0x3fb8aa3b, v1
	v_cndmask_b32_e32 v194, 0, v2, vcc
	v_sub_f32_e32 v2, v28, v32
	v_exp_f32_e32 v1, v1
	v_mul_f32_e32 v2, 0x3fb8aa3b, v2
	v_exp_f32_e32 v2, v2
	v_cmp_lt_f32_e32 vcc, s35, v27
	v_add_f32_e32 v0, v193, v0
	v_add_f32_e32 v0, v194, v0
	v_cndmask_b32_e32 v195, 0, v1, vcc
	v_cmp_lt_f32_e32 vcc, s35, v28
	v_sub_f32_e32 v1, v29, v32
	v_mul_f32_e32 v1, 0x3fb8aa3b, v1
	v_cndmask_b32_e32 v196, 0, v2, vcc
	v_sub_f32_e32 v2, v30, v32
	v_exp_f32_e32 v1, v1
	v_mul_f32_e32 v2, 0x3fb8aa3b, v2
	v_exp_f32_e32 v2, v2
	v_cmp_lt_f32_e32 vcc, s35, v29
	v_add_f32_e32 v0, v195, v0
	v_add_f32_e32 v0, v196, v0
	v_cndmask_b32_e32 v197, 0, v1, vcc
	v_cmp_lt_f32_e32 vcc, s35, v30
	v_sub_f32_e32 v1, v31, v32
	v_mul_f32_e32 v1, 0x3fb8aa3b, v1
	v_cndmask_b32_e32 v198, 0, v2, vcc
	v_sub_f32_e32 v2, v69, v32
	v_exp_f32_e32 v1, v1
	v_mul_f32_e32 v2, 0x3fb8aa3b, v2
	v_exp_f32_e32 v2, v2
	v_cmp_lt_f32_e32 vcc, s35, v31
	v_add_f32_e32 v0, v197, v0
	v_add_f32_e32 v0, v198, v0
	v_cndmask_b32_e32 v199, 0, v1, vcc
	v_cmp_lt_f32_e32 vcc, s35, v69
	v_sub_f32_e32 v1, v64, v32
	v_mul_f32_e32 v1, 0x3fb8aa3b, v1
	v_cndmask_b32_e32 v69, 0, v2, vcc
	v_sub_f32_e32 v2, v71, v32
	v_exp_f32_e32 v1, v1
	v_mul_f32_e32 v2, 0x3fb8aa3b, v2
	v_exp_f32_e32 v2, v2
	v_cmp_lt_f32_e32 vcc, s35, v64
	v_add_f32_e32 v0, v199, v0
	v_add_f32_e32 v0, v69, v0
	v_cndmask_b32_e32 v64, 0, v1, vcc
	v_cmp_lt_f32_e32 vcc, s35, v71
	v_sub_f32_e32 v1, v65, v32
	v_mul_f32_e32 v1, 0x3fb8aa3b, v1
	v_cndmask_b32_e32 v71, 0, v2, vcc
	v_sub_f32_e32 v2, v73, v32
	v_exp_f32_e32 v1, v1
	v_mul_f32_e32 v2, 0x3fb8aa3b, v2
	v_exp_f32_e32 v2, v2
	v_cmp_lt_f32_e32 vcc, s35, v65
	v_add_f32_e32 v0, v64, v0
	v_add_f32_e32 v0, v71, v0
	v_cndmask_b32_e32 v65, 0, v1, vcc
	v_cmp_lt_f32_e32 vcc, s35, v73
	v_sub_f32_e32 v1, v66, v32
	v_mul_f32_e32 v1, 0x3fb8aa3b, v1
	v_cndmask_b32_e32 v73, 0, v2, vcc
	v_sub_f32_e32 v2, v75, v32
	v_exp_f32_e32 v1, v1
	v_mul_f32_e32 v2, 0x3fb8aa3b, v2
	v_exp_f32_e32 v2, v2
	v_cmp_lt_f32_e32 vcc, s35, v66
	v_add_f32_e32 v0, v65, v0
	v_add_f32_e32 v0, v73, v0
	v_cndmask_b32_e32 v66, 0, v1, vcc
	v_cmp_lt_f32_e32 vcc, s35, v75
	v_sub_f32_e32 v1, v67, v32
	v_mul_f32_e32 v1, 0x3fb8aa3b, v1
	v_cndmask_b32_e32 v75, 0, v2, vcc
	v_sub_f32_e32 v2, v76, v32
	v_exp_f32_e32 v1, v1
	v_mul_f32_e32 v2, 0x3fb8aa3b, v2
	v_exp_f32_e32 v2, v2
	v_cmp_lt_f32_e32 vcc, s35, v67
	v_add_f32_e32 v0, v66, v0
	v_add_f32_e32 v0, v75, v0
	v_cndmask_b32_e32 v67, 0, v1, vcc
	v_cmp_lt_f32_e32 vcc, s35, v76
	v_sub_f32_e32 v1, v68, v32
	v_mul_f32_e32 v1, 0x3fb8aa3b, v1
	v_cndmask_b32_e32 v76, 0, v2, vcc
	v_sub_f32_e32 v2, v77, v32
	v_exp_f32_e32 v1, v1
	v_mul_f32_e32 v2, 0x3fb8aa3b, v2
	v_exp_f32_e32 v2, v2
	v_cmp_lt_f32_e32 vcc, s35, v68
	v_add_f32_e32 v0, v67, v0
	v_add_f32_e32 v0, v76, v0
	v_cndmask_b32_e32 v68, 0, v1, vcc
	v_cmp_lt_f32_e32 vcc, s35, v77
	v_sub_f32_e32 v1, v70, v32
	v_mul_f32_e32 v1, 0x3fb8aa3b, v1
	v_cndmask_b32_e32 v77, 0, v2, vcc
	v_sub_f32_e32 v2, v78, v32
	v_exp_f32_e32 v1, v1
	v_mul_f32_e32 v2, 0x3fb8aa3b, v2
	v_exp_f32_e32 v2, v2
	v_cmp_lt_f32_e32 vcc, s35, v70
	v_add_f32_e32 v0, v68, v0
	v_add_f32_e32 v0, v77, v0
	v_cndmask_b32_e32 v70, 0, v1, vcc
	v_cmp_lt_f32_e32 vcc, s35, v78
	v_sub_f32_e32 v1, v72, v32
	v_mul_f32_e32 v1, 0x3fb8aa3b, v1
	v_cndmask_b32_e32 v78, 0, v2, vcc
	v_sub_f32_e32 v2, v79, v32
	v_exp_f32_e32 v1, v1
	v_mul_f32_e32 v2, 0x3fb8aa3b, v2
	v_exp_f32_e32 v2, v2
	v_cmp_lt_f32_e32 vcc, s35, v72
	v_add_f32_e32 v0, v70, v0
	v_add_f32_e32 v0, v78, v0
	v_cndmask_b32_e32 v72, 0, v1, vcc
	v_cmp_lt_f32_e32 vcc, s35, v79
	v_sub_f32_e32 v1, v74, v32
	v_mul_f32_e32 v1, 0x3fb8aa3b, v1
	v_cndmask_b32_e32 v79, 0, v2, vcc
	v_sub_f32_e32 v2, v55, v32
	v_exp_f32_e32 v1, v1
	v_mul_f32_e32 v2, 0x3fb8aa3b, v2
	v_exp_f32_e32 v2, v2
	v_add_f32_e32 v0, v72, v0
	v_cmp_lt_f32_e32 vcc, s35, v74
	v_add_f32_e32 v0, v79, v0
	v_sub_f32_e32 v22, v54, v32
	v_cndmask_b32_e32 v74, 0, v1, vcc
	v_cmp_lt_f32_e32 vcc, s35, v55
	v_add_f32_e32 v0, v74, v0
	v_mul_f32_e32 v22, 0x3fb8aa3b, v22
	v_cndmask_b32_e32 v55, 0, v2, vcc
	v_add_f32_e32 v20, v55, v0
	v_sub_f32_e32 v0, v53, v32
	v_mul_f32_e32 v0, 0x3fb8aa3b, v0
	v_exp_f32_e32 v21, v0
	v_exp_f32_e32 v22, v22
	v_cmp_lt_f32_e32 vcc, s35, v53
	v_cvt_pk_bf16_f32 v16, v41, v42
	v_cvt_pk_bf16_f32 v17, v43, v44
	v_cvt_pk_bf16_f32 v18, v45, v47
	v_cvt_pk_bf16_f32 v19, v56, v59
	v_cndmask_b32_e32 v47, 0, v21, vcc
	v_cmp_lt_f32_e32 vcc, s35, v54
	v_mfma_f32_32x32x16_bf16 v[0:15], v[86:89], v[16:19], 0
	v_add_f32_e32 v41, v47, v20
	v_cndmask_b32_e32 v53, 0, v22, vcc
	v_sub_f32_e32 v42, v52, v32
	v_mul_f32_e32 v42, 0x3fb8aa3b, v42
	v_exp_f32_e32 v54, v42
	v_cvt_pk_bf16_f32 v42, v46, v57
	v_cvt_pk_bf16_f32 v43, v58, v60
	v_mfma_f32_32x32x16_bf16 v[16:31], v[82:85], v[16:19], 0
	v_cvt_pk_bf16_f32 v44, v61, v63
	v_cvt_pk_bf16_f32 v45, v163, v165
	v_cmp_lt_f32_e32 vcc, s35, v52
	v_sub_f32_e32 v52, v50, v32
	v_mul_f32_e32 v52, 0x3fb8aa3b, v52
	v_cndmask_b32_e32 v46, 0, v54, vcc
; __device__ __forceinline__ unsigned cvtpk(float lo, float hi) { f32x2_t v = {lo, hi}; bf16x2_t b = __builtin_convertvector(v, bf16x2_t); return __builtin_bit_cast(unsigned, b); }
; #define MFMA32(a, b, c) __builtin_amdgcn_mfma_f32_32x32x16_bf16((a), (b), (c), 0, 0, 0)
; __device__ __forceinline__ void attn_prompt_wave(const Params& P, int l, int qt, int tid_in) {
;     ...
;         for (int i = 0; i < 16; ++i) { const float p = st[kb][i] > -1e29f ? __expf(st[kb][i] - mx) : 0.f; st[kb][i] = p; sum += p; }
;     sum += __shfl_xor(sum, 32);
;     const float inv = 1.f / (sum + __expf(sink - mx));
;     f32x16 o0, o1;
; #pragma unroll
;     for (int i = 0; i < 16; ++i) { o0[i] = 0.f; o1[i] = 0.f; }
; #pragma unroll
;     for (int kb = 0; kb < 5; ++kb)
; #pragma unroll
;         for (int s = 0; s < 2; ++s) {
;             u32x4 pw; pw.x = cvtpk(st[kb][8 * s], st[kb][8 * s + 1]); pw.y = cvtpk(st[kb][8 * s + 2], st[kb][8 * s + 3]); pw.z = cvtpk(st[kb][8 * s + 4], st[kb][8 * s + 5]); pw.w = cvtpk(st[kb][8 * s + 6], st[kb][8 * s + 7]);
;             const bf16x8 pf = __builtin_bit_cast(bf16x8, pw);
; #pragma unroll
;             for (int db = 0; db < 2; ++db) {
;                 const u32x2 va = vfa[kb][s][db], vb = vfb[kb][s][db];
;                 u32x4 vw; vw.x = va.x; vw.y = va.y; vw.z = vb.x; vw.w = vb.y;
;                 const bf16x8 vf = __builtin_bit_cast(bf16x8, vw);
;                 if (db == 0) o0 = MFMA32(vf, pf, o0); else o1 = MFMA32(vf, pf, o1);
;             }
;         }
	v_exp_f32_e32 v52, v52
	v_mfma_f32_32x32x16_bf16 v[0:15], v[158:161], v[42:45], v[0:15]
	v_cmp_lt_f32_e32 vcc, s35, v50
	v_add_f32_e32 v41, v53, v41
	v_add_f32_e32 v41, v46, v41
	v_cndmask_b32_e32 v50, 0, v52, vcc
	v_sub_f32_e32 v52, v48, v32
	v_cmp_lt_f32_e32 vcc, s35, v51
	v_add_f32_e32 v41, v50, v41
	v_mfma_f32_32x32x16_bf16 v[16:31], v[154:157], v[42:45], v[16:31]
	v_sub_f32_e32 v42, v51, v32
	v_mul_f32_e32 v42, 0x3fb8aa3b, v42
	v_exp_f32_e32 v54, v42
	v_cvt_pk_bf16_f32 v42, v62, v162
	v_cvt_pk_bf16_f32 v43, v164, v167
	v_cvt_pk_bf16_f32 v44, v168, v169
	v_cvt_pk_bf16_f32 v45, v170, v171
	v_cndmask_b32_e32 v51, 0, v54, vcc
	v_sub_f32_e32 v54, v49, v32
	v_mfma_f32_32x32x16_bf16 v[0:15], v[150:153], v[42:45], v[0:15]
	v_mul_f32_e32 v54, 0x3fb8aa3b, v54
	v_cmp_lt_f32_e32 vcc, s35, v48
	v_exp_f32_e32 v54, v54
	v_add_f32_e32 v41, v51, v41
	v_mfma_f32_32x32x16_bf16 v[16:31], v[146:149], v[42:45], v[16:31]
	v_mul_f32_e32 v42, 0x3fb8aa3b, v52
	v_exp_f32_e32 v52, v42
	v_cvt_pk_bf16_f32 v42, v172, v173
	v_cvt_pk_bf16_f32 v43, v174, v175
	v_cvt_pk_bf16_f32 v44, v176, v177
	v_cvt_pk_bf16_f32 v45, v182, v183
	v_cndmask_b32_e32 v48, 0, v52, vcc
	v_cmp_lt_f32_e32 vcc, s35, v49
	v_mfma_f32_32x32x16_bf16 v[0:15], v[142:145], v[42:45], v[0:15]
	v_add_f32_e32 v41, v48, v41
	v_cndmask_b32_e32 v49, 0, v54, vcc
	v_cmp_lt_f32_e32 vcc, s35, v40
	v_add_f32_e32 v41, v49, v41
	v_mfma_f32_32x32x16_bf16 v[16:31], v[138:141], v[42:45], v[16:31]
	v_sub_f32_e32 v42, v40, v32
	v_mul_f32_e32 v42, 0x3fb8aa3b, v42
	v_exp_f32_e32 v52, v42
	v_cvt_pk_bf16_f32 v42, v184, v185
	v_cvt_pk_bf16_f32 v43, v186, v187
	v_cvt_pk_bf16_f32 v44, v188, v189
	v_cvt_pk_bf16_f32 v45, v190, v191
	v_sub_f32_e32 v40, v38, v32
	v_mul_f32_e32 v40, 0x3fb8aa3b, v40
	v_mfma_f32_32x32x16_bf16 v[0:15], v[134:137], v[42:45], v[0:15]
	v_exp_f32_e32 v56, v40
	v_sub_f32_e32 v40, v39, v32
	v_cndmask_b32_e32 v52, 0, v52, vcc
	v_mul_f32_e32 v40, 0x3fb8aa3b, v40
	v_add_f32_e32 v54, v52, v41
	v_cvt_pk_bf16_f32 v41, v194, v195
	v_cmp_lt_f32_e32 vcc, s35, v38
	v_mfma_f32_32x32x16_bf16 v[16:31], v[130:133], v[42:45], v[16:31]
	v_exp_f32_e32 v44, v40
	v_cvt_pk_bf16_f32 v40, v192, v193
	v_cvt_pk_bf16_f32 v42, v196, v197
	v_cvt_pk_bf16_f32 v43, v198, v199
	v_cndmask_b32_e32 v45, 0, v56, vcc
	v_cmp_lt_f32_e32 vcc, s35, v39
	v_add_f32_e32 v38, v45, v54
	v_mfma_f32_32x32x16_bf16 v[0:15], v[126:129], v[40:43], v[0:15]
	v_cndmask_b32_e32 v44, 0, v44, vcc
	v_add_f32_e32 v54, v44, v38
	v_sub_f32_e32 v38, v36, v32
	v_mul_f32_e32 v38, 0x3fb8aa3b, v38
	v_cvt_pk_bf16_f32 v39, v71, v65
	v_cmp_lt_f32_e32 vcc, s35, v36
	v_sub_f32_e32 v36, v35, v32
	v_mfma_f32_32x32x16_bf16 v[16:31], v[122:125], v[40:43], v[16:31]
	v_exp_f32_e32 v42, v38
	v_sub_f32_e32 v43, v37, v32
	v_cvt_pk_bf16_f32 v38, v69, v64
	v_cvt_pk_bf16_f32 v40, v73, v66
	v_cvt_pk_bf16_f32 v41, v75, v67
	v_mul_f32_e32 v43, 0x3fb8aa3b, v43
	v_exp_f32_e32 v43, v43
	v_mfma_f32_32x32x16_bf16 v[0:15], v[118:121], v[38:41], v[0:15]
	v_mul_f32_e32 v36, 0x3fb8aa3b, v36
	v_cndmask_b32_e32 v42, 0, v42, vcc
	v_cmp_lt_f32_e32 vcc, s35, v37
	v_add_f32_e32 v54, v42, v54
	v_cvt_pk_bf16_f32 v37, v77, v70
	v_cndmask_b32_e32 v43, 0, v43, vcc
	v_cmp_lt_f32_e32 vcc, s35, v35
	v_mfma_f32_32x32x16_bf16 v[16:31], v[114:117], v[38:41], v[16:31]
	v_exp_f32_e32 v40, v36
	v_add_f32_e32 v41, v43, v54
	v_cvt_pk_bf16_f32 v36, v76, v68
	v_cvt_pk_bf16_f32 v38, v78, v72
	v_cndmask_b32_e32 v40, 0, v40, vcc
	v_cvt_pk_bf16_f32 v39, v79, v74
	v_add_f32_e32 v35, v40, v41
	v_sub_f32_e32 v41, v33, v32
	v_mfma_f32_32x32x16_bf16 v[0:15], v[110:113], v[36:39], v[0:15]
	v_mul_f32_e32 v41, 0x3fb8aa3b, v41
	v_exp_f32_e32 v41, v41
	v_cmp_lt_f32_e32 vcc, s35, v33
	s_nop 1
	v_cndmask_b32_e32 v33, 0, v41, vcc
	v_cmp_lt_f32_e32 vcc, s35, v34
	v_mfma_f32_32x32x16_bf16 v[16:31], v[106:109], v[36:39], v[16:31]
	v_sub_f32_e32 v36, v34, v32
	v_mul_f32_e32 v36, 0x3fb8aa3b, v36
	v_exp_f32_e32 v54, v36
	v_add_f32_e32 v35, v33, v35
	v_cvt_pk_bf16_f32 v37, v53, v46
	v_cvt_pk_bf16_f32 v36, v55, v47
	v_cndmask_b32_e32 v41, 0, v54, vcc
	v_add_f32_e32 v46, v41, v35
	v_mov_b32_e32 v47, v46
	s_nop 1
	v_permlane32_swap_b32 v46, v47
	v_sub_f32_e32 v32, v166, v32
	v_mul_f32_e32 v32, 0x3fb8aa3b, v32
	v_exp_f32_e32 v32, v32
	v_cvt_pk_bf16_f32 v38, v50, v51
	v_cvt_pk_bf16_f32 v39, v48, v49
	v_cvt_pk_bf16_f32 v34, v52, v45
	v_cvt_pk_bf16_f32 v35, v44, v42
	v_mfma_f32_32x32x16_bf16 v[0:15], v[102:105], v[36:39], v[0:15]
	v_mfma_f32_32x32x16_bf16 v[16:31], v[98:101], v[36:39], v[16:31]
	v_cvt_pk_bf16_f32 v37, v33, v41
	s_waitcnt lgkmcnt(0)
; __device__ __forceinline__ unsigned cvtpk(float lo, float hi) { f32x2_t v = {lo, hi}; bf16x2_t b = __builtin_convertvector(v, bf16x2_t); return __builtin_bit_cast(unsigned, b); }
; #define MFMA32(a, b, c) __builtin_amdgcn_mfma_f32_32x32x16_bf16((a), (b), (c), 0, 0, 0)
; __device__ __forceinline__ void attn_prompt_wave(const Params& P, int l, int qt, int tid_in) {
;     ...
;     sum += __shfl_xor(sum, 32);
;     const float inv = 1.f / (sum + __expf(sink - mx));
;     f32x16 o0, o1;
; #pragma unroll
;     for (int i = 0; i < 16; ++i) { o0[i] = 0.f; o1[i] = 0.f; }
; #pragma unroll
;     for (int kb = 0; kb < 5; ++kb)
; #pragma unroll
;         for (int s = 0; s < 2; ++s) {
;             u32x4 pw; pw.x = cvtpk(st[kb][8 * s], st[kb][8 * s + 1]); pw.y = cvtpk(st[kb][8 * s + 2], st[kb][8 * s + 3]); pw.z = cvtpk(st[kb][8 * s + 4], st[kb][8 * s + 5]); pw.w = cvtpk(st[kb][8 * s + 6], st[kb][8 * s + 7]);
;             const bf16x8 pf = __builtin_bit_cast(bf16x8, pw);
; #pragma unroll
;             for (int db = 0; db < 2; ++db) {
;                 const u32x2 va = vfa[kb][s][db], vb = vfb[kb][s][db];
;                 u32x4 vw; vw.x = va.x; vw.y = va.y; vw.z = vb.x; vw.w = vb.y;
;                 const bf16x8 vf = __builtin_bit_cast(bf16x8, vw);
;                 if (db == 0) o0 = MFMA32(vf, pf, o0); else o1 = MFMA32(vf, pf, o1);
;             }
;         }
;     bf16* op = ATT + (size_t)qi * 512 + head * 64 + 4 * h;
; #pragma unroll
;     for (int g = 0; g < 4; ++g) {
;         u32x2 w; w.x = cvtpk(o0[4 * g] * inv, o0[4 * g + 1] * inv); w.y = cvtpk(o0[4 * g + 2] * inv, o0[4 * g + 3] * inv); *(u32x2*)(op + 8 * g) = w;
;         u32x2 w2; w2.x = cvtpk(o1[4 * g] * inv, o1[4 * g + 1] * inv); w2.y = cvtpk(o1[4 * g + 2] * inv, o1[4 * g + 3] * inv); *(u32x2*)(op + 32 + 8 * g) = w2;
;     }
	v_add_f32_e32 v33, v46, v47
	v_add_f32_e32 v32, v32, v33
	v_div_scale_f32 v33, s[0:1], v32, v32, 1.0
	v_rcp_f32_e32 v38, v33
	v_cvt_pk_bf16_f32 v36, v43, v40
	s_nop 1
	v_mfma_f32_32x32x16_bf16 v[0:15], v[94:97], v[34:37], v[0:15]
	v_mfma_f32_32x32x16_bf16 v[16:31], v[90:93], v[34:37], v[16:31]
	v_fma_f32 v34, -v33, v38, 1.0
	v_fmac_f32_e32 v38, v34, v38
	v_div_scale_f32 v34, vcc, 1.0, v32, 1.0
	v_mul_f32_e32 v35, v34, v38
	v_fma_f32 v36, -v33, v35, v34
	v_fmac_f32_e32 v35, v36, v38
	v_fma_f32 v33, -v33, v35, v34
	v_div_fmas_f32 v33, v33, v38, v35
	v_div_fixup_f32 v32, v33, v32, 1.0
	v_lshl_add_u64 v[34:35], s[86:87], 0, v[178:179]
	v_lshl_add_u64 v[34:35], v[180:181], 1, v[34:35]
	v_pk_mul_f32 v[0:1], v[0:1], v[32:33] op_sel_hi:[1,0]
	v_pk_mul_f32 v[2:3], v[2:3], v[32:33] op_sel_hi:[1,0]
	v_lshl_add_u64 v[34:35], v[34:35], 0, v[80:81]
	v_cvt_pk_bf16_f32 v0, v0, v1
	v_cvt_pk_bf16_f32 v1, v2, v3
	global_store_dwordx2 v[34:35], v[0:1], off
	v_pk_mul_f32 v[0:1], v[16:17], v[32:33] op_sel_hi:[1,0]
	v_pk_mul_f32 v[2:3], v[18:19], v[32:33] op_sel_hi:[1,0]
	v_cvt_pk_bf16_f32 v0, v0, v1
	v_cvt_pk_bf16_f32 v1, v2, v3
	global_store_dwordx2 v[34:35], v[0:1], off offset:64
	v_pk_mul_f32 v[0:1], v[4:5], v[32:33] op_sel_hi:[1,0]
	v_pk_mul_f32 v[2:3], v[6:7], v[32:33] op_sel_hi:[1,0]
	v_cvt_pk_bf16_f32 v0, v0, v1
	v_cvt_pk_bf16_f32 v1, v2, v3
	global_store_dwordx2 v[34:35], v[0:1], off offset:16
	v_pk_mul_f32 v[0:1], v[20:21], v[32:33] op_sel_hi:[1,0]
	v_pk_mul_f32 v[2:3], v[22:23], v[32:33] op_sel_hi:[1,0]
	v_cvt_pk_bf16_f32 v0, v0, v1
	v_cvt_pk_bf16_f32 v1, v2, v3
	global_store_dwordx2 v[34:35], v[0:1], off offset:80
	v_pk_mul_f32 v[0:1], v[8:9], v[32:33] op_sel_hi:[1,0]
	v_pk_mul_f32 v[2:3], v[10:11], v[32:33] op_sel_hi:[1,0]
	v_cvt_pk_bf16_f32 v0, v0, v1
	v_cvt_pk_bf16_f32 v1, v2, v3
	global_store_dwordx2 v[34:35], v[0:1], off offset:32
	v_pk_mul_f32 v[0:1], v[24:25], v[32:33] op_sel_hi:[1,0]
	v_pk_mul_f32 v[2:3], v[26:27], v[32:33] op_sel_hi:[1,0]
	v_cvt_pk_bf16_f32 v0, v0, v1
	v_cvt_pk_bf16_f32 v1, v2, v3
	global_store_dwordx2 v[34:35], v[0:1], off offset:96
	v_pk_mul_f32 v[0:1], v[12:13], v[32:33] op_sel_hi:[1,0]
	v_pk_mul_f32 v[2:3], v[14:15], v[32:33] op_sel_hi:[1,0]
	v_cvt_pk_bf16_f32 v0, v0, v1
	v_cvt_pk_bf16_f32 v1, v2, v3
	global_store_dwordx2 v[34:35], v[0:1], off offset:48
	v_pk_mul_f32 v[0:1], v[28:29], v[32:33] op_sel_hi:[1,0]
	v_pk_mul_f32 v[2:3], v[30:31], v[32:33] op_sel_hi:[1,0]
	v_cvt_pk_bf16_f32 v0, v0, v1
	v_cvt_pk_bf16_f32 v1, v2, v3
	global_store_dwordx2 v[34:35], v[0:1], off offset:112

; __device__ __forceinline__ void attn_sample_item(const Params& P, LAS unsigned char* lds, int l, int db, int kvh, int tid_in) {
;     ...
;     for (int rr = 0; rr < 2; ++rr) {
;         const int row = wid * 2 + rr, g = row >> 2; const float sink = P.in[I_SINK][l * 8 + kvh * 4 + g];
;         float v0 = S[row * 132 + lane], v1 = S[row * 132 + 64 + lane], v2 = lane < 4 ? S[row * 132 + 128 + lane] : -1e30f;
;         float mx = fmaxf(fmaxf(v0, v1), fmaxf(v2, sink));
; #pragma unroll
;         for (int o = 1; o < 64; o <<= 1) mx = fmaxf(mx, __shfl_xor(mx, o));
;         const float p0 = v0 > -1e29f ? __expf(v0 - mx) : 0.f, p1 = v1 > -1e29f ? __expf(v1 - mx) : 0.f, p2 = v2 > -1e29f ? __expf(v2 - mx) : 0.f;
;         float sum = p0 + p1 + p2;
; #pragma unroll
;         for (int o = 1; o < 64; o <<= 1) sum += __shfl_xor(sum, o);
;         const float inv = 1.f / (sum + __expf(sink - mx));
;         S[row * 132 + lane] = p0 * inv; S[row * 132 + 64 + lane] = p1 * inv; if (lane < 4) S[row * 132 + 128 + lane] = p2 * inv;
;     }
.LBB0_1005:
	s_or_b64 exec, exec, s[2:3]
	s_lshl_b32 s0, s15, 2
	v_ashrrev_i32_e32 v1, 7, v8
	s_or_b32 s0, s0, s13
	v_add_u32_e32 v2, s0, v1
	v_ashrrev_i32_e32 v3, 31, v2
	v_lshl_add_u64 v[2:3], v[2:3], 2, s[54:55]
	s_waitcnt lgkmcnt(0)
	s_barrier
	v_ashrrev_i32_e32 v4, 5, v8
	v_and_b32_e32 v2, 0xffffffe, v4
	v_mul_lo_u32 v2, v2, s57
	s_add_i32 s2, 0, 0x11a10
	v_lshlrev_b32_e32 v5, 2, v0
	v_add3_u32 v7, s2, v2, v5
	ds_read2st64_b32 v[2:3], v7 offset1:1
	v_cmp_gt_u32_e64 s[38:39], 4, v0
	v_mov_b32_e32 v9, 0xf149f2ca
	s_and_saveexec_b64 s[0:1], s[38:39]
	ds_read_b32 v9, v7 offset:512
	s_or_b64 exec, exec, s[0:1]
	s_waitcnt vmcnt(0)
	v_max_f32_e32 v6, v200, v200
	s_waitcnt lgkmcnt(0)
	v_max_f32_e32 v10, v9, v9
	v_max_f32_e32 v10, v10, v6
	v_max3_f32 v10, v2, v3, v10
	s_nop 1
	v_mov_b32_dpp v11, v10 quad_perm:[1,0,3,2] row_mask:0xf bank_mask:0xf
	v_cmp_lt_f32_e32 vcc, s35, v2
	s_waitcnt lgkmcnt(0)
	v_max_f32_e32 v11, v11, v11
	v_max_f32_e32 v10, v10, v11
	s_nop 1
	v_mov_b32_dpp v11, v10 quad_perm:[2,3,0,1] row_mask:0xf bank_mask:0xf
	s_waitcnt lgkmcnt(0)
	v_max_f32_e32 v11, v11, v11
	v_max_f32_e32 v10, v10, v11
	s_nop 1
	v_mov_b32_dpp v11, v10 row_half_mirror row_mask:0xf bank_mask:0xf
	s_waitcnt lgkmcnt(0)
	v_max_f32_e32 v11, v11, v11
	v_max_f32_e32 v10, v10, v11
	s_nop 1
	v_mov_b32_dpp v11, v10 row_mirror row_mask:0xf bank_mask:0xf
	s_waitcnt lgkmcnt(0)
	v_max_f32_e32 v11, v11, v11
	v_max_f32_e32 v10, v10, v11
	v_mov_b32_e32 v11, v10
	s_nop 1
	v_permlane16_swap_b32 v10, v11
	s_waitcnt lgkmcnt(0)
	v_max_f32_e32 v11, v11, v11
	v_max_f32_e32 v10, v10, v11
	v_mov_b32_e32 v11, v10
	s_nop 1
	v_permlane32_swap_b32 v10, v11
	s_waitcnt lgkmcnt(0)
	v_max_f32_e32 v11, v11, v11
	v_max_f32_e32 v10, v10, v11
	v_sub_f32_e32 v11, v2, v10
	v_sub_f32_e32 v12, v3, v10
	v_mul_f32_e32 v11, 0x3fb8aa3b, v11
	v_sub_f32_e32 v13, v9, v10
	v_mul_f32_e32 v12, 0x3fb8aa3b, v12
	v_exp_f32_e32 v11, v11
	v_mul_f32_e32 v13, 0x3fb8aa3b, v13
	v_exp_f32_e32 v12, v12
	v_exp_f32_e32 v13, v13
	v_cndmask_b32_e32 v11, 0, v11, vcc
	v_cmp_lt_f32_e32 vcc, s35, v3
	v_sub_f32_e32 v10, v1, v10
	v_mul_f32_e32 v10, 0x3fb8aa3b, v10
	v_cndmask_b32_e32 v12, 0, v12, vcc
	v_cmp_lt_f32_e32 vcc, s35, v9
	v_add_f32_e32 v3, v11, v12
	v_exp_f32_e32 v10, v10
	v_cndmask_b32_e32 v2, 0, v13, vcc
	v_add_f32_e32 v3, v2, v3
	s_nop 1
	v_mov_b32_dpp v9, v3 quad_perm:[1,0,3,2] row_mask:0xf bank_mask:0xf
	s_waitcnt lgkmcnt(0)
	v_add_f32_e32 v3, v3, v9
	s_nop 1
	v_mov_b32_dpp v9, v3 quad_perm:[2,3,0,1] row_mask:0xf bank_mask:0xf
	s_waitcnt lgkmcnt(0)
	v_add_f32_e32 v3, v3, v9
	s_nop 1
	v_mov_b32_dpp v9, v3 row_half_mirror row_mask:0xf bank_mask:0xf
	s_waitcnt lgkmcnt(0)
	v_add_f32_e32 v3, v3, v9
	s_nop 1
	v_mov_b32_dpp v9, v3 row_mirror row_mask:0xf bank_mask:0xf
	s_waitcnt lgkmcnt(0)
	v_add_f32_e32 v3, v3, v9
	v_mov_b32_e32 v9, v3
	s_nop 1
	v_permlane16_swap_b32 v3, v9
	s_waitcnt lgkmcnt(0)
	v_add_f32_e32 v3, v3, v9
	v_mov_b32_e32 v9, v3
	s_nop 1
	v_permlane32_swap_b32 v3, v9
	s_waitcnt lgkmcnt(0)
	v_add_f32_e32 v3, v3, v9
	v_add_f32_e32 v3, v10, v3
	v_div_scale_f32 v9, s[0:1], v3, v3, 1.0
	v_rcp_f32_e32 v10, v9
	v_div_scale_f32 v13, vcc, 1.0, v3, 1.0
	v_fma_f32 v14, -v9, v10, 1.0
	v_fmac_f32_e32 v10, v14, v10
	v_mul_f32_e32 v14, v13, v10
	v_fma_f32 v15, -v9, v14, v13
	v_fmac_f32_e32 v14, v15, v10
	v_fma_f32 v9, -v9, v14, v13
	v_div_fmas_f32 v9, v9, v10, v14
	v_div_fixup_f32 v3, v9, v3, 1.0
	v_mul_f32_e32 v9, v11, v3
	v_mul_f32_e32 v10, v12, v3
	ds_write2st64_b32 v7, v9, v10 offset1:1
	s_and_saveexec_b64 s[0:1], s[38:39]
	v_mul_f32_e32 v2, v2, v3
	ds_write_b32 v7, v2 offset:512
	s_or_b64 exec, exec, s[0:1]
	v_or_b32_e32 v2, 1, v4
	v_mul_lo_u32 v2, v2, s57
	v_add3_u32 v4, s2, v2, v5
	ds_read2st64_b32 v[2:3], v4 offset1:1
	v_mov_b32_e32 v5, 0xf149f2ca
	s_and_saveexec_b64 s[0:1], s[38:39]
	ds_read_b32 v5, v4 offset:512
	s_or_b64 exec, exec, s[0:1]
	s_waitcnt lgkmcnt(0)
	v_max_f32_e32 v7, v5, v5
	v_max_f32_e32 v6, v7, v6
	v_max3_f32 v6, v2, v3, v6
	s_nop 1
	v_mov_b32_dpp v7, v6 quad_perm:[1,0,3,2] row_mask:0xf bank_mask:0xf
	v_cmp_lt_f32_e32 vcc, s35, v2
	s_waitcnt lgkmcnt(0)
	v_max_f32_e32 v7, v7, v7
	v_max_f32_e32 v6, v6, v7
	s_nop 1
	v_mov_b32_dpp v7, v6 quad_perm:[2,3,0,1] row_mask:0xf bank_mask:0xf
	s_waitcnt lgkmcnt(0)
	v_max_f32_e32 v7, v7, v7
	v_max_f32_e32 v6, v6, v7
	s_nop 1
	v_mov_b32_dpp v7, v6 row_half_mirror row_mask:0xf bank_mask:0xf
	s_waitcnt lgkmcnt(0)
	v_max_f32_e32 v7, v7, v7
	v_max_f32_e32 v6, v6, v7
	s_nop 1
	v_mov_b32_dpp v7, v6 row_mirror row_mask:0xf bank_mask:0xf
	s_waitcnt lgkmcnt(0)
	v_max_f32_e32 v7, v7, v7
	v_max_f32_e32 v6, v6, v7
	v_mov_b32_e32 v7, v6
	s_nop 1
	v_permlane16_swap_b32 v6, v7
	s_waitcnt lgkmcnt(0)
	v_max_f32_e32 v7, v7, v7
	v_max_f32_e32 v6, v6, v7
	v_mov_b32_e32 v7, v6
	s_nop 1
	v_permlane32_swap_b32 v6, v7
	s_waitcnt lgkmcnt(0)
	v_max_f32_e32 v7, v7, v7
	v_max_f32_e32 v6, v6, v7
	v_sub_f32_e32 v7, v2, v6
	v_sub_f32_e32 v9, v3, v6
	v_mul_f32_e32 v7, 0x3fb8aa3b, v7
	v_sub_f32_e32 v10, v5, v6
	v_mul_f32_e32 v9, 0x3fb8aa3b, v9
	v_exp_f32_e32 v7, v7
	v_mul_f32_e32 v10, 0x3fb8aa3b, v10
	v_exp_f32_e32 v9, v9
	v_exp_f32_e32 v10, v10
	v_cndmask_b32_e32 v7, 0, v7, vcc
	v_cmp_lt_f32_e32 vcc, s35, v3
	v_sub_f32_e32 v1, v1, v6
	v_mul_f32_e32 v1, 0x3fb8aa3b, v1
	v_cndmask_b32_e32 v3, 0, v9, vcc
	v_cmp_lt_f32_e32 vcc, s35, v5
	v_add_f32_e32 v5, v7, v3
	v_exp_f32_e32 v1, v1
	v_cndmask_b32_e32 v2, 0, v10, vcc
	v_add_f32_e32 v5, v2, v5
	s_nop 1
	v_mov_b32_dpp v9, v5 quad_perm:[1,0,3,2] row_mask:0xf bank_mask:0xf
	s_waitcnt lgkmcnt(0)
	v_add_f32_e32 v5, v5, v9
	s_nop 1
	v_mov_b32_dpp v9, v5 quad_perm:[2,3,0,1] row_mask:0xf bank_mask:0xf
	s_waitcnt lgkmcnt(0)
	v_add_f32_e32 v5, v5, v9
	s_nop 1
	v_mov_b32_dpp v9, v5 row_half_mirror row_mask:0xf bank_mask:0xf
	s_waitcnt lgkmcnt(0)
	v_add_f32_e32 v5, v5, v9
	s_nop 1
	v_mov_b32_dpp v9, v5 row_mirror row_mask:0xf bank_mask:0xf
	s_waitcnt lgkmcnt(0)
	v_add_f32_e32 v5, v5, v9
	v_mov_b32_e32 v9, v5
	s_nop 1
	v_permlane16_swap_b32 v5, v9
	s_waitcnt lgkmcnt(0)
	v_add_f32_e32 v5, v5, v9
	v_mov_b32_e32 v6, v5
	s_nop 1
	v_permlane32_swap_b32 v5, v6
	s_waitcnt lgkmcnt(0)
	v_add_f32_e32 v5, v5, v6
	v_add_f32_e32 v1, v1, v5
	v_div_scale_f32 v5, s[0:1], v1, v1, 1.0
	v_rcp_f32_e32 v6, v5
	v_div_scale_f32 v9, vcc, 1.0, v1, 1.0
	v_fma_f32 v10, -v5, v6, 1.0
	v_fmac_f32_e32 v6, v10, v6
	v_mul_f32_e32 v10, v9, v6
	v_fma_f32 v11, -v5, v10, v9
	v_fmac_f32_e32 v10, v11, v6
	v_fma_f32 v5, -v5, v10, v9
	v_div_fmas_f32 v5, v5, v6, v10
	v_div_fixup_f32 v1, v5, v1, 1.0
	v_mul_f32_e32 v5, v7, v1
	v_mul_f32_e32 v3, v3, v1
	ds_write2st64_b32 v4, v5, v3 offset1:1
	s_and_saveexec_b64 s[0:1], s[38:39]
	v_mul_f32_e32 v1, v2, v1
	ds_write_b32 v4, v1 offset:512
	s_or_b64 exec, exec, s[0:1]
	s_waitcnt lgkmcnt(0)
	s_barrier
	s_and_saveexec_b64 s[2:3], s[36:37]
	s_cbranch_execz .LBB0_1018
	s_lshl_b32 s0, s16, 2
	v_mov_b32_e32 v1, 0x8610
	s_addk_i32 s0, 0x4080
	s_lshl_b32 s1, s15, 8
	v_lshl_add_u32 v2, v0, 2, v1
	s_mov_b64 s[4:5], 0
	v_lshlrev_b32_e32 v0, 1, v0

; __device__ __forceinline__ float bflo(unsigned w) { return __uint_as_float(w << 16); }
; __device__ __forceinline__ float bfhi(unsigned w) { return __uint_as_float(w & 0xffff0000u); }
; __device__ __forceinline__ u32x4 pack8(f32x4 a, f32x4 b) { u32x4 w; w.x = cvtpk(a[0], a[1]); w.y = cvtpk(a[2], a[3]); w.z = cvtpk(b[0], b[1]); w.w = cvtpk(b[2], b[3]); return w; }
;     __device__ __forceinline__ void operator()(const pg8::f32x4 (&acc)[2][2][4][2], const pg8::Unit& u, int wr, int wc, int fr, int fq) const {
;     ...
;                 for (int bj = 0; bj < 2; ++bj) {
;                     const int col = col0 + bj * 128;
;                     const u32x4 zw = zx[m][bj];
;                     f32x4 x0 = {bflo(zw.x), bfhi(zw.x), bflo(zw.y), bfhi(zw.y)}, x1 = {bflo(zw.z), bfhi(zw.z), bflo(zw.w), bfhi(zw.w)};
;                     if (pst) { const f32x4 g0 = *(const f32x4*)(pg + col), g1 = *(const f32x4*)(pg + col + 4), b0 = *(const f32x4*)(pb + col), b1 = *(const f32x4*)(pb + col + 4);
;                         x0 = (x0 - mu) * rstd * g0 + b0; x1 = (x1 - mu) * rstd * g1 + b1; }
;                     x0 = x0 * ALPHA + acc[ai][bj][m][0]; x1 = x1 * ALPHA + acc[ai][bj][m][1];
;                     if (Z) { float* p = Z + (size_t)row * 1024 + col; *(f32x4*)p = x0; *(f32x4*)(p + 4) = x1; }
;                     *(u32x4*)(ZB + (size_t)row * 1024 + col) = pack8(x0, x1);
;                     s += ((x0[0] + x0[1]) + (x0[2] + x0[3])) + ((x1[0] + x1[1]) + (x1[2] + x1[3]));
;                     q += ((x0[0] * x0[0] + x0[1] * x0[1]) + (x0[2] * x0[2] + x0[3] * x0[3])) + ((x1[0] * x1[0] + x1[1] * x1[1]) + (x1[2] * x1[2] + x1[3] * x1[3]));
;                 }
;                 s += __shfl_xor(s, 16); q += __shfl_xor(q, 16); s += __shfl_xor(s, 32); q += __shfl_xor(q, 32);
;                 if (fq == 0) { typedef float f32x2v __attribute__((ext_vector_type(2))); *(f32x2v*)(ost + (size_t)row * 32 + (u.pn * 4 + wc) * 2) = (f32x2v){s, q}; }
.LBB0_1448:
	v_mov_b32_e32 v196, v200
	v_mov_b32_e32 v197, v136
	v_mov_b32_e32 v198, v201
	v_mov_b32_e32 v199, v136
	v_mul_f32_e32 v187, v200, v200
	v_mul_f32_e32 v189, v201, v201
	v_pk_add_f32 v[200:201], v[196:197], v[198:199]
	v_pk_mul_f32 v[196:197], v[196:197], v[198:199]
	v_add_f32_e32 v186, v134, v135
	v_mov_b32_e32 v201, v197
	v_pk_add_f32 v[196:197], v[136:137], v[136:137] op_sel:[1,0]
	v_pk_mul_f32 v[136:137], v[136:137], v[136:137]
	v_add_f32_e32 v188, v132, v133
	v_mov_b32_e32 v197, v137
	v_pk_add_f32 v[136:137], v[196:197], v[200:201]
	v_pk_add_f32 v[186:187], v[186:187], v[188:189]
	v_pk_mul_f32 v[132:133], v[132:133], v[132:133]
	v_pk_mul_f32 v[134:135], v[134:135], v[134:135]
	v_pk_add_f32 v[136:137], v[136:137], v[186:187]
	v_pk_mov_b32 v[186:187], v[134:135], v[132:133] op_sel:[1,0]
	v_mov_b32_e32 v135, v133
	v_pk_add_f32 v[132:133], v[186:187], v[134:135]
	v_pk_fma_f32 v[128:129], v[202:203], s[34:35], v[128:129] op_sel_hi:[1,0,1]
	v_pk_add_f32 v[132:133], v[132:133], v[132:133] op_sel_hi:[0,1]
	v_mov_b32_e32 v132, v81
	v_pk_fma_f32 v[126:127], v[194:195], s[34:35], v[126:127] op_sel_hi:[1,0,1]
	v_pk_add_f32 v[132:133], v[136:137], v[132:133]
	v_pk_fma_f32 v[134:135], v[156:157], s[34:35], v[124:125] op_sel_hi:[1,0,1]
	v_pk_fma_f32 v[136:137], v[154:155], s[34:35], v[122:123] op_sel_hi:[1,0,1]
	v_mul_f32_e32 v123, v126, v126
	v_mul_f32_e32 v125, v127, v127
	v_mul_f32_e32 v155, v128, v128
	v_mul_f32_e32 v157, v129, v129
	v_mov_b32_e32 v122, v126
	v_mov_b32_e32 v124, v127
	v_mov_b32_e32 v154, v128
	v_mov_b32_e32 v156, v129
	v_mul_f32_e32 v187, v136, v136
	v_mul_f32_e32 v189, v137, v137
	v_mul_f32_e32 v195, v134, v134
	v_mul_f32_e32 v197, v135, v135
	v_pk_add_f32 v[122:123], v[122:123], v[124:125]
	v_pk_add_f32 v[124:125], v[154:155], v[156:157]
	v_mov_b32_e32 v186, v136
	v_mov_b32_e32 v188, v137
	v_mov_b32_e32 v194, v134
	v_mov_b32_e32 v196, v135
	v_pk_add_f32 v[122:123], v[122:123], v[124:125]
	v_pk_add_f32 v[124:125], v[186:187], v[188:189]
	v_pk_add_f32 v[154:155], v[194:195], v[196:197]
	s_lshl_b32 s0, s4, 3
	v_pk_add_f32 v[124:125], v[124:125], v[154:155]
	s_or_b32 s4, s0, s72
	v_pk_add_f32 v[122:123], v[122:123], v[124:125]
	v_cmp_eq_u32_e64 s[42:43], 0, v213
	v_pk_add_f32 v[122:123], v[132:133], v[122:123]
	v_mov_b32_e32 v124, v122
	s_nop 1
	v_permlane16_swap_b32 v122, v124
	v_mov_b32_e32 v125, v123
	s_nop 1
	v_permlane16_swap_b32 v123, v125
	s_ashr_i32 s5, s4, 31
	v_cvt_pk_bf16_f32 v126, v126, v127
	v_cvt_pk_bf16_f32 v127, v128, v129
	v_cvt_pk_bf16_f32 v128, v136, v137
	s_waitcnt lgkmcnt(0)
	v_pk_add_f32 v[122:123], v[122:123], v[124:125]
	v_mov_b32_e32 v124, v122
	s_nop 1
	v_permlane32_swap_b32 v122, v124
	v_mov_b32_e32 v125, v123
	s_nop 1
	v_permlane32_swap_b32 v123, v125
	v_cvt_pk_bf16_f32 v129, v134, v135
	global_store_dwordx4 v[130:131], v[126:129], off offset:256
	s_and_saveexec_b64 s[0:1], s[42:43]
	s_cbranch_execz .LBB0_1450
	v_lshlrev_b64 v[126:127], 7, v[176:177]
	v_lshl_add_u64 v[126:127], s[44:45], 0, v[126:127]
	v_lshl_add_u64 v[126:127], s[4:5], 2, v[126:127]
	s_waitcnt lgkmcnt(0)
	v_pk_add_f32 v[122:123], v[122:123], v[124:125]
	global_store_dwordx2 v[126:127], v[122:123], off

; __device__ __forceinline__ float bflo(unsigned w) { return __uint_as_float(w << 16); }
; __device__ __forceinline__ float bfhi(unsigned w) { return __uint_as_float(w & 0xffff0000u); }
; __device__ __forceinline__ u32x4 pack8(f32x4 a, f32x4 b) { u32x4 w; w.x = cvtpk(a[0], a[1]); w.y = cvtpk(a[2], a[3]); w.z = cvtpk(b[0], b[1]); w.w = cvtpk(b[2], b[3]); return w; }
;     __device__ __forceinline__ void operator()(const pg8::f32x4 (&acc)[2][2][4][2], const pg8::Unit& u, int wr, int wc, int fr, int fq) const {
;     ...
;                 for (int bj = 0; bj < 2; ++bj) {
;                     const int col = col0 + bj * 128;
;                     const u32x4 zw = zx[m][bj];
;                     f32x4 x0 = {bflo(zw.x), bfhi(zw.x), bflo(zw.y), bfhi(zw.y)}, x1 = {bflo(zw.z), bfhi(zw.z), bflo(zw.w), bfhi(zw.w)};
;                     if (pst) { const f32x4 g0 = *(const f32x4*)(pg + col), g1 = *(const f32x4*)(pg + col + 4), b0 = *(const f32x4*)(pb + col), b1 = *(const f32x4*)(pb + col + 4);
;                         x0 = (x0 - mu) * rstd * g0 + b0; x1 = (x1 - mu) * rstd * g1 + b1; }
;                     x0 = x0 * ALPHA + acc[ai][bj][m][0]; x1 = x1 * ALPHA + acc[ai][bj][m][1];
;                     if (Z) { float* p = Z + (size_t)row * 1024 + col; *(f32x4*)p = x0; *(f32x4*)(p + 4) = x1; }
;                     *(u32x4*)(ZB + (size_t)row * 1024 + col) = pack8(x0, x1);
;                     s += ((x0[0] + x0[1]) + (x0[2] + x0[3])) + ((x1[0] + x1[1]) + (x1[2] + x1[3]));
;                     q += ((x0[0] * x0[0] + x0[1] * x0[1]) + (x0[2] * x0[2] + x0[3] * x0[3])) + ((x1[0] * x1[0] + x1[1] * x1[1]) + (x1[2] * x1[2] + x1[3] * x1[3]));
;                 }
;                 s += __shfl_xor(s, 16); q += __shfl_xor(q, 16); s += __shfl_xor(s, 32); q += __shfl_xor(q, 32);
;                 if (fq == 0) { typedef float f32x2v __attribute__((ext_vector_type(2))); *(f32x2v*)(ost + (size_t)row * 32 + (u.pn * 4 + wc) * 2) = (f32x2v){s, q}; }
.LBB0_1457:
	v_mul_f32_e32 v123, v126, v126
	s_waitcnt lgkmcnt(0)
	v_mul_f32_e32 v125, v127, v127
	v_mov_b32_e32 v136, v126
	v_mov_b32_e32 v137, v112
	v_mov_b32_e32 v126, v127
	v_mov_b32_e32 v127, v112
	v_pk_add_f32 v[146:147], v[136:137], v[126:127]
	v_pk_mul_f32 v[126:127], v[136:137], v[126:127]
	v_add_f32_e32 v122, v110, v111
	v_mov_b32_e32 v147, v127
	v_pk_add_f32 v[126:127], v[112:113], v[112:113] op_sel:[1,0]
	v_pk_mul_f32 v[112:113], v[112:113], v[112:113]
	v_add_f32_e32 v124, v108, v109
	v_mov_b32_e32 v127, v113
	v_pk_add_f32 v[112:113], v[126:127], v[146:147]
	v_pk_add_f32 v[122:123], v[122:123], v[124:125]
	v_pk_mul_f32 v[108:109], v[108:109], v[108:109]
	v_pk_mul_f32 v[110:111], v[110:111], v[110:111]
	v_pk_add_f32 v[112:113], v[112:113], v[122:123]
	v_pk_mov_b32 v[122:123], v[110:111], v[108:109] op_sel:[1,0]
	v_mov_b32_e32 v111, v109
	v_pk_add_f32 v[108:109], v[122:123], v[110:111]
	v_pk_fma_f32 v[104:105], v[134:135], s[34:35], v[104:105] op_sel_hi:[1,0,1]
	v_pk_add_f32 v[108:109], v[108:109], v[108:109] op_sel_hi:[0,1]
	v_mov_b32_e32 v108, v81
	v_pk_fma_f32 v[102:103], v[132:133], s[34:35], v[102:103] op_sel_hi:[1,0,1]
	v_pk_add_f32 v[108:109], v[112:113], v[108:109]
	v_pk_fma_f32 v[110:111], v[130:131], s[34:35], v[100:101] op_sel_hi:[1,0,1]
	v_pk_fma_f32 v[112:113], v[128:129], s[34:35], v[98:99] op_sel_hi:[1,0,1]
	v_mul_f32_e32 v99, v102, v102
	v_mul_f32_e32 v101, v103, v103
	v_mul_f32_e32 v123, v104, v104
	v_mul_f32_e32 v125, v105, v105
	v_mov_b32_e32 v98, v102
	v_mov_b32_e32 v100, v103
	v_mov_b32_e32 v122, v104
	v_mov_b32_e32 v124, v105
	v_mul_f32_e32 v127, v112, v112
	v_mul_f32_e32 v129, v113, v113
	v_mul_f32_e32 v131, v110, v110
	v_mul_f32_e32 v133, v111, v111
	v_pk_add_f32 v[98:99], v[98:99], v[100:101]
	v_pk_add_f32 v[100:101], v[122:123], v[124:125]
	v_mov_b32_e32 v126, v112
	v_mov_b32_e32 v128, v113
	v_mov_b32_e32 v130, v110
	v_mov_b32_e32 v132, v111
	v_pk_add_f32 v[98:99], v[98:99], v[100:101]
	v_pk_add_f32 v[100:101], v[126:127], v[128:129]
	v_pk_add_f32 v[122:123], v[130:131], v[132:133]
	v_cvt_pk_bf16_f32 v102, v102, v103
	v_pk_add_f32 v[100:101], v[100:101], v[122:123]
	v_cvt_pk_bf16_f32 v103, v104, v105
	v_pk_add_f32 v[98:99], v[98:99], v[100:101]
	v_cvt_pk_bf16_f32 v104, v112, v113
	v_pk_add_f32 v[98:99], v[108:109], v[98:99]
	v_mov_b32_e32 v100, v98
	s_nop 1
	v_permlane16_swap_b32 v98, v100
	v_mov_b32_e32 v101, v99
	s_nop 1
	v_permlane16_swap_b32 v99, v101
	v_cvt_pk_bf16_f32 v105, v110, v111
	global_store_dwordx4 v[106:107], v[102:105], off offset:256
	s_waitcnt lgkmcnt(0)
	v_pk_add_f32 v[98:99], v[98:99], v[100:101]
	v_mov_b32_e32 v100, v98
	s_nop 1
	v_permlane32_swap_b32 v98, v100
	v_mov_b32_e32 v101, v99
	s_nop 1
	v_permlane32_swap_b32 v99, v101
	s_and_saveexec_b64 s[0:1], s[42:43]
	s_cbranch_execz .LBB0_1459
	v_lshlrev_b64 v[102:103], 7, v[190:191]
	v_lshl_add_u64 v[102:103], s[44:45], 0, v[102:103]
	v_lshl_add_u64 v[102:103], s[4:5], 2, v[102:103]
	s_waitcnt lgkmcnt(0)
	v_pk_add_f32 v[98:99], v[98:99], v[100:101]
	global_store_dwordx2 v[102:103], v[98:99], off

; __device__ __forceinline__ float bflo(unsigned w) { return __uint_as_float(w << 16); }
; __device__ __forceinline__ float bfhi(unsigned w) { return __uint_as_float(w & 0xffff0000u); }
; __device__ __forceinline__ u32x4 pack8(f32x4 a, f32x4 b) { u32x4 w; w.x = cvtpk(a[0], a[1]); w.y = cvtpk(a[2], a[3]); w.z = cvtpk(b[0], b[1]); w.w = cvtpk(b[2], b[3]); return w; }
;     __device__ __forceinline__ void operator()(const pg8::f32x4 (&acc)[2][2][4][2], const pg8::Unit& u, int wr, int wc, int fr, int fq) const {
;     ...
;                 for (int bj = 0; bj < 2; ++bj) {
;                     const int col = col0 + bj * 128;
;                     const u32x4 zw = zx[m][bj];
;                     f32x4 x0 = {bflo(zw.x), bfhi(zw.x), bflo(zw.y), bfhi(zw.y)}, x1 = {bflo(zw.z), bfhi(zw.z), bflo(zw.w), bfhi(zw.w)};
;                     if (pst) { const f32x4 g0 = *(const f32x4*)(pg + col), g1 = *(const f32x4*)(pg + col + 4), b0 = *(const f32x4*)(pb + col), b1 = *(const f32x4*)(pb + col + 4);
;                         x0 = (x0 - mu) * rstd * g0 + b0; x1 = (x1 - mu) * rstd * g1 + b1; }
;                     x0 = x0 * ALPHA + acc[ai][bj][m][0]; x1 = x1 * ALPHA + acc[ai][bj][m][1];
;                     if (Z) { float* p = Z + (size_t)row * 1024 + col; *(f32x4*)p = x0; *(f32x4*)(p + 4) = x1; }
;                     *(u32x4*)(ZB + (size_t)row * 1024 + col) = pack8(x0, x1);
;                     s += ((x0[0] + x0[1]) + (x0[2] + x0[3])) + ((x1[0] + x1[1]) + (x1[2] + x1[3]));
;                     q += ((x0[0] * x0[0] + x0[1] * x0[1]) + (x0[2] * x0[2] + x0[3] * x0[3])) + ((x1[0] * x1[0] + x1[1] * x1[1]) + (x1[2] * x1[2] + x1[3] * x1[3]));
;                 }
;                 s += __shfl_xor(s, 16); q += __shfl_xor(q, 16); s += __shfl_xor(s, 32); q += __shfl_xor(q, 32);
;                 if (fq == 0) { typedef float f32x2v __attribute__((ext_vector_type(2))); *(f32x2v*)(ost + (size_t)row * 32 + (u.pn * 4 + wc) * 2) = (f32x2v){s, q}; }
.LBB0_1466:
	v_mul_f32_e32 v99, v102, v102
	s_waitcnt lgkmcnt(0)
	v_mul_f32_e32 v101, v103, v103
	v_mov_b32_e32 v112, v102
	v_mov_b32_e32 v113, v96
	v_mov_b32_e32 v102, v103
	v_mov_b32_e32 v103, v96
	v_pk_add_f32 v[122:123], v[112:113], v[102:103]
	v_pk_mul_f32 v[102:103], v[112:113], v[102:103]
	v_add_f32_e32 v98, v94, v95
	v_mov_b32_e32 v123, v103
	v_pk_add_f32 v[102:103], v[96:97], v[96:97] op_sel:[1,0]
	v_pk_mul_f32 v[96:97], v[96:97], v[96:97]
	v_add_f32_e32 v100, v92, v93
	v_mov_b32_e32 v103, v97
	v_pk_add_f32 v[96:97], v[102:103], v[122:123]
	v_pk_add_f32 v[98:99], v[98:99], v[100:101]
	v_pk_mul_f32 v[92:93], v[92:93], v[92:93]
	v_pk_mul_f32 v[94:95], v[94:95], v[94:95]
	v_pk_add_f32 v[96:97], v[96:97], v[98:99]
	v_pk_mov_b32 v[98:99], v[94:95], v[92:93] op_sel:[1,0]
	v_mov_b32_e32 v95, v93
	v_pk_add_f32 v[92:93], v[98:99], v[94:95]
	v_pk_fma_f32 v[88:89], v[110:111], s[34:35], v[88:89] op_sel_hi:[1,0,1]
	v_pk_add_f32 v[92:93], v[92:93], v[92:93] op_sel_hi:[0,1]
	v_mov_b32_e32 v92, v81
	v_pk_fma_f32 v[86:87], v[108:109], s[34:35], v[86:87] op_sel_hi:[1,0,1]
	v_pk_add_f32 v[92:93], v[96:97], v[92:93]
	v_pk_fma_f32 v[94:95], v[106:107], s[34:35], v[84:85] op_sel_hi:[1,0,1]
	v_pk_fma_f32 v[96:97], v[104:105], s[34:35], v[82:83] op_sel_hi:[1,0,1]
	v_mul_f32_e32 v83, v86, v86
	v_mul_f32_e32 v85, v87, v87
	v_mul_f32_e32 v99, v88, v88
	v_mul_f32_e32 v101, v89, v89
	v_mov_b32_e32 v82, v86
	v_mov_b32_e32 v84, v87
	v_mov_b32_e32 v98, v88
	v_mov_b32_e32 v100, v89
	v_mul_f32_e32 v103, v96, v96
	v_mul_f32_e32 v105, v97, v97
	v_mul_f32_e32 v107, v94, v94
	v_mul_f32_e32 v109, v95, v95
	v_pk_add_f32 v[82:83], v[82:83], v[84:85]
	v_pk_add_f32 v[84:85], v[98:99], v[100:101]
	v_mov_b32_e32 v102, v96
	v_mov_b32_e32 v104, v97
	v_mov_b32_e32 v106, v94
	v_mov_b32_e32 v108, v95
	v_pk_add_f32 v[82:83], v[82:83], v[84:85]
	v_pk_add_f32 v[84:85], v[102:103], v[104:105]
	v_pk_add_f32 v[98:99], v[106:107], v[108:109]
	v_cvt_pk_bf16_f32 v86, v86, v87
	v_pk_add_f32 v[84:85], v[84:85], v[98:99]
	v_cvt_pk_bf16_f32 v87, v88, v89
	v_pk_add_f32 v[82:83], v[82:83], v[84:85]
	v_cvt_pk_bf16_f32 v88, v96, v97
	v_pk_add_f32 v[82:83], v[92:93], v[82:83]
	v_mov_b32_e32 v84, v82
	s_nop 1
	v_permlane16_swap_b32 v82, v84
	v_mov_b32_e32 v85, v83
	s_nop 1
	v_permlane16_swap_b32 v83, v85
	v_cvt_pk_bf16_f32 v89, v94, v95
	global_store_dwordx4 v[90:91], v[86:89], off offset:256
	s_waitcnt lgkmcnt(0)
	v_pk_add_f32 v[82:83], v[82:83], v[84:85]
	v_mov_b32_e32 v84, v82
	s_nop 1
	v_permlane32_swap_b32 v82, v84
	v_mov_b32_e32 v85, v83
	s_nop 1
	v_permlane32_swap_b32 v83, v85
	s_and_saveexec_b64 s[0:1], s[42:43]
	s_cbranch_execz .LBB0_1468
	v_lshlrev_b64 v[86:87], 7, v[182:183]
	v_lshl_add_u64 v[86:87], s[44:45], 0, v[86:87]
	v_lshl_add_u64 v[86:87], s[4:5], 2, v[86:87]
	s_waitcnt lgkmcnt(0)
	v_pk_add_f32 v[82:83], v[82:83], v[84:85]
	global_store_dwordx2 v[86:87], v[82:83], off

; __device__ __forceinline__ float bflo(unsigned w) { return __uint_as_float(w << 16); }
; __device__ __forceinline__ float bfhi(unsigned w) { return __uint_as_float(w & 0xffff0000u); }
; __device__ __forceinline__ u32x4 pack8(f32x4 a, f32x4 b) { u32x4 w; w.x = cvtpk(a[0], a[1]); w.y = cvtpk(a[2], a[3]); w.z = cvtpk(b[0], b[1]); w.w = cvtpk(b[2], b[3]); return w; }
;     __device__ __forceinline__ void operator()(const pg8::f32x4 (&acc)[2][2][4][2], const pg8::Unit& u, int wr, int wc, int fr, int fq) const {
;     ...
;                 for (int bj = 0; bj < 2; ++bj) {
;                     const int col = col0 + bj * 128;
;                     const u32x4 zw = zx[m][bj];
;                     f32x4 x0 = {bflo(zw.x), bfhi(zw.x), bflo(zw.y), bfhi(zw.y)}, x1 = {bflo(zw.z), bfhi(zw.z), bflo(zw.w), bfhi(zw.w)};
;                     if (pst) { const f32x4 g0 = *(const f32x4*)(pg + col), g1 = *(const f32x4*)(pg + col + 4), b0 = *(const f32x4*)(pb + col), b1 = *(const f32x4*)(pb + col + 4);
;                         x0 = (x0 - mu) * rstd * g0 + b0; x1 = (x1 - mu) * rstd * g1 + b1; }
;                     x0 = x0 * ALPHA + acc[ai][bj][m][0]; x1 = x1 * ALPHA + acc[ai][bj][m][1];
;                     if (Z) { float* p = Z + (size_t)row * 1024 + col; *(f32x4*)p = x0; *(f32x4*)(p + 4) = x1; }
;                     *(u32x4*)(ZB + (size_t)row * 1024 + col) = pack8(x0, x1);
;                     s += ((x0[0] + x0[1]) + (x0[2] + x0[3])) + ((x1[0] + x1[1]) + (x1[2] + x1[3]));
;                     q += ((x0[0] * x0[0] + x0[1] * x0[1]) + (x0[2] * x0[2] + x0[3] * x0[3])) + ((x1[0] * x1[0] + x1[1] * x1[1]) + (x1[2] * x1[2] + x1[3] * x1[3]));
;                 }
;                 s += __shfl_xor(s, 16); q += __shfl_xor(q, 16); s += __shfl_xor(s, 32); q += __shfl_xor(q, 32);
;                 if (fq == 0) { typedef float f32x2v __attribute__((ext_vector_type(2))); *(f32x2v*)(ost + (size_t)row * 32 + (u.pn * 4 + wc) * 2) = (f32x2v){s, q}; }
.LBB0_1475:
	v_mul_f32_e32 v83, v86, v86
	s_waitcnt lgkmcnt(0)
	v_mul_f32_e32 v85, v87, v87
	v_mov_b32_e32 v96, v86
	v_mov_b32_e32 v97, v78
	v_mov_b32_e32 v86, v87
	v_mov_b32_e32 v87, v78
	v_pk_add_f32 v[98:99], v[96:97], v[86:87]
	v_pk_mul_f32 v[86:87], v[96:97], v[86:87]
	v_add_f32_e32 v82, v76, v77
	v_mov_b32_e32 v99, v87
	v_pk_add_f32 v[86:87], v[78:79], v[78:79] op_sel:[1,0]
	v_pk_mul_f32 v[78:79], v[78:79], v[78:79]
	v_add_f32_e32 v84, v74, v75
	v_mov_b32_e32 v87, v79
	v_pk_add_f32 v[78:79], v[86:87], v[98:99]
	v_pk_add_f32 v[82:83], v[82:83], v[84:85]
	v_pk_mul_f32 v[74:75], v[74:75], v[74:75]
	v_pk_mul_f32 v[76:77], v[76:77], v[76:77]
	v_pk_add_f32 v[78:79], v[78:79], v[82:83]
	v_pk_mov_b32 v[82:83], v[76:77], v[74:75] op_sel:[1,0]
	v_mov_b32_e32 v77, v75
	v_pk_add_f32 v[74:75], v[82:83], v[76:77]
	v_pk_fma_f32 v[70:71], v[94:95], s[34:35], v[70:71] op_sel_hi:[1,0,1]
	v_pk_add_f32 v[74:75], v[74:75], v[74:75] op_sel_hi:[0,1]
	v_mov_b32_e32 v74, v81
	v_pk_fma_f32 v[68:69], v[92:93], s[34:35], v[68:69] op_sel_hi:[1,0,1]
	v_pk_add_f32 v[74:75], v[78:79], v[74:75]
	v_pk_fma_f32 v[76:77], v[90:91], s[34:35], v[66:67] op_sel_hi:[1,0,1]
	v_pk_fma_f32 v[78:79], v[88:89], s[34:35], v[64:65] op_sel_hi:[1,0,1]
	v_mul_f32_e32 v65, v68, v68
	v_mul_f32_e32 v67, v69, v69
	v_mul_f32_e32 v83, v70, v70
	v_mul_f32_e32 v85, v71, v71
	v_mov_b32_e32 v64, v68
	v_mov_b32_e32 v66, v69
	v_mov_b32_e32 v82, v70
	v_mov_b32_e32 v84, v71
	v_mul_f32_e32 v87, v78, v78
	v_mul_f32_e32 v89, v79, v79
	v_mul_f32_e32 v91, v76, v76
	v_mul_f32_e32 v93, v77, v77
	v_pk_add_f32 v[64:65], v[64:65], v[66:67]
	v_pk_add_f32 v[66:67], v[82:83], v[84:85]
	v_mov_b32_e32 v86, v78
	v_mov_b32_e32 v88, v79
	v_mov_b32_e32 v90, v76
	v_mov_b32_e32 v92, v77
	v_pk_add_f32 v[64:65], v[64:65], v[66:67]
	v_pk_add_f32 v[66:67], v[86:87], v[88:89]
	v_pk_add_f32 v[82:83], v[90:91], v[92:93]
	v_cvt_pk_bf16_f32 v68, v68, v69
	v_pk_add_f32 v[66:67], v[66:67], v[82:83]
	v_cvt_pk_bf16_f32 v69, v70, v71
	v_pk_add_f32 v[64:65], v[64:65], v[66:67]
	v_cvt_pk_bf16_f32 v70, v78, v79
	v_pk_add_f32 v[64:65], v[74:75], v[64:65]
	v_mov_b32_e32 v66, v64
	s_nop 1
	v_permlane16_swap_b32 v64, v66
	v_mov_b32_e32 v67, v65
	s_nop 1
	v_permlane16_swap_b32 v65, v67
	v_cvt_pk_bf16_f32 v71, v76, v77
	global_store_dwordx4 v[72:73], v[68:71], off offset:256
	s_waitcnt lgkmcnt(0)
	v_pk_add_f32 v[64:65], v[64:65], v[66:67]
	v_mov_b32_e32 v66, v64
	s_nop 1
	v_permlane32_swap_b32 v64, v66
	v_mov_b32_e32 v67, v65
	s_nop 1
	v_permlane32_swap_b32 v65, v67
	s_and_saveexec_b64 s[0:1], s[42:43]
	s_cbranch_execz .LBB0_1477
	v_lshlrev_b64 v[68:69], 7, v[178:179]
	v_lshl_add_u64 v[68:69], s[44:45], 0, v[68:69]
	v_lshl_add_u64 v[68:69], s[4:5], 2, v[68:69]
	s_waitcnt lgkmcnt(0)
	v_pk_add_f32 v[64:65], v[64:65], v[66:67]
	global_store_dwordx2 v[68:69], v[64:65], off

; __device__ __forceinline__ float bflo(unsigned w) { return __uint_as_float(w << 16); }
; __device__ __forceinline__ float bfhi(unsigned w) { return __uint_as_float(w & 0xffff0000u); }
; __device__ __forceinline__ u32x4 pack8(f32x4 a, f32x4 b) { u32x4 w; w.x = cvtpk(a[0], a[1]); w.y = cvtpk(a[2], a[3]); w.z = cvtpk(b[0], b[1]); w.w = cvtpk(b[2], b[3]); return w; }
;     __device__ __forceinline__ void operator()(const pg8::f32x4 (&acc)[2][2][4][2], const pg8::Unit& u, int wr, int wc, int fr, int fq) const {
;     ...
;                 for (int bj = 0; bj < 2; ++bj) {
;                     const int col = col0 + bj * 128;
;                     const u32x4 zw = zx[m][bj];
;                     f32x4 x0 = {bflo(zw.x), bfhi(zw.x), bflo(zw.y), bfhi(zw.y)}, x1 = {bflo(zw.z), bfhi(zw.z), bflo(zw.w), bfhi(zw.w)};
;                     if (pst) { const f32x4 g0 = *(const f32x4*)(pg + col), g1 = *(const f32x4*)(pg + col + 4), b0 = *(const f32x4*)(pb + col), b1 = *(const f32x4*)(pb + col + 4);
;                         x0 = (x0 - mu) * rstd * g0 + b0; x1 = (x1 - mu) * rstd * g1 + b1; }
;                     x0 = x0 * ALPHA + acc[ai][bj][m][0]; x1 = x1 * ALPHA + acc[ai][bj][m][1];
;                     if (Z) { float* p = Z + (size_t)row * 1024 + col; *(f32x4*)p = x0; *(f32x4*)(p + 4) = x1; }
;                     *(u32x4*)(ZB + (size_t)row * 1024 + col) = pack8(x0, x1);
;                     s += ((x0[0] + x0[1]) + (x0[2] + x0[3])) + ((x1[0] + x1[1]) + (x1[2] + x1[3]));
;                     q += ((x0[0] * x0[0] + x0[1] * x0[1]) + (x0[2] * x0[2] + x0[3] * x0[3])) + ((x1[0] * x1[0] + x1[1] * x1[1]) + (x1[2] * x1[2] + x1[3] * x1[3]));
;                 }
;                 s += __shfl_xor(s, 16); q += __shfl_xor(q, 16); s += __shfl_xor(s, 32); q += __shfl_xor(q, 32);
;                 if (fq == 0) { typedef float f32x2v __attribute__((ext_vector_type(2))); *(f32x2v*)(ost + (size_t)row * 32 + (u.pn * 4 + wc) * 2) = (f32x2v){s, q}; }
.LBB0_1484:
	v_mul_f32_e32 v113, v94, v94
	v_mul_f32_e32 v115, v95, v95
	v_mov_b32_e32 v118, v94
	v_mov_b32_e32 v119, v62
	v_mov_b32_e32 v94, v95
	v_mov_b32_e32 v95, v62
	v_pk_add_f32 v[120:121], v[118:119], v[94:95]
	v_pk_mul_f32 v[94:95], v[118:119], v[94:95]
	v_add_f32_e32 v112, v60, v61
	v_mov_b32_e32 v121, v95
	v_pk_add_f32 v[94:95], v[62:63], v[62:63] op_sel:[1,0]
	v_pk_mul_f32 v[62:63], v[62:63], v[62:63]
	v_add_f32_e32 v114, v58, v59
	v_mov_b32_e32 v95, v63
	v_pk_add_f32 v[62:63], v[94:95], v[120:121]
	v_pk_add_f32 v[94:95], v[112:113], v[114:115]
	v_pk_mul_f32 v[58:59], v[58:59], v[58:59]
	v_pk_mul_f32 v[60:61], v[60:61], v[60:61]
	v_pk_add_f32 v[62:63], v[62:63], v[94:95]
	v_pk_mov_b32 v[94:95], v[60:61], v[58:59] op_sel:[1,0]
	v_mov_b32_e32 v61, v59
	v_pk_add_f32 v[58:59], v[94:95], v[60:61]
	v_pk_fma_f32 v[54:55], v[116:117], s[34:35], v[54:55] op_sel_hi:[1,0,1]
	v_pk_add_f32 v[58:59], v[58:59], v[58:59] op_sel_hi:[0,1]
	v_mov_b32_e32 v58, v81
	v_pk_fma_f32 v[52:53], v[96:97], s[34:35], v[52:53] op_sel_hi:[1,0,1]
	v_pk_add_f32 v[58:59], v[62:63], v[58:59]
	v_pk_fma_f32 v[60:61], v[92:93], s[34:35], v[50:51] op_sel_hi:[1,0,1]
	v_pk_fma_f32 v[62:63], v[90:91], s[34:35], v[48:49] op_sel_hi:[1,0,1]
	v_mul_f32_e32 v49, v52, v52
	v_mul_f32_e32 v51, v53, v53
	v_mul_f32_e32 v91, v54, v54
	v_mul_f32_e32 v93, v55, v55
	v_mov_b32_e32 v48, v52
	v_mov_b32_e32 v50, v53
	v_mov_b32_e32 v90, v54
	v_mov_b32_e32 v92, v55
	v_mul_f32_e32 v95, v62, v62
	v_mul_f32_e32 v97, v63, v63
	v_mul_f32_e32 v113, v60, v60
	v_mul_f32_e32 v115, v61, v61
	v_pk_add_f32 v[48:49], v[48:49], v[50:51]
	v_pk_add_f32 v[50:51], v[90:91], v[92:93]
	v_mov_b32_e32 v94, v62
	v_mov_b32_e32 v96, v63
	v_mov_b32_e32 v112, v60
	v_mov_b32_e32 v114, v61
	v_pk_add_f32 v[48:49], v[48:49], v[50:51]
	v_pk_add_f32 v[50:51], v[94:95], v[96:97]
	v_pk_add_f32 v[90:91], v[112:113], v[114:115]
	v_cvt_pk_bf16_f32 v52, v52, v53
	v_pk_add_f32 v[50:51], v[50:51], v[90:91]
	v_cvt_pk_bf16_f32 v53, v54, v55
	v_pk_add_f32 v[48:49], v[48:49], v[50:51]
	v_cvt_pk_bf16_f32 v54, v62, v63
	v_pk_add_f32 v[48:49], v[58:59], v[48:49]
	v_mov_b32_e32 v50, v48
	s_nop 1
	v_permlane16_swap_b32 v48, v50
	v_mov_b32_e32 v51, v49
	s_nop 1
	v_permlane16_swap_b32 v49, v51
	v_cvt_pk_bf16_f32 v55, v60, v61
	global_store_dwordx4 v[56:57], v[52:55], off offset:256
	s_waitcnt lgkmcnt(0)
	v_pk_add_f32 v[48:49], v[48:49], v[50:51]
	v_mov_b32_e32 v50, v48
	s_nop 1
	v_permlane32_swap_b32 v48, v50
	v_mov_b32_e32 v51, v49
	s_nop 1
	v_permlane32_swap_b32 v49, v51
	s_and_saveexec_b64 s[0:1], s[42:43]
	s_cbranch_execz .LBB0_1486
	v_lshlrev_b64 v[52:53], 7, v[110:111]
	v_lshl_add_u64 v[52:53], s[44:45], 0, v[52:53]
	v_lshl_add_u64 v[52:53], s[4:5], 2, v[52:53]
	s_waitcnt lgkmcnt(0)
	v_pk_add_f32 v[48:49], v[48:49], v[50:51]
	global_store_dwordx2 v[52:53], v[48:49], off

; __device__ __forceinline__ float bflo(unsigned w) { return __uint_as_float(w << 16); }
; __device__ __forceinline__ float bfhi(unsigned w) { return __uint_as_float(w & 0xffff0000u); }
; __device__ __forceinline__ u32x4 pack8(f32x4 a, f32x4 b) { u32x4 w; w.x = cvtpk(a[0], a[1]); w.y = cvtpk(a[2], a[3]); w.z = cvtpk(b[0], b[1]); w.w = cvtpk(b[2], b[3]); return w; }
;     __device__ __forceinline__ void operator()(const pg8::f32x4 (&acc)[2][2][4][2], const pg8::Unit& u, int wr, int wc, int fr, int fq) const {
;     ...
;                 for (int bj = 0; bj < 2; ++bj) {
;                     const int col = col0 + bj * 128;
;                     const u32x4 zw = zx[m][bj];
;                     f32x4 x0 = {bflo(zw.x), bfhi(zw.x), bflo(zw.y), bfhi(zw.y)}, x1 = {bflo(zw.z), bfhi(zw.z), bflo(zw.w), bfhi(zw.w)};
;                     if (pst) { const f32x4 g0 = *(const f32x4*)(pg + col), g1 = *(const f32x4*)(pg + col + 4), b0 = *(const f32x4*)(pb + col), b1 = *(const f32x4*)(pb + col + 4);
;                         x0 = (x0 - mu) * rstd * g0 + b0; x1 = (x1 - mu) * rstd * g1 + b1; }
;                     x0 = x0 * ALPHA + acc[ai][bj][m][0]; x1 = x1 * ALPHA + acc[ai][bj][m][1];
;                     if (Z) { float* p = Z + (size_t)row * 1024 + col; *(f32x4*)p = x0; *(f32x4*)(p + 4) = x1; }
;                     *(u32x4*)(ZB + (size_t)row * 1024 + col) = pack8(x0, x1);
;                     s += ((x0[0] + x0[1]) + (x0[2] + x0[3])) + ((x1[0] + x1[1]) + (x1[2] + x1[3]));
;                     q += ((x0[0] * x0[0] + x0[1] * x0[1]) + (x0[2] * x0[2] + x0[3] * x0[3])) + ((x1[0] * x1[0] + x1[1] * x1[1]) + (x1[2] * x1[2] + x1[3] * x1[3]));
;                 }
;                 s += __shfl_xor(s, 16); q += __shfl_xor(q, 16); s += __shfl_xor(s, 32); q += __shfl_xor(q, 32);
;                 if (fq == 0) { typedef float f32x2v __attribute__((ext_vector_type(2))); *(f32x2v*)(ost + (size_t)row * 32 + (u.pn * 4 + wc) * 2) = (f32x2v){s, q}; }
.LBB0_1493:
	v_mul_f32_e32 v49, v52, v52
	s_waitcnt lgkmcnt(0)
	v_mul_f32_e32 v51, v53, v53
	v_mov_b32_e32 v62, v52
	v_mov_b32_e32 v63, v46
	v_mov_b32_e32 v52, v53
	v_mov_b32_e32 v53, v46
	v_pk_add_f32 v[82:83], v[62:63], v[52:53]
	v_pk_mul_f32 v[52:53], v[62:63], v[52:53]
	v_add_f32_e32 v48, v44, v45
	v_mov_b32_e32 v83, v53
	v_pk_add_f32 v[52:53], v[46:47], v[46:47] op_sel:[1,0]
	v_pk_mul_f32 v[46:47], v[46:47], v[46:47]
	v_add_f32_e32 v50, v42, v43
	v_mov_b32_e32 v53, v47
	v_pk_add_f32 v[46:47], v[52:53], v[82:83]
	v_pk_add_f32 v[48:49], v[48:49], v[50:51]
	v_pk_mul_f32 v[42:43], v[42:43], v[42:43]
	v_pk_mul_f32 v[44:45], v[44:45], v[44:45]
	v_pk_add_f32 v[46:47], v[46:47], v[48:49]
	v_pk_mov_b32 v[48:49], v[44:45], v[42:43] op_sel:[1,0]
	v_mov_b32_e32 v45, v43
	v_pk_add_f32 v[42:43], v[48:49], v[44:45]
	v_pk_fma_f32 v[38:39], v[60:61], s[34:35], v[38:39] op_sel_hi:[1,0,1]
	v_pk_add_f32 v[42:43], v[42:43], v[42:43] op_sel_hi:[0,1]
	v_mov_b32_e32 v42, v81
	v_pk_fma_f32 v[36:37], v[58:59], s[34:35], v[36:37] op_sel_hi:[1,0,1]
	v_pk_add_f32 v[42:43], v[46:47], v[42:43]
	v_pk_fma_f32 v[44:45], v[56:57], s[34:35], v[34:35] op_sel_hi:[1,0,1]
	v_pk_fma_f32 v[46:47], v[54:55], s[34:35], v[32:33] op_sel_hi:[1,0,1]
	v_mul_f32_e32 v33, v36, v36
	v_mul_f32_e32 v35, v37, v37
	v_mul_f32_e32 v49, v38, v38
	v_mul_f32_e32 v51, v39, v39
	v_mov_b32_e32 v32, v36
	v_mov_b32_e32 v34, v37
	v_mov_b32_e32 v48, v38
	v_mov_b32_e32 v50, v39
	v_mul_f32_e32 v53, v46, v46
	v_mul_f32_e32 v55, v47, v47
	v_mul_f32_e32 v57, v44, v44
	v_mul_f32_e32 v59, v45, v45
	v_pk_add_f32 v[32:33], v[32:33], v[34:35]
	v_pk_add_f32 v[34:35], v[48:49], v[50:51]
	v_mov_b32_e32 v52, v46
	v_mov_b32_e32 v54, v47
	v_mov_b32_e32 v56, v44
	v_mov_b32_e32 v58, v45
	v_pk_add_f32 v[32:33], v[32:33], v[34:35]
	v_pk_add_f32 v[34:35], v[52:53], v[54:55]
	v_pk_add_f32 v[48:49], v[56:57], v[58:59]
	v_cvt_pk_bf16_f32 v36, v36, v37
	v_pk_add_f32 v[34:35], v[34:35], v[48:49]
	v_cvt_pk_bf16_f32 v37, v38, v39
	v_pk_add_f32 v[32:33], v[32:33], v[34:35]
	v_cvt_pk_bf16_f32 v38, v46, v47
	v_pk_add_f32 v[32:33], v[42:43], v[32:33]
	v_mov_b32_e32 v34, v32
	s_nop 1
	v_permlane16_swap_b32 v32, v34
	v_mov_b32_e32 v35, v33
	s_nop 1
	v_permlane16_swap_b32 v33, v35
	v_cvt_pk_bf16_f32 v39, v44, v45
	global_store_dwordx4 v[40:41], v[36:39], off offset:256
	s_waitcnt lgkmcnt(0)
	v_pk_add_f32 v[32:33], v[32:33], v[34:35]
	v_mov_b32_e32 v34, v32
	s_nop 1
	v_permlane32_swap_b32 v32, v34
	v_mov_b32_e32 v35, v33
	s_nop 1
	v_permlane32_swap_b32 v33, v35
	s_and_saveexec_b64 s[0:1], s[42:43]
	s_cbranch_execz .LBB0_1495
	v_lshlrev_b64 v[36:37], 7, v[106:107]
	v_lshl_add_u64 v[36:37], s[44:45], 0, v[36:37]
	v_lshl_add_u64 v[36:37], s[4:5], 2, v[36:37]
	s_waitcnt lgkmcnt(0)
	v_pk_add_f32 v[32:33], v[32:33], v[34:35]
	global_store_dwordx2 v[36:37], v[32:33], off

; __device__ __forceinline__ float bflo(unsigned w) { return __uint_as_float(w << 16); }
; __device__ __forceinline__ float bfhi(unsigned w) { return __uint_as_float(w & 0xffff0000u); }
; __device__ __forceinline__ u32x4 pack8(f32x4 a, f32x4 b) { u32x4 w; w.x = cvtpk(a[0], a[1]); w.y = cvtpk(a[2], a[3]); w.z = cvtpk(b[0], b[1]); w.w = cvtpk(b[2], b[3]); return w; }
;     __device__ __forceinline__ void operator()(const pg8::f32x4 (&acc)[2][2][4][2], const pg8::Unit& u, int wr, int wc, int fr, int fq) const {
;     ...
;                 for (int bj = 0; bj < 2; ++bj) {
;                     const int col = col0 + bj * 128;
;                     const u32x4 zw = zx[m][bj];
;                     f32x4 x0 = {bflo(zw.x), bfhi(zw.x), bflo(zw.y), bfhi(zw.y)}, x1 = {bflo(zw.z), bfhi(zw.z), bflo(zw.w), bfhi(zw.w)};
;                     if (pst) { const f32x4 g0 = *(const f32x4*)(pg + col), g1 = *(const f32x4*)(pg + col + 4), b0 = *(const f32x4*)(pb + col), b1 = *(const f32x4*)(pb + col + 4);
;                         x0 = (x0 - mu) * rstd * g0 + b0; x1 = (x1 - mu) * rstd * g1 + b1; }
;                     x0 = x0 * ALPHA + acc[ai][bj][m][0]; x1 = x1 * ALPHA + acc[ai][bj][m][1];
;                     if (Z) { float* p = Z + (size_t)row * 1024 + col; *(f32x4*)p = x0; *(f32x4*)(p + 4) = x1; }
;                     *(u32x4*)(ZB + (size_t)row * 1024 + col) = pack8(x0, x1);
;                     s += ((x0[0] + x0[1]) + (x0[2] + x0[3])) + ((x1[0] + x1[1]) + (x1[2] + x1[3]));
;                     q += ((x0[0] * x0[0] + x0[1] * x0[1]) + (x0[2] * x0[2] + x0[3] * x0[3])) + ((x1[0] * x1[0] + x1[1] * x1[1]) + (x1[2] * x1[2] + x1[3] * x1[3]));
;                 }
;                 s += __shfl_xor(s, 16); q += __shfl_xor(q, 16); s += __shfl_xor(s, 32); q += __shfl_xor(q, 32);
;                 if (fq == 0) { typedef float f32x2v __attribute__((ext_vector_type(2))); *(f32x2v*)(ost + (size_t)row * 32 + (u.pn * 4 + wc) * 2) = (f32x2v){s, q}; }
.LBB0_1502:
	v_mul_f32_e32 v33, v36, v36
	s_waitcnt lgkmcnt(0)
	v_mul_f32_e32 v35, v37, v37
	v_mov_b32_e32 v46, v36
	v_mov_b32_e32 v47, v30
	v_mov_b32_e32 v36, v37
	v_mov_b32_e32 v37, v30
	v_pk_add_f32 v[48:49], v[46:47], v[36:37]
	v_pk_mul_f32 v[36:37], v[46:47], v[36:37]
	v_add_f32_e32 v32, v28, v29
	v_mov_b32_e32 v49, v37
	v_pk_add_f32 v[36:37], v[30:31], v[30:31] op_sel:[1,0]
	v_pk_mul_f32 v[30:31], v[30:31], v[30:31]
	v_add_f32_e32 v34, v26, v27
	v_mov_b32_e32 v37, v31
	v_pk_add_f32 v[30:31], v[36:37], v[48:49]
	v_pk_add_f32 v[32:33], v[32:33], v[34:35]
	v_pk_mul_f32 v[26:27], v[26:27], v[26:27]
	v_pk_mul_f32 v[28:29], v[28:29], v[28:29]
	v_pk_add_f32 v[30:31], v[30:31], v[32:33]
	v_pk_mov_b32 v[32:33], v[28:29], v[26:27] op_sel:[1,0]
	v_mov_b32_e32 v29, v27
	v_pk_add_f32 v[26:27], v[32:33], v[28:29]
	v_pk_fma_f32 v[22:23], v[44:45], s[34:35], v[22:23] op_sel_hi:[1,0,1]
	v_pk_add_f32 v[26:27], v[26:27], v[26:27] op_sel_hi:[0,1]
	v_mov_b32_e32 v26, v81
	v_pk_fma_f32 v[20:21], v[42:43], s[34:35], v[20:21] op_sel_hi:[1,0,1]
	v_pk_add_f32 v[26:27], v[30:31], v[26:27]
	v_pk_fma_f32 v[28:29], v[40:41], s[34:35], v[18:19] op_sel_hi:[1,0,1]
	v_pk_fma_f32 v[30:31], v[38:39], s[34:35], v[16:17] op_sel_hi:[1,0,1]
	v_mul_f32_e32 v17, v20, v20
	v_mul_f32_e32 v19, v21, v21
	v_mul_f32_e32 v33, v22, v22
	v_mul_f32_e32 v35, v23, v23
	v_mov_b32_e32 v16, v20
	v_mov_b32_e32 v18, v21
	v_mov_b32_e32 v32, v22
	v_mov_b32_e32 v34, v23
	v_mul_f32_e32 v37, v30, v30
	v_mul_f32_e32 v39, v31, v31
	v_mul_f32_e32 v41, v28, v28
	v_mul_f32_e32 v43, v29, v29
	v_pk_add_f32 v[16:17], v[16:17], v[18:19]
	v_pk_add_f32 v[18:19], v[32:33], v[34:35]
	v_mov_b32_e32 v36, v30
	v_mov_b32_e32 v38, v31
	v_mov_b32_e32 v40, v28
	v_mov_b32_e32 v42, v29
	v_pk_add_f32 v[16:17], v[16:17], v[18:19]
	v_pk_add_f32 v[18:19], v[36:37], v[38:39]
	v_pk_add_f32 v[32:33], v[40:41], v[42:43]
	v_cvt_pk_bf16_f32 v20, v20, v21
	v_pk_add_f32 v[18:19], v[18:19], v[32:33]
	v_cvt_pk_bf16_f32 v21, v22, v23
	v_pk_add_f32 v[16:17], v[16:17], v[18:19]
	v_cvt_pk_bf16_f32 v22, v30, v31
	v_pk_add_f32 v[16:17], v[26:27], v[16:17]
	v_mov_b32_e32 v18, v16
	s_nop 1
	v_permlane16_swap_b32 v16, v18
	v_mov_b32_e32 v19, v17
	s_nop 1
	v_permlane16_swap_b32 v17, v19
	v_cvt_pk_bf16_f32 v23, v28, v29
	global_store_dwordx4 v[24:25], v[20:23], off offset:256
	s_waitcnt lgkmcnt(0)
	v_pk_add_f32 v[16:17], v[16:17], v[18:19]
	v_mov_b32_e32 v18, v16
	s_nop 1
	v_permlane32_swap_b32 v16, v18
	v_mov_b32_e32 v19, v17
	s_nop 1
	v_permlane32_swap_b32 v17, v19
	s_and_saveexec_b64 s[0:1], s[42:43]
	s_cbranch_execz .LBB0_1504
	v_lshlrev_b64 v[20:21], 7, v[102:103]
	v_lshl_add_u64 v[20:21], s[44:45], 0, v[20:21]
	v_lshl_add_u64 v[20:21], s[4:5], 2, v[20:21]
	s_waitcnt lgkmcnt(0)
	v_pk_add_f32 v[16:17], v[16:17], v[18:19]
	global_store_dwordx2 v[20:21], v[16:17], off

; __device__ __forceinline__ float bflo(unsigned w) { return __uint_as_float(w << 16); }
; __device__ __forceinline__ float bfhi(unsigned w) { return __uint_as_float(w & 0xffff0000u); }
; __device__ __forceinline__ u32x4 pack8(f32x4 a, f32x4 b) { u32x4 w; w.x = cvtpk(a[0], a[1]); w.y = cvtpk(a[2], a[3]); w.z = cvtpk(b[0], b[1]); w.w = cvtpk(b[2], b[3]); return w; }
;     __device__ __forceinline__ void operator()(const pg8::f32x4 (&acc)[2][2][4][2], const pg8::Unit& u, int wr, int wc, int fr, int fq) const {
;     ...
;                 for (int bj = 0; bj < 2; ++bj) {
;                     const int col = col0 + bj * 128;
;                     const u32x4 zw = zx[m][bj];
;                     f32x4 x0 = {bflo(zw.x), bfhi(zw.x), bflo(zw.y), bfhi(zw.y)}, x1 = {bflo(zw.z), bfhi(zw.z), bflo(zw.w), bfhi(zw.w)};
;                     if (pst) { const f32x4 g0 = *(const f32x4*)(pg + col), g1 = *(const f32x4*)(pg + col + 4), b0 = *(const f32x4*)(pb + col), b1 = *(const f32x4*)(pb + col + 4);
;                         x0 = (x0 - mu) * rstd * g0 + b0; x1 = (x1 - mu) * rstd * g1 + b1; }
;                     x0 = x0 * ALPHA + acc[ai][bj][m][0]; x1 = x1 * ALPHA + acc[ai][bj][m][1];
;                     if (Z) { float* p = Z + (size_t)row * 1024 + col; *(f32x4*)p = x0; *(f32x4*)(p + 4) = x1; }
;                     *(u32x4*)(ZB + (size_t)row * 1024 + col) = pack8(x0, x1);
;                     s += ((x0[0] + x0[1]) + (x0[2] + x0[3])) + ((x1[0] + x1[1]) + (x1[2] + x1[3]));
;                     q += ((x0[0] * x0[0] + x0[1] * x0[1]) + (x0[2] * x0[2] + x0[3] * x0[3])) + ((x1[0] * x1[0] + x1[1] * x1[1]) + (x1[2] * x1[2] + x1[3] * x1[3]));
;                 }
;                 s += __shfl_xor(s, 16); q += __shfl_xor(q, 16); s += __shfl_xor(s, 32); q += __shfl_xor(q, 32);
;                 if (fq == 0) { typedef float f32x2v __attribute__((ext_vector_type(2))); *(f32x2v*)(ost + (size_t)row * 32 + (u.pn * 4 + wc) * 2) = (f32x2v){s, q}; }
.LBB0_1511:
	v_mul_f32_e32 v17, v20, v20
	s_waitcnt lgkmcnt(0)
	v_mul_f32_e32 v19, v21, v21
	v_mov_b32_e32 v30, v20
	v_mov_b32_e32 v31, v14
	v_mov_b32_e32 v20, v21
	v_mov_b32_e32 v21, v14
	v_pk_add_f32 v[32:33], v[30:31], v[20:21]
	v_pk_mul_f32 v[20:21], v[30:31], v[20:21]
	v_add_f32_e32 v16, v12, v13
	v_mov_b32_e32 v33, v21
	v_pk_add_f32 v[20:21], v[14:15], v[14:15] op_sel:[1,0]
	v_pk_mul_f32 v[14:15], v[14:15], v[14:15]
	v_add_f32_e32 v18, v10, v11
	v_mov_b32_e32 v21, v15
	v_pk_add_f32 v[14:15], v[20:21], v[32:33]
	v_pk_add_f32 v[16:17], v[16:17], v[18:19]
	v_pk_mul_f32 v[10:11], v[10:11], v[10:11]
	v_pk_mul_f32 v[12:13], v[12:13], v[12:13]
	v_pk_add_f32 v[14:15], v[14:15], v[16:17]
	v_pk_mov_b32 v[16:17], v[12:13], v[10:11] op_sel:[1,0]
	v_mov_b32_e32 v13, v11
	v_pk_add_f32 v[10:11], v[16:17], v[12:13]
	v_pk_fma_f32 v[6:7], v[28:29], s[34:35], v[6:7] op_sel_hi:[1,0,1]
	v_pk_add_f32 v[10:11], v[10:11], v[10:11] op_sel_hi:[0,1]
	v_mov_b32_e32 v10, v81
	v_pk_fma_f32 v[4:5], v[26:27], s[34:35], v[4:5] op_sel_hi:[1,0,1]
	v_pk_add_f32 v[10:11], v[14:15], v[10:11]
	v_pk_fma_f32 v[12:13], v[24:25], s[34:35], v[2:3] op_sel_hi:[1,0,1]
	v_pk_fma_f32 v[14:15], v[22:23], s[34:35], v[0:1] op_sel_hi:[1,0,1]
	v_mul_f32_e32 v1, v4, v4
	v_mul_f32_e32 v3, v5, v5
	v_mul_f32_e32 v17, v6, v6
	v_mul_f32_e32 v19, v7, v7
	v_mov_b32_e32 v0, v4
	v_mov_b32_e32 v2, v5
	v_mov_b32_e32 v16, v6
	v_mov_b32_e32 v18, v7
	v_mul_f32_e32 v21, v14, v14
	v_mul_f32_e32 v23, v15, v15
	v_mul_f32_e32 v25, v12, v12
	v_mul_f32_e32 v27, v13, v13
	v_pk_add_f32 v[0:1], v[0:1], v[2:3]
	v_pk_add_f32 v[2:3], v[16:17], v[18:19]
	v_mov_b32_e32 v20, v14
	v_mov_b32_e32 v22, v15
	v_mov_b32_e32 v24, v12
	v_mov_b32_e32 v26, v13
	v_pk_add_f32 v[0:1], v[0:1], v[2:3]
	v_pk_add_f32 v[2:3], v[20:21], v[22:23]
	v_pk_add_f32 v[16:17], v[24:25], v[26:27]
	v_cvt_pk_bf16_f32 v4, v4, v5
	v_pk_add_f32 v[2:3], v[2:3], v[16:17]
	v_cvt_pk_bf16_f32 v5, v6, v7
	v_pk_add_f32 v[0:1], v[0:1], v[2:3]
	v_cvt_pk_bf16_f32 v6, v14, v15
	v_pk_add_f32 v[0:1], v[10:11], v[0:1]
	v_mov_b32_e32 v2, v0
	s_nop 1
	v_permlane16_swap_b32 v0, v2
	v_mov_b32_e32 v3, v1
	s_nop 1
	v_permlane16_swap_b32 v1, v3
	v_cvt_pk_bf16_f32 v7, v12, v13
	global_store_dwordx4 v[8:9], v[4:7], off offset:256
	s_waitcnt lgkmcnt(0)
	v_pk_add_f32 v[0:1], v[0:1], v[2:3]
	v_mov_b32_e32 v2, v0
	s_nop 1
	v_permlane32_swap_b32 v0, v2
	v_mov_b32_e32 v3, v1
	s_nop 1
	v_permlane32_swap_b32 v1, v3
	s_and_saveexec_b64 s[0:1], s[42:43]
	s_cbranch_execz .LBB0_1513
	v_lshlrev_b64 v[4:5], 7, v[98:99]
	v_lshl_add_u64 v[4:5], s[44:45], 0, v[4:5]
	v_lshl_add_u64 v[4:5], s[4:5], 2, v[4:5]
	s_waitcnt lgkmcnt(0)
	v_pk_add_f32 v[0:1], v[0:1], v[2:3]
	global_store_dwordx2 v[4:5], v[0:1], off

; #define LAS __attribute__((address_space(3)))
; template <int EPI> __device__ __forceinline__ void tail_gemm(LAS unsigned char* lds, const bf16* Am, const bf16* Bt, int K, const TailEpi& E, int tid_in) {
;     ...
;     const int rl = tid >> 3, c8 = (tid & 7) * 8, row = row0 + rl, col = col0 + c8;
;     f32x4 v0 = {0.f, 0.f, 0.f, 0.f}, v1 = v0;
; #pragma unroll
;     for (int ww = 0; ww < 8; ++ww) { const LAS float* p = (const LAS float*)lds + (size_t)ww * 64 * 65 + rl * 65 + c8;
;         v0[0] += p[0]; v0[1] += p[1]; v0[2] += p[2]; v0[3] += p[3]; v1[0] += p[4]; v1[1] += p[5]; v1[2] += p[6]; v1[3] += p[7]; }
;     const size_t off = (size_t)row * 1024 + col;
;     if (EPI == 0 || EPI == 1) {
;         const u32x4 s = *(const u32x4*)(E.S + off);
;         v0[0] *= bflo(s.x); v0[1] *= bfhi(s.x); v0[2] *= bflo(s.y); v0[3] *= bfhi(s.y); v1[0] *= bflo(s.z); v1[1] *= bfhi(s.z); v1[2] *= bflo(s.w); v1[3] *= bfhi(s.w);
;         if (EPI == 1) { const u32x4 a = *(const u32x4*)(E.A + off);
;             v0[0] += bflo(a.x); v0[1] += bfhi(a.x); v0[2] += bflo(a.y); v0[3] += bfhi(a.y); v1[0] += bflo(a.z); v1[1] += bfhi(a.z); v1[2] += bflo(a.w); v1[3] += bfhi(a.w); }
;         *(u32x4*)(E.S + off) = pack8(v0, v1);
;     } else {
;         const u32x4 zw = *(const u32x4*)(E.ZB + off);
;         f32x4 x0 = {bflo(zw.x), bfhi(zw.x), bflo(zw.y), bfhi(zw.y)}, x1 = {bflo(zw.z), bfhi(zw.z), bflo(zw.w), bfhi(zw.w)};
;         if (E.pst) {
;             const f32x4* sp = (const f32x4*)(E.pst + (size_t)row * 32); float s = 0.f, q = 0.f;
; #pragma unroll
;             for (int i = 0; i < 8; ++i) { const f32x4 t = sp[i]; s += t[0] + t[2]; q += t[1] + t[3]; }
;             const float mu = s * (1.f / D), rstd = __builtin_amdgcn_rsqf(fmaxf(q * (1.f / D) - mu * mu, 0.f) + LN_EPS);
;             const f32x4 g0 = *(const f32x4*)(E.pg + col), g1 = *(const f32x4*)(E.pg + col + 4), b0 = *(const f32x4*)(E.pb + col), b1 = *(const f32x4*)(E.pb + col + 4);
;             x0 = (x0 - mu) * rstd * g0 + b0; x1 = (x1 - mu) * rstd * g1 + b1;
;         }
;         x0 = x0 * ALPHA + v0; x1 = x1 * ALPHA + v1;
;         if (E.Z) { *(f32x4*)(E.Z + off) = x0; *(f32x4*)(E.Z + off + 4) = x1; }
;         *(u32x4*)(E.ZB + off) = pack8(x0, x1);
;         float s = ((x0[0] + x0[1]) + (x0[2] + x0[3])) + ((x1[0] + x1[1]) + (x1[2] + x1[3]));
.LBB0_1530:
	s_waitcnt lgkmcnt(14)
	v_pk_add_f32 v[50:51], v[50:51], 0 op_sel_hi:[1,0]
	v_pk_add_f32 v[54:55], v[54:55], 0 op_sel_hi:[1,0]
	v_pk_add_f32 v[12:13], v[50:51], v[12:13]
	v_pk_add_f32 v[18:19], v[54:55], v[18:19]
	v_pk_add_f32 v[8:9], v[12:13], v[8:9]
	v_pk_add_f32 v[12:13], v[20:21], 0 op_sel_hi:[1,0]
	v_pk_add_f32 v[14:15], v[14:15], 0 op_sel_hi:[1,0]
	v_pk_add_f32 v[18:19], v[18:19], v[34:35]
	v_pk_add_f32 v[6:7], v[14:15], v[6:7]
	v_pk_add_f32 v[12:13], v[12:13], v[28:29]
	v_pk_add_f32 v[8:9], v[8:9], v[10:11]
	v_pk_add_f32 v[10:11], v[18:19], v[26:27]
	v_pk_add_f32 v[12:13], v[12:13], v[30:31]
	v_pk_add_f32 v[4:5], v[6:7], v[4:5]
	v_pk_add_f32 v[10:11], v[10:11], v[58:59]
	v_pk_add_f32 v[8:9], v[8:9], v[56:57]
	v_pk_add_f32 v[4:5], v[4:5], v[16:17]
	v_pk_add_f32 v[6:7], v[12:13], v[22:23]
	s_waitcnt lgkmcnt(11)
	v_pk_add_f32 v[8:9], v[8:9], v[60:61]
	s_waitcnt lgkmcnt(10)
	v_pk_add_f32 v[10:11], v[10:11], v[62:63]
	v_pk_add_f32 v[6:7], v[6:7], v[32:33]
	v_pk_add_f32 v[4:5], v[4:5], v[24:25]
	s_waitcnt lgkmcnt(6)
	v_pk_add_f32 v[10:11], v[10:11], v[66:67]
	v_pk_add_f32 v[8:9], v[8:9], v[64:65]
	v_pk_add_f32 v[4:5], v[4:5], v[36:37]
	v_pk_add_f32 v[6:7], v[6:7], v[38:39]
	s_waitcnt lgkmcnt(3)
	v_pk_add_f32 v[8:9], v[8:9], v[68:69]
	s_waitcnt lgkmcnt(2)
	v_pk_add_f32 v[10:11], v[10:11], v[70:71]
	v_pk_add_f32 v[6:7], v[6:7], v[42:43]
	v_pk_add_f32 v[4:5], v[4:5], v[40:41]
	s_waitcnt lgkmcnt(0)
	v_pk_add_f32 v[6:7], v[6:7], v[46:47]
	v_pk_add_f32 v[4:5], v[4:5], v[44:45]
	v_pk_fma_f32 v[10:11], v[52:53], s[34:35], v[10:11] op_sel_hi:[1,0,1]
	v_pk_fma_f32 v[8:9], v[48:49], s[34:35], v[8:9] op_sel_hi:[1,0,1]
	v_pk_fma_f32 v[12:13], v[74:75], s[34:35], v[6:7] op_sel_hi:[1,0,1]
	v_pk_fma_f32 v[14:15], v[72:73], s[34:35], v[4:5] op_sel_hi:[1,0,1]
	v_mul_f32_e32 v5, v8, v8
	v_mul_f32_e32 v7, v9, v9
	v_mul_f32_e32 v17, v10, v10
	v_mul_f32_e32 v19, v11, v11
	v_mov_b32_e32 v4, v8
	v_mov_b32_e32 v6, v9
	v_mov_b32_e32 v16, v10
	v_mov_b32_e32 v18, v11
	v_mul_f32_e32 v21, v14, v14
	v_mul_f32_e32 v23, v15, v15
	v_mul_f32_e32 v25, v12, v12
	v_mul_f32_e32 v27, v13, v13
	v_pk_add_f32 v[4:5], v[4:5], v[6:7]
	v_pk_add_f32 v[6:7], v[16:17], v[18:19]
	v_mov_b32_e32 v20, v14
	v_mov_b32_e32 v22, v15
	v_mov_b32_e32 v24, v12
	v_mov_b32_e32 v26, v13
	v_pk_add_f32 v[4:5], v[4:5], v[6:7]
	v_pk_add_f32 v[6:7], v[20:21], v[22:23]
	v_pk_add_f32 v[16:17], v[24:25], v[26:27]
	v_cvt_pk_bf16_f32 v8, v8, v9
	v_pk_add_f32 v[6:7], v[6:7], v[16:17]
	v_cvt_pk_bf16_f32 v9, v10, v11
	v_pk_add_f32 v[4:5], v[4:5], v[6:7]
	s_nop 1
	v_mov_b32_dpp v6, v4 quad_perm:[1,0,3,2] row_mask:0xf bank_mask:0xf
	s_nop 1
	v_mov_b32_dpp v7, v5 quad_perm:[1,0,3,2] row_mask:0xf bank_mask:0xf
	v_cvt_pk_bf16_f32 v10, v14, v15
	v_cvt_pk_bf16_f32 v11, v12, v13
	global_store_dwordx4 v[0:1], v[8:11], off
	s_waitcnt lgkmcnt(0)
	v_pk_add_f32 v[4:5], v[4:5], v[6:7]
	s_nop 1
	v_mov_b32_dpp v6, v4 quad_perm:[2,3,0,1] row_mask:0xf bank_mask:0xf
	s_nop 1
	v_mov_b32_dpp v7, v5 quad_perm:[2,3,0,1] row_mask:0xf bank_mask:0xf
	s_waitcnt lgkmcnt(0)
	v_pk_add_f32 v[4:5], v[4:5], v[6:7]
	s_nop 1
	v_mov_b32_dpp v6, v4 row_half_mirror row_mask:0xf bank_mask:0xf
	s_nop 1
	v_mov_b32_dpp v7, v5 row_half_mirror row_mask:0xf bank_mask:0xf
	s_and_saveexec_b64 s[0:1], s[40:41]
	s_cbranch_execz .LBB0_1519
	v_lshl_add_u64 v[2:3], s[44:45], 0, v[2:3]
	s_mov_b32 s5, s93
	s_lshl_b32 s4, s13, 3
	s_waitcnt lgkmcnt(0)
	v_pk_add_f32 v[0:1], v[4:5], v[6:7]
	v_lshl_add_u64 v[2:3], v[2:3], 0, s[4:5]
	global_store_dwordx2 v[2:3], v[0:1], off
	s_branch .LBB0_1519

; __device__ __forceinline__ float bflo(unsigned w) { return __uint_as_float(w << 16); }
; __device__ __forceinline__ float bfhi(unsigned w) { return __uint_as_float(w & 0xffff0000u); }
; __device__ __forceinline__ u32x4 pack8(f32x4 a, f32x4 b) { u32x4 w; w.x = cvtpk(a[0], a[1]); w.y = cvtpk(a[2], a[3]); w.z = cvtpk(b[0], b[1]); w.w = cvtpk(b[2], b[3]); return w; }
;     __device__ __forceinline__ void operator()(const pg8::f32x4 (&acc)[2][2][4][2], const pg8::Unit& u, int wr, int wc, int fr, int fq) const {
;     ...
;             for (int m = 0; m < 4; ++m) {
;                 const int rloc = ai * 128 + wr * 64 + m * 16 + fr, row = u.pm * 256 + rloc;
;                 float mu = 0.f, rstd = 1.f; if (pst) ln_row_stats(pst, rloc, mu, rstd);
;                 float s = 0.f, q = 0.f;
; #pragma unroll
;                 for (int bj = 0; bj < 2; ++bj) {
;                     const int col = col0 + bj * 128;
;                     const u32x4 zw = zx[m][bj];
;                     f32x4 x0 = {bflo(zw.x), bfhi(zw.x), bflo(zw.y), bfhi(zw.y)}, x1 = {bflo(zw.z), bfhi(zw.z), bflo(zw.w), bfhi(zw.w)};
;                     if (pst) { const f32x4 g0 = *(const f32x4*)(pg + col), g1 = *(const f32x4*)(pg + col + 4), b0 = *(const f32x4*)(pb + col), b1 = *(const f32x4*)(pb + col + 4);
;                         x0 = (x0 - mu) * rstd * g0 + b0; x1 = (x1 - mu) * rstd * g1 + b1; }
;                     x0 = x0 * ALPHA + acc[ai][bj][m][0]; x1 = x1 * ALPHA + acc[ai][bj][m][1];
;                     if (Z) { float* p = Z + (size_t)row * 1024 + col; *(f32x4*)p = x0; *(f32x4*)(p + 4) = x1; }
;                     *(u32x4*)(ZB + (size_t)row * 1024 + col) = pack8(x0, x1);
;                     s += ((x0[0] + x0[1]) + (x0[2] + x0[3])) + ((x1[0] + x1[1]) + (x1[2] + x1[3]));
;                     q += ((x0[0] * x0[0] + x0[1] * x0[1]) + (x0[2] * x0[2] + x0[3] * x0[3])) + ((x1[0] * x1[0] + x1[1] * x1[1]) + (x1[2] * x1[2] + x1[3] * x1[3]));
;                 }
;                 s += __shfl_xor(s, 16); q += __shfl_xor(q, 16); s += __shfl_xor(s, 32); q += __shfl_xor(q, 32);
;                 if (fq == 0) { typedef float f32x2v __attribute__((ext_vector_type(2))); *(f32x2v*)(ost + (size_t)row * 32 + (u.pn * 4 + wc) * 2) = (f32x2v){s, q}; }
.LBB0_1702:
	v_mul_f32_e32 v155, v148, v148
	v_mul_f32_e32 v157, v149, v149
	v_mov_b32_e32 v186, v148
	v_mov_b32_e32 v187, v146
	v_mov_b32_e32 v148, v149
	v_mov_b32_e32 v149, v146
	v_pk_add_f32 v[188:189], v[186:187], v[148:149]
	v_pk_mul_f32 v[148:149], v[186:187], v[148:149]
	v_add_f32_e32 v154, v142, v143
	v_mov_b32_e32 v189, v149
	v_pk_add_f32 v[148:149], v[146:147], v[146:147] op_sel:[1,0]
	v_pk_mul_f32 v[146:147], v[146:147], v[146:147]
	v_add_f32_e32 v156, v144, v145
	v_mov_b32_e32 v149, v147
	v_pk_add_f32 v[146:147], v[148:149], v[188:189]
	v_pk_add_f32 v[148:149], v[154:155], v[156:157]
	v_pk_mul_f32 v[144:145], v[144:145], v[144:145]
	v_pk_mul_f32 v[142:143], v[142:143], v[142:143]
	v_pk_add_f32 v[146:147], v[146:147], v[148:149]
	v_pk_mov_b32 v[148:149], v[142:143], v[144:145] op_sel:[1,0]
	v_mov_b32_e32 v143, v145
	v_pk_add_f32 v[142:143], v[148:149], v[142:143]
	v_mul_f32_e32 v145, v134, v134
	v_pk_add_f32 v[142:143], v[142:143], v[142:143] op_sel_hi:[0,1]
	v_mov_b32_e32 v142, v81
	v_pk_add_f32 v[142:143], v[146:147], v[142:143]
	v_mul_f32_e32 v147, v135, v135
	v_mul_f32_e32 v149, v136, v136
	v_mul_f32_e32 v155, v137, v137
	v_mov_b32_e32 v144, v134
	v_mov_b32_e32 v146, v135
	v_mov_b32_e32 v148, v136
	v_mov_b32_e32 v154, v137
	v_mul_f32_e32 v157, v130, v130
	v_mul_f32_e32 v187, v131, v131
	v_mul_f32_e32 v189, v132, v132
	v_mul_f32_e32 v197, v133, v133
	v_pk_add_f32 v[144:145], v[144:145], v[146:147]
	v_pk_add_f32 v[146:147], v[148:149], v[154:155]
	v_mov_b32_e32 v156, v130
	v_mov_b32_e32 v186, v131
	v_mov_b32_e32 v188, v132
	v_mov_b32_e32 v196, v133
	v_pk_add_f32 v[144:145], v[144:145], v[146:147]
	v_pk_add_f32 v[146:147], v[156:157], v[186:187]
	v_pk_add_f32 v[148:149], v[188:189], v[196:197]
	s_lshl_b32 s0, s64, 3
	v_pk_add_f32 v[146:147], v[146:147], v[148:149]
	s_or_b32 s64, s0, s70
	v_pk_add_f32 v[144:145], v[144:145], v[146:147]
	v_cmp_eq_u32_e64 s[42:43], 0, v205
	v_pk_add_f32 v[142:143], v[142:143], v[144:145]
	v_mov_b32_e32 v146, v142
	s_nop 1
	v_permlane16_swap_b32 v142, v146
	v_mov_b32_e32 v147, v143
	s_nop 1
	v_permlane16_swap_b32 v143, v147
	v_cvt_pk_bf16_f32 v144, v134, v135
	s_ashr_i32 s65, s64, 31
	v_cvt_pk_bf16_f32 v145, v136, v137
	s_waitcnt lgkmcnt(0)
	v_pk_add_f32 v[134:135], v[142:143], v[146:147]
	v_mov_b32_e32 v142, v134
	s_nop 1
	v_permlane32_swap_b32 v134, v142
	v_mov_b32_e32 v143, v135
	s_nop 1
	v_permlane32_swap_b32 v135, v143
	v_cvt_pk_bf16_f32 v146, v130, v131
	v_cvt_pk_bf16_f32 v147, v132, v133
	global_store_dwordx4 v[194:195], v[144:147], off offset:256
	s_and_saveexec_b64 s[0:1], s[42:43]
	s_cbranch_execz .LBB0_1704
	v_lshlrev_b64 v[130:131], 7, v[176:177]
	v_lshl_add_u64 v[130:131], s[52:53], 0, v[130:131]
	v_lshl_add_u64 v[130:131], s[64:65], 2, v[130:131]
	s_waitcnt lgkmcnt(0)
	v_pk_add_f32 v[132:133], v[134:135], v[142:143]
	global_store_dwordx2 v[130:131], v[132:133], off

; __device__ __forceinline__ float bflo(unsigned w) { return __uint_as_float(w << 16); }
; __device__ __forceinline__ float bfhi(unsigned w) { return __uint_as_float(w & 0xffff0000u); }
; __device__ __forceinline__ u32x4 pack8(f32x4 a, f32x4 b) { u32x4 w; w.x = cvtpk(a[0], a[1]); w.y = cvtpk(a[2], a[3]); w.z = cvtpk(b[0], b[1]); w.w = cvtpk(b[2], b[3]); return w; }
;     __device__ __forceinline__ void operator()(const pg8::f32x4 (&acc)[2][2][4][2], const pg8::Unit& u, int wr, int wc, int fr, int fq) const {
;     ...
;             for (int m = 0; m < 4; ++m) {
;                 const int rloc = ai * 128 + wr * 64 + m * 16 + fr, row = u.pm * 256 + rloc;
;                 float mu = 0.f, rstd = 1.f; if (pst) ln_row_stats(pst, rloc, mu, rstd);
;                 float s = 0.f, q = 0.f;
; #pragma unroll
;                 for (int bj = 0; bj < 2; ++bj) {
;                     const int col = col0 + bj * 128;
;                     const u32x4 zw = zx[m][bj];
;                     f32x4 x0 = {bflo(zw.x), bfhi(zw.x), bflo(zw.y), bfhi(zw.y)}, x1 = {bflo(zw.z), bfhi(zw.z), bflo(zw.w), bfhi(zw.w)};
;                     if (pst) { const f32x4 g0 = *(const f32x4*)(pg + col), g1 = *(const f32x4*)(pg + col + 4), b0 = *(const f32x4*)(pb + col), b1 = *(const f32x4*)(pb + col + 4);
;                         x0 = (x0 - mu) * rstd * g0 + b0; x1 = (x1 - mu) * rstd * g1 + b1; }
;                     x0 = x0 * ALPHA + acc[ai][bj][m][0]; x1 = x1 * ALPHA + acc[ai][bj][m][1];
;                     if (Z) { float* p = Z + (size_t)row * 1024 + col; *(f32x4*)p = x0; *(f32x4*)(p + 4) = x1; }
;                     *(u32x4*)(ZB + (size_t)row * 1024 + col) = pack8(x0, x1);
;                     s += ((x0[0] + x0[1]) + (x0[2] + x0[3])) + ((x1[0] + x1[1]) + (x1[2] + x1[3]));
;                     q += ((x0[0] * x0[0] + x0[1] * x0[1]) + (x0[2] * x0[2] + x0[3] * x0[3])) + ((x1[0] * x1[0] + x1[1] * x1[1]) + (x1[2] * x1[2] + x1[3] * x1[3]));
;                 }
;                 s += __shfl_xor(s, 16); q += __shfl_xor(q, 16); s += __shfl_xor(s, 32); q += __shfl_xor(q, 32);
;                 if (fq == 0) { typedef float f32x2v __attribute__((ext_vector_type(2))); *(f32x2v*)(ost + (size_t)row * 32 + (u.pn * 4 + wc) * 2) = (f32x2v){s, q}; }
.LBB0_1708:
	v_mul_f32_e32 v131, v124, v124
	v_mul_f32_e32 v135, v125, v125
	v_mov_b32_e32 v136, v124
	v_mov_b32_e32 v137, v122
	v_mov_b32_e32 v124, v125
	v_mov_b32_e32 v125, v122
	v_pk_add_f32 v[138:139], v[136:137], v[124:125]
	v_pk_mul_f32 v[124:125], v[136:137], v[124:125]
	v_add_f32_e32 v130, v118, v119
	v_mov_b32_e32 v139, v125
	v_pk_add_f32 v[124:125], v[122:123], v[122:123] op_sel:[1,0]
	v_pk_mul_f32 v[122:123], v[122:123], v[122:123]
	v_add_f32_e32 v134, v120, v121
	v_mov_b32_e32 v125, v123
	v_pk_add_f32 v[122:123], v[124:125], v[138:139]
	v_pk_add_f32 v[124:125], v[130:131], v[134:135]
	v_pk_mul_f32 v[120:121], v[120:121], v[120:121]
	v_pk_mul_f32 v[118:119], v[118:119], v[118:119]
	v_pk_add_f32 v[122:123], v[122:123], v[124:125]
	v_pk_mov_b32 v[124:125], v[118:119], v[120:121] op_sel:[1,0]
	v_mov_b32_e32 v119, v121
	v_pk_add_f32 v[118:119], v[124:125], v[118:119]
	v_mul_f32_e32 v121, v110, v110
	v_pk_add_f32 v[118:119], v[118:119], v[118:119] op_sel_hi:[0,1]
	v_mov_b32_e32 v118, v81
	v_pk_add_f32 v[118:119], v[122:123], v[118:119]
	v_mul_f32_e32 v123, v111, v111
	v_mul_f32_e32 v125, v112, v112
	v_mul_f32_e32 v131, v113, v113
	v_mov_b32_e32 v120, v110
	v_mov_b32_e32 v122, v111
	v_mov_b32_e32 v124, v112
	v_mov_b32_e32 v130, v113
	v_mul_f32_e32 v135, v106, v106
	v_mul_f32_e32 v137, v107, v107
	v_mul_f32_e32 v139, v108, v108
	v_mul_f32_e32 v141, v109, v109
	v_pk_add_f32 v[120:121], v[120:121], v[122:123]
	v_pk_add_f32 v[122:123], v[124:125], v[130:131]
	v_mov_b32_e32 v134, v106
	v_mov_b32_e32 v136, v107
	v_mov_b32_e32 v138, v108
	v_mov_b32_e32 v140, v109
	v_pk_add_f32 v[120:121], v[120:121], v[122:123]
	v_pk_add_f32 v[122:123], v[134:135], v[136:137]
	v_pk_add_f32 v[124:125], v[138:139], v[140:141]
	s_nop 0
	v_pk_add_f32 v[122:123], v[122:123], v[124:125]
	s_nop 0
	v_pk_add_f32 v[120:121], v[120:121], v[122:123]
	s_nop 0
	v_pk_add_f32 v[118:119], v[118:119], v[120:121]
	v_mov_b32_e32 v122, v118
	s_nop 1
	v_permlane16_swap_b32 v118, v122
	v_mov_b32_e32 v123, v119
	s_nop 1
	v_permlane16_swap_b32 v119, v123
	v_cvt_pk_bf16_f32 v120, v110, v111
	v_cvt_pk_bf16_f32 v121, v112, v113
	s_waitcnt lgkmcnt(0)
	v_pk_add_f32 v[110:111], v[118:119], v[122:123]
	v_mov_b32_e32 v118, v110
	s_nop 1
	v_permlane32_swap_b32 v110, v118
	v_mov_b32_e32 v119, v111
	s_nop 1
	v_permlane32_swap_b32 v111, v119
	v_cvt_pk_bf16_f32 v122, v106, v107
	v_cvt_pk_bf16_f32 v123, v108, v109
	global_store_dwordx4 v[132:133], v[120:123], off offset:256
	s_and_saveexec_b64 s[0:1], s[42:43]
	s_cbranch_execz .LBB0_1710
	v_lshlrev_b64 v[106:107], 7, v[190:191]
	v_lshl_add_u64 v[106:107], s[52:53], 0, v[106:107]
	v_lshl_add_u64 v[106:107], s[64:65], 2, v[106:107]
	s_waitcnt lgkmcnt(0)
	v_pk_add_f32 v[108:109], v[110:111], v[118:119]
	global_store_dwordx2 v[106:107], v[108:109], off

; __device__ __forceinline__ float bflo(unsigned w) { return __uint_as_float(w << 16); }
; __device__ __forceinline__ float bfhi(unsigned w) { return __uint_as_float(w & 0xffff0000u); }
; __device__ __forceinline__ u32x4 pack8(f32x4 a, f32x4 b) { u32x4 w; w.x = cvtpk(a[0], a[1]); w.y = cvtpk(a[2], a[3]); w.z = cvtpk(b[0], b[1]); w.w = cvtpk(b[2], b[3]); return w; }
;     __device__ __forceinline__ void operator()(const pg8::f32x4 (&acc)[2][2][4][2], const pg8::Unit& u, int wr, int wc, int fr, int fq) const {
;     ...
;             for (int m = 0; m < 4; ++m) {
;                 const int rloc = ai * 128 + wr * 64 + m * 16 + fr, row = u.pm * 256 + rloc;
;                 float mu = 0.f, rstd = 1.f; if (pst) ln_row_stats(pst, rloc, mu, rstd);
;                 float s = 0.f, q = 0.f;
; #pragma unroll
;                 for (int bj = 0; bj < 2; ++bj) {
;                     const int col = col0 + bj * 128;
;                     const u32x4 zw = zx[m][bj];
;                     f32x4 x0 = {bflo(zw.x), bfhi(zw.x), bflo(zw.y), bfhi(zw.y)}, x1 = {bflo(zw.z), bfhi(zw.z), bflo(zw.w), bfhi(zw.w)};
;                     if (pst) { const f32x4 g0 = *(const f32x4*)(pg + col), g1 = *(const f32x4*)(pg + col + 4), b0 = *(const f32x4*)(pb + col), b1 = *(const f32x4*)(pb + col + 4);
;                         x0 = (x0 - mu) * rstd * g0 + b0; x1 = (x1 - mu) * rstd * g1 + b1; }
;                     x0 = x0 * ALPHA + acc[ai][bj][m][0]; x1 = x1 * ALPHA + acc[ai][bj][m][1];
;                     if (Z) { float* p = Z + (size_t)row * 1024 + col; *(f32x4*)p = x0; *(f32x4*)(p + 4) = x1; }
;                     *(u32x4*)(ZB + (size_t)row * 1024 + col) = pack8(x0, x1);
;                     s += ((x0[0] + x0[1]) + (x0[2] + x0[3])) + ((x1[0] + x1[1]) + (x1[2] + x1[3]));
;                     q += ((x0[0] * x0[0] + x0[1] * x0[1]) + (x0[2] * x0[2] + x0[3] * x0[3])) + ((x1[0] * x1[0] + x1[1] * x1[1]) + (x1[2] * x1[2] + x1[3] * x1[3]));
;                 }
;                 s += __shfl_xor(s, 16); q += __shfl_xor(q, 16); s += __shfl_xor(s, 32); q += __shfl_xor(q, 32);
;                 if (fq == 0) { typedef float f32x2v __attribute__((ext_vector_type(2))); *(f32x2v*)(ost + (size_t)row * 32 + (u.pn * 4 + wc) * 2) = (f32x2v){s, q}; }
.LBB0_1714:
	v_mul_f32_e32 v107, v100, v100
	v_mul_f32_e32 v111, v101, v101
	v_mov_b32_e32 v112, v100
	v_mov_b32_e32 v113, v98
	v_mov_b32_e32 v100, v101
	v_mov_b32_e32 v101, v98
	v_pk_add_f32 v[114:115], v[112:113], v[100:101]
	v_pk_mul_f32 v[100:101], v[112:113], v[100:101]
	v_add_f32_e32 v106, v94, v95
	v_mov_b32_e32 v115, v101
	v_pk_add_f32 v[100:101], v[98:99], v[98:99] op_sel:[1,0]
	v_pk_mul_f32 v[98:99], v[98:99], v[98:99]
	v_add_f32_e32 v110, v96, v97
	v_mov_b32_e32 v101, v99
	v_pk_add_f32 v[98:99], v[100:101], v[114:115]
	v_pk_add_f32 v[100:101], v[106:107], v[110:111]
	v_pk_mul_f32 v[96:97], v[96:97], v[96:97]
	v_pk_mul_f32 v[94:95], v[94:95], v[94:95]
	v_pk_add_f32 v[98:99], v[98:99], v[100:101]
	v_pk_mov_b32 v[100:101], v[94:95], v[96:97] op_sel:[1,0]
	v_mov_b32_e32 v95, v97
	v_pk_add_f32 v[94:95], v[100:101], v[94:95]
	v_mul_f32_e32 v97, v86, v86
	v_pk_add_f32 v[94:95], v[94:95], v[94:95] op_sel_hi:[0,1]
	v_mov_b32_e32 v94, v81
	v_pk_add_f32 v[94:95], v[98:99], v[94:95]
	v_mul_f32_e32 v99, v87, v87
	v_mul_f32_e32 v101, v88, v88
	v_mul_f32_e32 v107, v89, v89
	v_mov_b32_e32 v96, v86
	v_mov_b32_e32 v98, v87
	v_mov_b32_e32 v100, v88
	v_mov_b32_e32 v106, v89
	v_mul_f32_e32 v111, v82, v82
	v_mul_f32_e32 v113, v83, v83
	v_mul_f32_e32 v115, v84, v84
	v_mul_f32_e32 v117, v85, v85
	v_pk_add_f32 v[96:97], v[96:97], v[98:99]
	v_pk_add_f32 v[98:99], v[100:101], v[106:107]
	v_mov_b32_e32 v110, v82
	v_mov_b32_e32 v112, v83
	v_mov_b32_e32 v114, v84
	v_mov_b32_e32 v116, v85
	v_pk_add_f32 v[96:97], v[96:97], v[98:99]
	v_pk_add_f32 v[98:99], v[110:111], v[112:113]
	v_pk_add_f32 v[100:101], v[114:115], v[116:117]
	s_nop 0
	v_pk_add_f32 v[98:99], v[98:99], v[100:101]
	s_nop 0
	v_pk_add_f32 v[96:97], v[96:97], v[98:99]
	s_nop 0
	v_pk_add_f32 v[94:95], v[94:95], v[96:97]
	v_mov_b32_e32 v98, v94
	s_nop 1
	v_permlane16_swap_b32 v94, v98
	v_mov_b32_e32 v99, v95
	s_nop 1
	v_permlane16_swap_b32 v95, v99
	v_cvt_pk_bf16_f32 v96, v86, v87
	v_cvt_pk_bf16_f32 v97, v88, v89
	s_waitcnt lgkmcnt(0)
	v_pk_add_f32 v[86:87], v[94:95], v[98:99]
	v_mov_b32_e32 v94, v86
	s_nop 1
	v_permlane32_swap_b32 v86, v94
	v_mov_b32_e32 v95, v87
	s_nop 1
	v_permlane32_swap_b32 v87, v95
	v_cvt_pk_bf16_f32 v98, v82, v83
	v_cvt_pk_bf16_f32 v99, v84, v85
	global_store_dwordx4 v[108:109], v[96:99], off offset:256
	s_and_saveexec_b64 s[0:1], s[42:43]
	s_cbranch_execz .LBB0_1716
	v_lshlrev_b64 v[82:83], 7, v[182:183]
	v_lshl_add_u64 v[82:83], s[52:53], 0, v[82:83]
	v_lshl_add_u64 v[82:83], s[64:65], 2, v[82:83]
	s_waitcnt lgkmcnt(0)
	v_pk_add_f32 v[84:85], v[86:87], v[94:95]
	global_store_dwordx2 v[82:83], v[84:85], off

; __device__ __forceinline__ float bflo(unsigned w) { return __uint_as_float(w << 16); }
; __device__ __forceinline__ float bfhi(unsigned w) { return __uint_as_float(w & 0xffff0000u); }
; __device__ __forceinline__ u32x4 pack8(f32x4 a, f32x4 b) { u32x4 w; w.x = cvtpk(a[0], a[1]); w.y = cvtpk(a[2], a[3]); w.z = cvtpk(b[0], b[1]); w.w = cvtpk(b[2], b[3]); return w; }
;     __device__ __forceinline__ void operator()(const pg8::f32x4 (&acc)[2][2][4][2], const pg8::Unit& u, int wr, int wc, int fr, int fq) const {
;     ...
;             for (int m = 0; m < 4; ++m) {
;                 const int rloc = ai * 128 + wr * 64 + m * 16 + fr, row = u.pm * 256 + rloc;
;                 float mu = 0.f, rstd = 1.f; if (pst) ln_row_stats(pst, rloc, mu, rstd);
;                 float s = 0.f, q = 0.f;
; #pragma unroll
;                 for (int bj = 0; bj < 2; ++bj) {
;                     const int col = col0 + bj * 128;
;                     const u32x4 zw = zx[m][bj];
;                     f32x4 x0 = {bflo(zw.x), bfhi(zw.x), bflo(zw.y), bfhi(zw.y)}, x1 = {bflo(zw.z), bfhi(zw.z), bflo(zw.w), bfhi(zw.w)};
;                     if (pst) { const f32x4 g0 = *(const f32x4*)(pg + col), g1 = *(const f32x4*)(pg + col + 4), b0 = *(const f32x4*)(pb + col), b1 = *(const f32x4*)(pb + col + 4);
;                         x0 = (x0 - mu) * rstd * g0 + b0; x1 = (x1 - mu) * rstd * g1 + b1; }
;                     x0 = x0 * ALPHA + acc[ai][bj][m][0]; x1 = x1 * ALPHA + acc[ai][bj][m][1];
;                     if (Z) { float* p = Z + (size_t)row * 1024 + col; *(f32x4*)p = x0; *(f32x4*)(p + 4) = x1; }
;                     *(u32x4*)(ZB + (size_t)row * 1024 + col) = pack8(x0, x1);
;                     s += ((x0[0] + x0[1]) + (x0[2] + x0[3])) + ((x1[0] + x1[1]) + (x1[2] + x1[3]));
;                     q += ((x0[0] * x0[0] + x0[1] * x0[1]) + (x0[2] * x0[2] + x0[3] * x0[3])) + ((x1[0] * x1[0] + x1[1] * x1[1]) + (x1[2] * x1[2] + x1[3] * x1[3]));
;                 }
;                 s += __shfl_xor(s, 16); q += __shfl_xor(q, 16); s += __shfl_xor(s, 32); q += __shfl_xor(q, 32);
;                 if (fq == 0) { typedef float f32x2v __attribute__((ext_vector_type(2))); *(f32x2v*)(ost + (size_t)row * 32 + (u.pn * 4 + wc) * 2) = (f32x2v){s, q}; }
.LBB0_1720:
	v_mul_f32_e32 v83, v78, v78
	v_mul_f32_e32 v87, v79, v79
	v_mov_b32_e32 v88, v78
	v_mov_b32_e32 v89, v76
	v_mov_b32_e32 v78, v79
	v_mov_b32_e32 v79, v76
	v_pk_add_f32 v[90:91], v[88:89], v[78:79]
	v_pk_mul_f32 v[78:79], v[88:89], v[78:79]
	v_add_f32_e32 v82, v72, v73
	v_mov_b32_e32 v91, v79
	v_pk_add_f32 v[78:79], v[76:77], v[76:77] op_sel:[1,0]
	v_pk_mul_f32 v[76:77], v[76:77], v[76:77]
	v_add_f32_e32 v86, v74, v75
	v_mov_b32_e32 v79, v77
	v_pk_add_f32 v[76:77], v[78:79], v[90:91]
	v_pk_add_f32 v[78:79], v[82:83], v[86:87]
	v_pk_mul_f32 v[74:75], v[74:75], v[74:75]
	v_pk_mul_f32 v[72:73], v[72:73], v[72:73]
	v_pk_add_f32 v[76:77], v[76:77], v[78:79]
	v_pk_mov_b32 v[78:79], v[72:73], v[74:75] op_sel:[1,0]
	v_mov_b32_e32 v73, v75
	v_pk_add_f32 v[72:73], v[78:79], v[72:73]
	v_mul_f32_e32 v75, v68, v68
	v_pk_add_f32 v[72:73], v[72:73], v[72:73] op_sel_hi:[0,1]
	v_mov_b32_e32 v72, v81
	v_pk_add_f32 v[72:73], v[76:77], v[72:73]
	v_mul_f32_e32 v77, v69, v69
	v_mul_f32_e32 v79, v70, v70
	v_mul_f32_e32 v83, v71, v71
	v_mov_b32_e32 v74, v68
	v_mov_b32_e32 v76, v69
	v_mov_b32_e32 v78, v70
	v_mov_b32_e32 v82, v71
	v_mul_f32_e32 v87, v64, v64
	v_mul_f32_e32 v89, v65, v65
	v_mul_f32_e32 v91, v66, v66
	v_mul_f32_e32 v93, v67, v67
	v_pk_add_f32 v[74:75], v[74:75], v[76:77]
	v_pk_add_f32 v[76:77], v[78:79], v[82:83]
	v_mov_b32_e32 v86, v64
	v_mov_b32_e32 v88, v65
	v_mov_b32_e32 v90, v66
	v_mov_b32_e32 v92, v67
	v_pk_add_f32 v[74:75], v[74:75], v[76:77]
	v_pk_add_f32 v[76:77], v[86:87], v[88:89]
	v_pk_add_f32 v[78:79], v[90:91], v[92:93]
	s_nop 0
	v_pk_add_f32 v[76:77], v[76:77], v[78:79]
	s_nop 0
	v_pk_add_f32 v[74:75], v[74:75], v[76:77]
	s_nop 0
	v_pk_add_f32 v[72:73], v[72:73], v[74:75]
	v_mov_b32_e32 v76, v72
	s_nop 1
	v_permlane16_swap_b32 v72, v76
	v_mov_b32_e32 v77, v73
	s_nop 1
	v_permlane16_swap_b32 v73, v77
	v_cvt_pk_bf16_f32 v74, v68, v69
	v_cvt_pk_bf16_f32 v75, v70, v71
	s_waitcnt lgkmcnt(0)
	v_pk_add_f32 v[68:69], v[72:73], v[76:77]
	v_mov_b32_e32 v72, v68
	s_nop 1
	v_permlane32_swap_b32 v68, v72
	v_mov_b32_e32 v73, v69
	s_nop 1
	v_permlane32_swap_b32 v69, v73
	v_cvt_pk_bf16_f32 v76, v64, v65
	v_cvt_pk_bf16_f32 v77, v66, v67
	global_store_dwordx4 v[84:85], v[74:77], off offset:256
	s_and_saveexec_b64 s[0:1], s[42:43]
	s_cbranch_execz .LBB0_1722
	v_lshlrev_b64 v[64:65], 7, v[178:179]
	v_lshl_add_u64 v[64:65], s[52:53], 0, v[64:65]
	v_lshl_add_u64 v[64:65], s[64:65], 2, v[64:65]
	s_waitcnt lgkmcnt(0)
	v_pk_add_f32 v[66:67], v[68:69], v[72:73]
	global_store_dwordx2 v[64:65], v[66:67], off

; __device__ __forceinline__ float bflo(unsigned w) { return __uint_as_float(w << 16); }
; __device__ __forceinline__ float bfhi(unsigned w) { return __uint_as_float(w & 0xffff0000u); }
; __device__ __forceinline__ u32x4 pack8(f32x4 a, f32x4 b) { u32x4 w; w.x = cvtpk(a[0], a[1]); w.y = cvtpk(a[2], a[3]); w.z = cvtpk(b[0], b[1]); w.w = cvtpk(b[2], b[3]); return w; }
;     __device__ __forceinline__ void operator()(const pg8::f32x4 (&acc)[2][2][4][2], const pg8::Unit& u, int wr, int wc, int fr, int fq) const {
;     ...
;             for (int m = 0; m < 4; ++m) {
;                 const int rloc = ai * 128 + wr * 64 + m * 16 + fr, row = u.pm * 256 + rloc;
;                 float mu = 0.f, rstd = 1.f; if (pst) ln_row_stats(pst, rloc, mu, rstd);
;                 float s = 0.f, q = 0.f;
; #pragma unroll
;                 for (int bj = 0; bj < 2; ++bj) {
;                     const int col = col0 + bj * 128;
;                     const u32x4 zw = zx[m][bj];
;                     f32x4 x0 = {bflo(zw.x), bfhi(zw.x), bflo(zw.y), bfhi(zw.y)}, x1 = {bflo(zw.z), bfhi(zw.z), bflo(zw.w), bfhi(zw.w)};
;                     if (pst) { const f32x4 g0 = *(const f32x4*)(pg + col), g1 = *(const f32x4*)(pg + col + 4), b0 = *(const f32x4*)(pb + col), b1 = *(const f32x4*)(pb + col + 4);
;                         x0 = (x0 - mu) * rstd * g0 + b0; x1 = (x1 - mu) * rstd * g1 + b1; }
;                     x0 = x0 * ALPHA + acc[ai][bj][m][0]; x1 = x1 * ALPHA + acc[ai][bj][m][1];
;                     if (Z) { float* p = Z + (size_t)row * 1024 + col; *(f32x4*)p = x0; *(f32x4*)(p + 4) = x1; }
;                     *(u32x4*)(ZB + (size_t)row * 1024 + col) = pack8(x0, x1);
;                     s += ((x0[0] + x0[1]) + (x0[2] + x0[3])) + ((x1[0] + x1[1]) + (x1[2] + x1[3]));
;                     q += ((x0[0] * x0[0] + x0[1] * x0[1]) + (x0[2] * x0[2] + x0[3] * x0[3])) + ((x1[0] * x1[0] + x1[1] * x1[1]) + (x1[2] * x1[2] + x1[3] * x1[3]));
;                 }
;                 s += __shfl_xor(s, 16); q += __shfl_xor(q, 16); s += __shfl_xor(s, 32); q += __shfl_xor(q, 32);
;                 if (fq == 0) { typedef float f32x2v __attribute__((ext_vector_type(2))); *(f32x2v*)(ost + (size_t)row * 32 + (u.pn * 4 + wc) * 2) = (f32x2v){s, q}; }
.LBB0_1726:
	v_mul_f32_e32 v91, v62, v62
	v_mul_f32_e32 v93, v63, v63
	v_mov_b32_e32 v108, v62
	v_mov_b32_e32 v109, v60
	v_mov_b32_e32 v62, v63
	v_mov_b32_e32 v63, v60
	v_pk_add_f32 v[112:113], v[108:109], v[62:63]
	v_pk_mul_f32 v[62:63], v[108:109], v[62:63]
	v_add_f32_e32 v90, v56, v57
	v_mov_b32_e32 v113, v63
	v_pk_add_f32 v[62:63], v[60:61], v[60:61] op_sel:[1,0]
	v_pk_mul_f32 v[60:61], v[60:61], v[60:61]
	v_add_f32_e32 v92, v58, v59
	v_mov_b32_e32 v63, v61
	v_pk_add_f32 v[60:61], v[62:63], v[112:113]
	v_pk_add_f32 v[62:63], v[90:91], v[92:93]
	v_pk_mul_f32 v[58:59], v[58:59], v[58:59]
	v_pk_mul_f32 v[56:57], v[56:57], v[56:57]
	v_pk_add_f32 v[60:61], v[60:61], v[62:63]
	v_pk_mov_b32 v[62:63], v[56:57], v[58:59] op_sel:[1,0]
	v_mov_b32_e32 v57, v59
	v_pk_add_f32 v[56:57], v[62:63], v[56:57]
	v_mul_f32_e32 v59, v52, v52
	v_pk_add_f32 v[56:57], v[56:57], v[56:57] op_sel_hi:[0,1]
	v_mov_b32_e32 v56, v81
	v_pk_add_f32 v[56:57], v[60:61], v[56:57]
	v_mul_f32_e32 v61, v53, v53
	v_mul_f32_e32 v63, v54, v54
	v_mul_f32_e32 v91, v55, v55
	v_mov_b32_e32 v58, v52
	v_mov_b32_e32 v60, v53
	v_mov_b32_e32 v62, v54
	v_mov_b32_e32 v90, v55
	v_mul_f32_e32 v93, v48, v48
	v_mul_f32_e32 v109, v49, v49
	v_mul_f32_e32 v113, v50, v50
	v_mul_f32_e32 v115, v51, v51
	v_pk_add_f32 v[58:59], v[58:59], v[60:61]
	v_pk_add_f32 v[60:61], v[62:63], v[90:91]
	v_mov_b32_e32 v92, v48
	v_mov_b32_e32 v108, v49
	v_mov_b32_e32 v112, v50
	v_mov_b32_e32 v114, v51
	v_pk_add_f32 v[58:59], v[58:59], v[60:61]
	v_pk_add_f32 v[60:61], v[92:93], v[108:109]
	v_pk_add_f32 v[62:63], v[112:113], v[114:115]
	s_nop 0
	v_pk_add_f32 v[60:61], v[60:61], v[62:63]
	s_nop 0
	v_pk_add_f32 v[58:59], v[58:59], v[60:61]
	s_nop 0
	v_pk_add_f32 v[56:57], v[56:57], v[58:59]
	v_mov_b32_e32 v60, v56
	s_nop 1
	v_permlane16_swap_b32 v56, v60
	v_mov_b32_e32 v61, v57
	s_nop 1
	v_permlane16_swap_b32 v57, v61
	v_cvt_pk_bf16_f32 v58, v52, v53
	v_cvt_pk_bf16_f32 v59, v54, v55
	s_waitcnt lgkmcnt(0)
	v_pk_add_f32 v[52:53], v[56:57], v[60:61]
	v_mov_b32_e32 v56, v52
	s_nop 1
	v_permlane32_swap_b32 v52, v56
	v_mov_b32_e32 v57, v53
	s_nop 1
	v_permlane32_swap_b32 v53, v57
	v_cvt_pk_bf16_f32 v60, v48, v49
	v_cvt_pk_bf16_f32 v61, v50, v51
	global_store_dwordx4 v[110:111], v[58:61], off offset:256
	s_and_saveexec_b64 s[0:1], s[42:43]
	s_cbranch_execz .LBB0_1728
	v_lshlrev_b64 v[48:49], 7, v[106:107]
	v_lshl_add_u64 v[48:49], s[52:53], 0, v[48:49]
	v_lshl_add_u64 v[48:49], s[64:65], 2, v[48:49]
	s_waitcnt lgkmcnt(0)
	v_pk_add_f32 v[50:51], v[52:53], v[56:57]
	global_store_dwordx2 v[48:49], v[50:51], off

; __device__ __forceinline__ float bflo(unsigned w) { return __uint_as_float(w << 16); }
; __device__ __forceinline__ float bfhi(unsigned w) { return __uint_as_float(w & 0xffff0000u); }
; __device__ __forceinline__ u32x4 pack8(f32x4 a, f32x4 b) { u32x4 w; w.x = cvtpk(a[0], a[1]); w.y = cvtpk(a[2], a[3]); w.z = cvtpk(b[0], b[1]); w.w = cvtpk(b[2], b[3]); return w; }
;     __device__ __forceinline__ void operator()(const pg8::f32x4 (&acc)[2][2][4][2], const pg8::Unit& u, int wr, int wc, int fr, int fq) const {
;     ...
;             for (int m = 0; m < 4; ++m) {
;                 const int rloc = ai * 128 + wr * 64 + m * 16 + fr, row = u.pm * 256 + rloc;
;                 float mu = 0.f, rstd = 1.f; if (pst) ln_row_stats(pst, rloc, mu, rstd);
;                 float s = 0.f, q = 0.f;
; #pragma unroll
;                 for (int bj = 0; bj < 2; ++bj) {
;                     const int col = col0 + bj * 128;
;                     const u32x4 zw = zx[m][bj];
;                     f32x4 x0 = {bflo(zw.x), bfhi(zw.x), bflo(zw.y), bfhi(zw.y)}, x1 = {bflo(zw.z), bfhi(zw.z), bflo(zw.w), bfhi(zw.w)};
;                     if (pst) { const f32x4 g0 = *(const f32x4*)(pg + col), g1 = *(const f32x4*)(pg + col + 4), b0 = *(const f32x4*)(pb + col), b1 = *(const f32x4*)(pb + col + 4);
;                         x0 = (x0 - mu) * rstd * g0 + b0; x1 = (x1 - mu) * rstd * g1 + b1; }
;                     x0 = x0 * ALPHA + acc[ai][bj][m][0]; x1 = x1 * ALPHA + acc[ai][bj][m][1];
;                     if (Z) { float* p = Z + (size_t)row * 1024 + col; *(f32x4*)p = x0; *(f32x4*)(p + 4) = x1; }
;                     *(u32x4*)(ZB + (size_t)row * 1024 + col) = pack8(x0, x1);
;                     s += ((x0[0] + x0[1]) + (x0[2] + x0[3])) + ((x1[0] + x1[1]) + (x1[2] + x1[3]));
;                     q += ((x0[0] * x0[0] + x0[1] * x0[1]) + (x0[2] * x0[2] + x0[3] * x0[3])) + ((x1[0] * x1[0] + x1[1] * x1[1]) + (x1[2] * x1[2] + x1[3] * x1[3]));
;                 }
;                 s += __shfl_xor(s, 16); q += __shfl_xor(q, 16); s += __shfl_xor(s, 32); q += __shfl_xor(q, 32);
;                 if (fq == 0) { typedef float f32x2v __attribute__((ext_vector_type(2))); *(f32x2v*)(ost + (size_t)row * 32 + (u.pn * 4 + wc) * 2) = (f32x2v){s, q}; }
.LBB0_1732:
	v_mul_f32_e32 v49, v46, v46
	v_mul_f32_e32 v53, v47, v47
	v_mov_b32_e32 v54, v46
	v_mov_b32_e32 v55, v44
	v_mov_b32_e32 v46, v47
	v_mov_b32_e32 v47, v44
	v_pk_add_f32 v[56:57], v[54:55], v[46:47]
	v_pk_mul_f32 v[46:47], v[54:55], v[46:47]
	v_add_f32_e32 v48, v40, v41
	v_mov_b32_e32 v57, v47
	v_pk_add_f32 v[46:47], v[44:45], v[44:45] op_sel:[1,0]
	v_pk_mul_f32 v[44:45], v[44:45], v[44:45]
	v_add_f32_e32 v52, v42, v43
	v_mov_b32_e32 v47, v45
	v_pk_add_f32 v[44:45], v[46:47], v[56:57]
	v_pk_add_f32 v[46:47], v[48:49], v[52:53]
	v_pk_mul_f32 v[42:43], v[42:43], v[42:43]
	v_pk_mul_f32 v[40:41], v[40:41], v[40:41]
	v_pk_add_f32 v[44:45], v[44:45], v[46:47]
	v_pk_mov_b32 v[46:47], v[40:41], v[42:43] op_sel:[1,0]
	v_mov_b32_e32 v41, v43
	v_pk_add_f32 v[40:41], v[46:47], v[40:41]
	v_mul_f32_e32 v43, v36, v36
	v_pk_add_f32 v[40:41], v[40:41], v[40:41] op_sel_hi:[0,1]
	v_mov_b32_e32 v40, v81
	v_pk_add_f32 v[40:41], v[44:45], v[40:41]
	v_mul_f32_e32 v45, v37, v37
	v_mul_f32_e32 v47, v38, v38
	v_mul_f32_e32 v49, v39, v39
	v_mov_b32_e32 v42, v36
	v_mov_b32_e32 v44, v37
	v_mov_b32_e32 v46, v38
	v_mov_b32_e32 v48, v39
	v_mul_f32_e32 v53, v32, v32
	v_mul_f32_e32 v55, v33, v33
	v_mul_f32_e32 v57, v34, v34
	v_mul_f32_e32 v59, v35, v35
	v_pk_add_f32 v[42:43], v[42:43], v[44:45]
	v_pk_add_f32 v[44:45], v[46:47], v[48:49]
	v_mov_b32_e32 v52, v32
	v_mov_b32_e32 v54, v33
	v_mov_b32_e32 v56, v34
	v_mov_b32_e32 v58, v35
	v_pk_add_f32 v[42:43], v[42:43], v[44:45]
	v_pk_add_f32 v[44:45], v[52:53], v[54:55]
	v_pk_add_f32 v[46:47], v[56:57], v[58:59]
	s_nop 0
	v_pk_add_f32 v[44:45], v[44:45], v[46:47]
	s_nop 0
	v_pk_add_f32 v[42:43], v[42:43], v[44:45]
	s_nop 0
	v_pk_add_f32 v[40:41], v[40:41], v[42:43]
	v_mov_b32_e32 v44, v40
	s_nop 1
	v_permlane16_swap_b32 v40, v44
	v_mov_b32_e32 v45, v41
	s_nop 1
	v_permlane16_swap_b32 v41, v45
	v_cvt_pk_bf16_f32 v42, v36, v37
	v_cvt_pk_bf16_f32 v43, v38, v39
	s_waitcnt lgkmcnt(0)
	v_pk_add_f32 v[36:37], v[40:41], v[44:45]
	v_mov_b32_e32 v40, v36
	s_nop 1
	v_permlane32_swap_b32 v36, v40
	v_mov_b32_e32 v41, v37
	s_nop 1
	v_permlane32_swap_b32 v37, v41
	v_cvt_pk_bf16_f32 v44, v32, v33
	v_cvt_pk_bf16_f32 v45, v34, v35
	global_store_dwordx4 v[50:51], v[42:45], off offset:256
	s_and_saveexec_b64 s[0:1], s[42:43]
	s_cbranch_execz .LBB0_1734
	v_lshlrev_b64 v[32:33], 7, v[102:103]
	v_lshl_add_u64 v[32:33], s[52:53], 0, v[32:33]
	v_lshl_add_u64 v[32:33], s[64:65], 2, v[32:33]
	s_waitcnt lgkmcnt(0)
	v_pk_add_f32 v[34:35], v[36:37], v[40:41]
	global_store_dwordx2 v[32:33], v[34:35], off

; __device__ __forceinline__ float bflo(unsigned w) { return __uint_as_float(w << 16); }
; __device__ __forceinline__ float bfhi(unsigned w) { return __uint_as_float(w & 0xffff0000u); }
; __device__ __forceinline__ u32x4 pack8(f32x4 a, f32x4 b) { u32x4 w; w.x = cvtpk(a[0], a[1]); w.y = cvtpk(a[2], a[3]); w.z = cvtpk(b[0], b[1]); w.w = cvtpk(b[2], b[3]); return w; }
;     __device__ __forceinline__ void operator()(const pg8::f32x4 (&acc)[2][2][4][2], const pg8::Unit& u, int wr, int wc, int fr, int fq) const {
;     ...
;             for (int m = 0; m < 4; ++m) {
;                 const int rloc = ai * 128 + wr * 64 + m * 16 + fr, row = u.pm * 256 + rloc;
;                 float mu = 0.f, rstd = 1.f; if (pst) ln_row_stats(pst, rloc, mu, rstd);
;                 float s = 0.f, q = 0.f;
; #pragma unroll
;                 for (int bj = 0; bj < 2; ++bj) {
;                     const int col = col0 + bj * 128;
;                     const u32x4 zw = zx[m][bj];
;                     f32x4 x0 = {bflo(zw.x), bfhi(zw.x), bflo(zw.y), bfhi(zw.y)}, x1 = {bflo(zw.z), bfhi(zw.z), bflo(zw.w), bfhi(zw.w)};
;                     if (pst) { const f32x4 g0 = *(const f32x4*)(pg + col), g1 = *(const f32x4*)(pg + col + 4), b0 = *(const f32x4*)(pb + col), b1 = *(const f32x4*)(pb + col + 4);
;                         x0 = (x0 - mu) * rstd * g0 + b0; x1 = (x1 - mu) * rstd * g1 + b1; }
;                     x0 = x0 * ALPHA + acc[ai][bj][m][0]; x1 = x1 * ALPHA + acc[ai][bj][m][1];
;                     if (Z) { float* p = Z + (size_t)row * 1024 + col; *(f32x4*)p = x0; *(f32x4*)(p + 4) = x1; }
;                     *(u32x4*)(ZB + (size_t)row * 1024 + col) = pack8(x0, x1);
;                     s += ((x0[0] + x0[1]) + (x0[2] + x0[3])) + ((x1[0] + x1[1]) + (x1[2] + x1[3]));
;                     q += ((x0[0] * x0[0] + x0[1] * x0[1]) + (x0[2] * x0[2] + x0[3] * x0[3])) + ((x1[0] * x1[0] + x1[1] * x1[1]) + (x1[2] * x1[2] + x1[3] * x1[3]));
;                 }
;                 s += __shfl_xor(s, 16); q += __shfl_xor(q, 16); s += __shfl_xor(s, 32); q += __shfl_xor(q, 32);
;                 if (fq == 0) { typedef float f32x2v __attribute__((ext_vector_type(2))); *(f32x2v*)(ost + (size_t)row * 32 + (u.pn * 4 + wc) * 2) = (f32x2v){s, q}; }
.LBB0_1738:
	v_mul_f32_e32 v33, v30, v30
	v_mul_f32_e32 v37, v31, v31
	v_mov_b32_e32 v38, v30
	v_mov_b32_e32 v39, v28
	v_mov_b32_e32 v30, v31
	v_mov_b32_e32 v31, v28
	v_pk_add_f32 v[40:41], v[38:39], v[30:31]
	v_pk_mul_f32 v[30:31], v[38:39], v[30:31]
	v_add_f32_e32 v32, v24, v25
	v_mov_b32_e32 v41, v31
	v_pk_add_f32 v[30:31], v[28:29], v[28:29] op_sel:[1,0]
	v_pk_mul_f32 v[28:29], v[28:29], v[28:29]
	v_add_f32_e32 v36, v26, v27
	v_mov_b32_e32 v31, v29
	v_pk_add_f32 v[28:29], v[30:31], v[40:41]
	v_pk_add_f32 v[30:31], v[32:33], v[36:37]
	v_pk_mul_f32 v[26:27], v[26:27], v[26:27]
	v_pk_mul_f32 v[24:25], v[24:25], v[24:25]
	v_pk_add_f32 v[28:29], v[28:29], v[30:31]
	v_pk_mov_b32 v[30:31], v[24:25], v[26:27] op_sel:[1,0]
	v_mov_b32_e32 v25, v27
	v_pk_add_f32 v[24:25], v[30:31], v[24:25]
	v_mul_f32_e32 v27, v20, v20
	v_pk_add_f32 v[24:25], v[24:25], v[24:25] op_sel_hi:[0,1]
	v_mov_b32_e32 v24, v81
	v_pk_add_f32 v[24:25], v[28:29], v[24:25]
	v_mul_f32_e32 v29, v21, v21
	v_mul_f32_e32 v31, v22, v22
	v_mul_f32_e32 v33, v23, v23
	v_mov_b32_e32 v26, v20
	v_mov_b32_e32 v28, v21
	v_mov_b32_e32 v30, v22
	v_mov_b32_e32 v32, v23
	v_mul_f32_e32 v37, v16, v16
	v_mul_f32_e32 v39, v17, v17
	v_mul_f32_e32 v41, v18, v18
	v_mul_f32_e32 v43, v19, v19
	v_pk_add_f32 v[26:27], v[26:27], v[28:29]
	v_pk_add_f32 v[28:29], v[30:31], v[32:33]
	v_mov_b32_e32 v36, v16
	v_mov_b32_e32 v38, v17
	v_mov_b32_e32 v40, v18
	v_mov_b32_e32 v42, v19
	v_pk_add_f32 v[26:27], v[26:27], v[28:29]
	v_pk_add_f32 v[28:29], v[36:37], v[38:39]
	v_pk_add_f32 v[30:31], v[40:41], v[42:43]
	s_nop 0
	v_pk_add_f32 v[28:29], v[28:29], v[30:31]
	s_nop 0
	v_pk_add_f32 v[26:27], v[26:27], v[28:29]
	s_nop 0
	v_pk_add_f32 v[24:25], v[24:25], v[26:27]
	v_mov_b32_e32 v28, v24
	s_nop 1
	v_permlane16_swap_b32 v24, v28
	v_mov_b32_e32 v29, v25
	s_nop 1
	v_permlane16_swap_b32 v25, v29
	v_cvt_pk_bf16_f32 v26, v20, v21
	v_cvt_pk_bf16_f32 v27, v22, v23
	s_waitcnt lgkmcnt(0)
	v_pk_add_f32 v[20:21], v[24:25], v[28:29]
	v_mov_b32_e32 v24, v20
	s_nop 1
	v_permlane32_swap_b32 v20, v24
	v_mov_b32_e32 v25, v21
	s_nop 1
	v_permlane32_swap_b32 v21, v25
	v_cvt_pk_bf16_f32 v28, v16, v17
	v_cvt_pk_bf16_f32 v29, v18, v19
	global_store_dwordx4 v[34:35], v[26:29], off offset:256
	s_and_saveexec_b64 s[0:1], s[42:43]
	s_cbranch_execz .LBB0_1740
	v_lshlrev_b64 v[16:17], 7, v[98:99]
	v_lshl_add_u64 v[16:17], s[52:53], 0, v[16:17]
	v_lshl_add_u64 v[16:17], s[64:65], 2, v[16:17]
	s_waitcnt lgkmcnt(0)
	v_pk_add_f32 v[18:19], v[20:21], v[24:25]
	global_store_dwordx2 v[16:17], v[18:19], off

; __device__ __forceinline__ float bflo(unsigned w) { return __uint_as_float(w << 16); }
; __device__ __forceinline__ float bfhi(unsigned w) { return __uint_as_float(w & 0xffff0000u); }
; __device__ __forceinline__ u32x4 pack8(f32x4 a, f32x4 b) { u32x4 w; w.x = cvtpk(a[0], a[1]); w.y = cvtpk(a[2], a[3]); w.z = cvtpk(b[0], b[1]); w.w = cvtpk(b[2], b[3]); return w; }
;     __device__ __forceinline__ void operator()(const pg8::f32x4 (&acc)[2][2][4][2], const pg8::Unit& u, int wr, int wc, int fr, int fq) const {
;     ...
;             for (int m = 0; m < 4; ++m) {
;                 const int rloc = ai * 128 + wr * 64 + m * 16 + fr, row = u.pm * 256 + rloc;
;                 float mu = 0.f, rstd = 1.f; if (pst) ln_row_stats(pst, rloc, mu, rstd);
;                 float s = 0.f, q = 0.f;
; #pragma unroll
;                 for (int bj = 0; bj < 2; ++bj) {
;                     const int col = col0 + bj * 128;
;                     const u32x4 zw = zx[m][bj];
;                     f32x4 x0 = {bflo(zw.x), bfhi(zw.x), bflo(zw.y), bfhi(zw.y)}, x1 = {bflo(zw.z), bfhi(zw.z), bflo(zw.w), bfhi(zw.w)};
;                     if (pst) { const f32x4 g0 = *(const f32x4*)(pg + col), g1 = *(const f32x4*)(pg + col + 4), b0 = *(const f32x4*)(pb + col), b1 = *(const f32x4*)(pb + col + 4);
;                         x0 = (x0 - mu) * rstd * g0 + b0; x1 = (x1 - mu) * rstd * g1 + b1; }
;                     x0 = x0 * ALPHA + acc[ai][bj][m][0]; x1 = x1 * ALPHA + acc[ai][bj][m][1];
;                     if (Z) { float* p = Z + (size_t)row * 1024 + col; *(f32x4*)p = x0; *(f32x4*)(p + 4) = x1; }
;                     *(u32x4*)(ZB + (size_t)row * 1024 + col) = pack8(x0, x1);
;                     s += ((x0[0] + x0[1]) + (x0[2] + x0[3])) + ((x1[0] + x1[1]) + (x1[2] + x1[3]));
;                     q += ((x0[0] * x0[0] + x0[1] * x0[1]) + (x0[2] * x0[2] + x0[3] * x0[3])) + ((x1[0] * x1[0] + x1[1] * x1[1]) + (x1[2] * x1[2] + x1[3] * x1[3]));
;                 }
;                 s += __shfl_xor(s, 16); q += __shfl_xor(q, 16); s += __shfl_xor(s, 32); q += __shfl_xor(q, 32);
;                 if (fq == 0) { typedef float f32x2v __attribute__((ext_vector_type(2))); *(f32x2v*)(ost + (size_t)row * 32 + (u.pn * 4 + wc) * 2) = (f32x2v){s, q}; }
.LBB0_1744:
	v_mul_f32_e32 v17, v14, v14
	v_mul_f32_e32 v21, v15, v15
	v_mov_b32_e32 v22, v14
	v_mov_b32_e32 v23, v12
	v_mov_b32_e32 v14, v15
	v_mov_b32_e32 v15, v12
	v_pk_add_f32 v[24:25], v[22:23], v[14:15]
	v_pk_mul_f32 v[14:15], v[22:23], v[14:15]
	v_add_f32_e32 v16, v8, v9
	v_mov_b32_e32 v25, v15
	v_pk_add_f32 v[14:15], v[12:13], v[12:13] op_sel:[1,0]
	v_pk_mul_f32 v[12:13], v[12:13], v[12:13]
	v_add_f32_e32 v20, v10, v11
	v_mov_b32_e32 v15, v13
	v_pk_add_f32 v[12:13], v[14:15], v[24:25]
	v_pk_add_f32 v[14:15], v[16:17], v[20:21]
	v_pk_mul_f32 v[10:11], v[10:11], v[10:11]
	v_pk_mul_f32 v[8:9], v[8:9], v[8:9]
	v_pk_add_f32 v[12:13], v[12:13], v[14:15]
	v_pk_mov_b32 v[14:15], v[8:9], v[10:11] op_sel:[1,0]
	v_mov_b32_e32 v9, v11
	v_pk_add_f32 v[8:9], v[14:15], v[8:9]
	v_mul_f32_e32 v11, v4, v4
	v_pk_add_f32 v[8:9], v[8:9], v[8:9] op_sel_hi:[0,1]
	v_mov_b32_e32 v8, v81
	v_pk_add_f32 v[8:9], v[12:13], v[8:9]
	v_mul_f32_e32 v13, v5, v5
	v_mul_f32_e32 v15, v6, v6
	v_mul_f32_e32 v17, v7, v7
	v_mov_b32_e32 v10, v4
	v_mov_b32_e32 v12, v5
	v_mov_b32_e32 v14, v6
	v_mov_b32_e32 v16, v7
	v_mul_f32_e32 v21, v0, v0
	v_mul_f32_e32 v23, v1, v1
	v_mul_f32_e32 v25, v2, v2
	v_mul_f32_e32 v27, v3, v3
	v_pk_add_f32 v[10:11], v[10:11], v[12:13]
	v_pk_add_f32 v[12:13], v[14:15], v[16:17]
	v_mov_b32_e32 v20, v0
	v_mov_b32_e32 v22, v1
	v_mov_b32_e32 v24, v2
	v_mov_b32_e32 v26, v3
	v_pk_add_f32 v[10:11], v[10:11], v[12:13]
	v_pk_add_f32 v[12:13], v[20:21], v[22:23]
	v_pk_add_f32 v[14:15], v[24:25], v[26:27]
	s_nop 0
	v_pk_add_f32 v[12:13], v[12:13], v[14:15]
	s_nop 0
	v_pk_add_f32 v[10:11], v[10:11], v[12:13]
	s_nop 0
	v_pk_add_f32 v[8:9], v[8:9], v[10:11]
	v_mov_b32_e32 v12, v8
	s_nop 1
	v_permlane16_swap_b32 v8, v12
	v_mov_b32_e32 v13, v9
	s_nop 1
	v_permlane16_swap_b32 v9, v13
	v_cvt_pk_bf16_f32 v10, v4, v5
	v_cvt_pk_bf16_f32 v11, v6, v7
	s_waitcnt lgkmcnt(0)
	v_pk_add_f32 v[4:5], v[8:9], v[12:13]
	v_mov_b32_e32 v8, v4
	s_nop 1
	v_permlane32_swap_b32 v4, v8
	v_mov_b32_e32 v9, v5
	s_nop 1
	v_permlane32_swap_b32 v5, v9
	v_cvt_pk_bf16_f32 v12, v0, v1
	v_cvt_pk_bf16_f32 v13, v2, v3
	global_store_dwordx4 v[18:19], v[10:13], off offset:256
	s_and_saveexec_b64 s[0:1], s[42:43]
	s_cbranch_execz .LBB0_1746
	v_lshlrev_b64 v[0:1], 7, v[94:95]
	v_lshl_add_u64 v[0:1], s[52:53], 0, v[0:1]
	v_lshl_add_u64 v[0:1], s[64:65], 2, v[0:1]
	s_waitcnt lgkmcnt(0)
	v_pk_add_f32 v[2:3], v[4:5], v[8:9]
	global_store_dwordx2 v[0:1], v[2:3], off

; __device__ __forceinline__ u32x4 pack8(f32x4 a, f32x4 b) { u32x4 w; w.x = cvtpk(a[0], a[1]); w.y = cvtpk(a[2], a[3]); w.z = cvtpk(b[0], b[1]); w.w = cvtpk(b[2], b[3]); return w; }
; template <int EPI> __device__ __forceinline__ void tail_gemm(LAS unsigned char* lds, const bf16* Am, const bf16* Bt, int K, const TailEpi& E, int tid_in) {
;     ...
;         x0 = x0 * ALPHA + v0; x1 = x1 * ALPHA + v1;
;         if (E.Z) { *(f32x4*)(E.Z + off) = x0; *(f32x4*)(E.Z + off + 4) = x1; }
;         *(u32x4*)(E.ZB + off) = pack8(x0, x1);
;         float s = ((x0[0] + x0[1]) + (x0[2] + x0[3])) + ((x1[0] + x1[1]) + (x1[2] + x1[3]));
;         float q = ((x0[0] * x0[0] + x0[1] * x0[1]) + (x0[2] * x0[2] + x0[3] * x0[3])) + ((x1[0] * x1[0] + x1[1] * x1[1]) + (x1[2] * x1[2] + x1[3] * x1[3]));
;         s += __shfl_xor(s, 1); q += __shfl_xor(q, 1); s += __shfl_xor(s, 2); q += __shfl_xor(q, 2); s += __shfl_xor(s, 4); q += __shfl_xor(q, 4);
;         if ((tid & 7) == 0) { typedef float f32x2v __attribute__((ext_vector_type(2))); *(f32x2v*)(E.ost + (size_t)row * 32 + (su & 15) * 2) = (f32x2v){s, q}; }
.LBB0_1763:
	v_cvt_pk_bf16_f32 v8, v4, v5
	v_cvt_pk_bf16_f32 v9, v6, v7
	v_cvt_pk_bf16_f32 v10, v0, v1
	v_cvt_pk_bf16_f32 v11, v2, v3
	global_store_dwordx4 v[26:27], v[8:11], off
	v_mul_f32_e32 v13, v6, v6
	v_mul_f32_e32 v15, v7, v7
	v_mul_f32_e32 v9, v4, v4
	v_mul_f32_e32 v11, v5, v5
	v_mul_f32_e32 v17, v0, v0
	v_mul_f32_e32 v19, v1, v1
	v_mul_f32_e32 v21, v2, v2
	v_mul_f32_e32 v23, v3, v3
	v_mov_b32_e32 v8, v4
	v_mov_b32_e32 v10, v5
	v_mov_b32_e32 v12, v6
	v_mov_b32_e32 v14, v7
	v_mov_b32_e32 v16, v0
	v_mov_b32_e32 v18, v1
	v_mov_b32_e32 v20, v2
	v_mov_b32_e32 v22, v3
	v_pk_add_f32 v[4:5], v[8:9], v[10:11]
	v_pk_add_f32 v[6:7], v[12:13], v[14:15]
	v_pk_add_f32 v[0:1], v[16:17], v[18:19]
	v_pk_add_f32 v[2:3], v[20:21], v[22:23]
	v_pk_add_f32 v[4:5], v[4:5], v[6:7]
	v_pk_add_f32 v[0:1], v[0:1], v[2:3]
	s_nop 0
	v_pk_add_f32 v[0:1], v[4:5], v[0:1]
	s_nop 1
	v_mov_b32_dpp v2, v0 quad_perm:[1,0,3,2] row_mask:0xf bank_mask:0xf
	s_nop 1
	v_mov_b32_dpp v3, v1 quad_perm:[1,0,3,2] row_mask:0xf bank_mask:0xf
	s_waitcnt lgkmcnt(0)
	v_pk_add_f32 v[0:1], v[0:1], v[2:3]
	s_nop 1
	v_mov_b32_dpp v2, v0 quad_perm:[2,3,0,1] row_mask:0xf bank_mask:0xf
	s_nop 1
	v_mov_b32_dpp v3, v1 quad_perm:[2,3,0,1] row_mask:0xf bank_mask:0xf
	s_waitcnt lgkmcnt(0)
	v_pk_add_f32 v[0:1], v[0:1], v[2:3]
	s_nop 1
	v_mov_b32_dpp v2, v0 row_half_mirror row_mask:0xf bank_mask:0xf
	s_nop 1
	v_mov_b32_dpp v3, v1 row_half_mirror row_mask:0xf bank_mask:0xf
	s_and_saveexec_b64 s[0:1], s[38:39]
	s_cbranch_execz .LBB0_1752
	s_waitcnt lgkmcnt(0)
	v_pk_add_f32 v[0:1], v[0:1], v[2:3]
	v_lshl_add_u64 v[2:3], s[52:53], 0, v[24:25]
	s_lshl_b32 s68, s13, 3
	v_lshl_add_u64 v[2:3], v[2:3], 0, s[68:69]
	global_store_dwordx2 v[2:3], v[0:1], off
	s_branch .LBB0_1752

; template <bool FINAL> __device__ __forceinline__ void ln_pass(const Params& P, const float* g, const float* b, int tid_in) {
;     ...
;     for (int m = gw; m < M; m += NGW) {
;         f32x4 v[4]; float s = 0.f;
; #pragma unroll
;         for (int j = 0; j < 4; ++j) { v[j] = vn[j]; s += (v[j][0] + v[j][1]) + (v[j][2] + v[j][3]); }
;         { const int mn = m + NGW < M ? m + NGW : m;
; #pragma unroll
;           for (int j = 0; j < 4; ++j) vn[j] = *(const f32x4*)(X + (size_t)mn * D + 256 * j + 4 * lane); }
; #pragma unroll
;         for (int o = 1; o < 64; o <<= 1) s += __shfl_xor(s, o);
;         const float mean = s * (1.f / D); float q = 0.f;
; #pragma unroll
;         for (int j = 0; j < 4; ++j) { v[j] = v[j] - mean; q += (v[j][0] * v[j][0] + v[j][1] * v[j][1]) + (v[j][2] * v[j][2] + v[j][3] * v[j][3]); }
; #pragma unroll
;         for (int o = 1; o < 64; o <<= 1) q += __shfl_xor(q, o);
.LBB0_1819:
	v_pk_add_f32 v[46:47], v[72:73], v[44:45]
	v_add_f32_e32 v33, v36, v37
	s_waitcnt lgkmcnt(0)
	v_add_f32_e32 v35, v46, v47
	v_pk_add_f32 v[46:47], v[70:71], v[40:41]
	v_add_f32_e32 v75, v38, v39
	v_pk_add_f32 v[46:47], v[46:47], v[46:47] op_sel_hi:[0,1]
	v_add_f32_e32 v43, 0, v35
	v_mov_b32_e32 v35, v47
	v_readlane_b32 s0, v252, 58
	v_pk_add_f32 v[48:49], v[32:33], v[74:75]
	v_pk_add_f32 v[46:47], v[34:35], v[42:43]
	v_add_u32_e32 v43, s0, v68
	v_pk_add_f32 v[46:47], v[48:49], v[46:47]
	v_cmp_gt_i32_e32 vcc, s10, v43
	v_add_f32_e32 v33, v46, v47
	s_nop 1
	v_mov_b32_dpp v35, v33 quad_perm:[1,0,3,2] row_mask:0xf bank_mask:0xf
	v_cndmask_b32_e32 v46, v68, v43, vcc
	v_ashrrev_i32_e32 v47, 31, v46
	v_lshlrev_b64 v[46:47], 12, v[46:47]
	v_lshl_add_u64 v[76:77], v[66:67], 0, v[46:47]
	global_load_dwordx4 v[58:61], v[76:77], off
	global_load_dwordx4 v[54:57], v[76:77], off offset:1024
	global_load_dwordx4 v[50:53], v[76:77], off offset:2048
	global_load_dwordx4 v[46:49], v[76:77], off offset:3072
	s_waitcnt lgkmcnt(0)
	v_add_f32_e32 v33, v33, v35
	s_nop 1
	v_mov_b32_dpp v35, v33 quad_perm:[2,3,0,1] row_mask:0xf bank_mask:0xf
	v_readlane_b32 s1, v252, 59
	v_cmp_lt_i32_e64 s[0:1], s11, v43
	v_cmp_lt_i32_e32 vcc, s12, v68
	s_waitcnt lgkmcnt(0)
	v_add_f32_e32 v33, v33, v35
	s_nop 1
	v_mov_b32_dpp v35, v33 row_half_mirror row_mask:0xf bank_mask:0xf
	s_waitcnt lgkmcnt(0)
	v_add_f32_e32 v33, v33, v35
	s_nop 1
	v_mov_b32_dpp v35, v33 row_mirror row_mask:0xf bank_mask:0xf
	s_waitcnt lgkmcnt(0)
	v_add_f32_e32 v33, v33, v35
	v_mov_b32_e32 v35, v33
	s_nop 1
	v_permlane16_swap_b32 v33, v35
	s_waitcnt lgkmcnt(0)
	v_add_f32_e32 v33, v33, v35
	v_mov_b32_e32 v35, v33
	s_nop 1
	v_permlane32_swap_b32 v33, v35
	s_waitcnt lgkmcnt(0)
	v_add_f32_e32 v33, v33, v35
	v_fmac_f32_e32 v45, 0xba800000, v33
	v_fmac_f32_e32 v72, 0xba800000, v33
	v_fmac_f32_e32 v73, 0xba800000, v33
	v_fmac_f32_e32 v44, 0xba800000, v33
	v_mul_f32_e32 v35, v72, v72
	v_mul_f32_e32 v62, v45, v45
	v_fmac_f32_e32 v41, 0xba800000, v33
	v_fmac_f32_e32 v70, 0xba800000, v33
	v_fmac_f32_e32 v35, v44, v44
	v_fmac_f32_e32 v62, v73, v73
	v_fmac_f32_e32 v71, 0xba800000, v33
	v_add_f32_e32 v35, v35, v62
	v_fmac_f32_e32 v40, 0xba800000, v33
	v_mul_f32_e32 v62, v70, v70
	v_mul_f32_e32 v65, v41, v41
	v_fmac_f32_e32 v62, v40, v40
	v_fmac_f32_e32 v65, v71, v71
	v_add_f32_e32 v62, v62, v65
	v_fmac_f32_e32 v39, 0xba800000, v33
	v_fmac_f32_e32 v37, 0xba800000, v33
	v_add_f32_e32 v35, v35, v62
	v_fmac_f32_e32 v38, 0xba800000, v33
	v_fmac_f32_e32 v36, 0xba800000, v33
	v_mul_f32_e32 v62, v37, v37
	v_mul_f32_e32 v65, v39, v39
	v_fmac_f32_e32 v62, v36, v36
	v_fmac_f32_e32 v65, v38, v38
	v_add_f32_e32 v62, v62, v65
	v_fmac_f32_e32 v42, 0xba800000, v33
	v_fmac_f32_e32 v74, 0xba800000, v33
	v_add_f32_e32 v35, v62, v35
	v_fmac_f32_e32 v34, 0xba800000, v33
	v_fmac_f32_e32 v32, 0xba800000, v33
	v_mul_f32_e32 v33, v74, v74
	v_mul_f32_e32 v62, v42, v42
	v_fmac_f32_e32 v33, v32, v32
	v_fmac_f32_e32 v62, v34, v34
	v_add_f32_e32 v33, v33, v62
	v_add_f32_e32 v33, v33, v35
	s_nop 1
	v_mov_b32_dpp v35, v33 quad_perm:[1,0,3,2] row_mask:0xf bank_mask:0xf
	s_waitcnt lgkmcnt(0)
	v_add_f32_e32 v33, v33, v35
	s_nop 1
	v_mov_b32_dpp v35, v33 quad_perm:[2,3,0,1] row_mask:0xf bank_mask:0xf
	s_waitcnt lgkmcnt(0)
	v_add_f32_e32 v33, v33, v35
	s_nop 1
	v_mov_b32_dpp v35, v33 row_half_mirror row_mask:0xf bank_mask:0xf
	s_waitcnt lgkmcnt(0)
	v_add_f32_e32 v33, v33, v35
	s_nop 1
	v_mov_b32_dpp v35, v33 row_mirror row_mask:0xf bank_mask:0xf
	s_waitcnt lgkmcnt(0)
	v_add_f32_e32 v33, v33, v35
	v_mov_b32_e32 v35, v33
	s_nop 1
	v_permlane16_swap_b32 v33, v35
	s_waitcnt lgkmcnt(0)
	v_add_f32_e32 v33, v33, v35
	v_mov_b32_e32 v35, v33
	s_nop 1
	v_permlane32_swap_b32 v33, v35
	s_and_saveexec_b64 s[2:3], vcc
	s_xor_b64 s[2:3], exec, s[2:3]
	s_cbranch_execz .LBB0_1822
	v_add_u32_e32 v62, 0xffffbf80, v68
	v_lshlrev_b64 v[76:77], 12, v[62:63]
	v_lshl_add_u64 v[76:77], s[4:5], 0, v[76:77]
	s_andn2_saveexec_b64 s[2:3], s[2:3]
	s_cbranch_execnz .LBB0_1823
